# GEMM K loops: first K step of each tile peeled with zero addends so the 128 accumulator clears per tile header are gone
# speedup vs baseline: 1.0023x; 1.0023x over previous
; #define PG8_STAGE(bufoff, gbase, voff) do { _Pragma("unroll") for (int _i = 0; _i < 2; ++_i) \
;         __builtin_amdgcn_global_load_lds((const unsigned*)((const char*)(gbase) + (voff)[_i]), (PG8_LAS unsigned*)(lds + (bufoff) + ldsw + _i * 8192), 16, 0, 0); } while (0)
; #define PG8_WAIT_V(n) asm volatile("s_waitcnt vmcnt(" #n ")" ::: "memory")
; #define PG8_WAIT_L(n) asm volatile("s_waitcnt lgkmcnt(" #n ")" ::: "memory")
; #define PG8_BAR __builtin_amdgcn_s_barrier()
; #define PG8_SCHED __builtin_amdgcn_sched_barrier(0)
; template <class Epi, class Sched, bool ALIGN_EPI = false, bool SP2 = false, bool F8 = false>
; __device__ __forceinline__ void gemm_phase(PG8_LAS unsigned char* lds, const Gemm g, const Sched& S, const Epi& E) {
;     ...
;         const bool has_next = S.next(ui + 1, nxt);
;         const char* nA = has_next ? (const char*)g.A + (size_t)nxt.pm * tstep : cA; const char* nB = has_next ? (const char*)g.Bt + (size_t)nxt.pn * tstep : cB;
;         for (int t = 0; t < nt; t += 2) {
;             const bool last = (t == nt - 2);
;             const char* a1 = cA + (size_t)(t + 1) * kstep;
;             const char* a2 = last ? nA : cA + (size_t)(t + 2) * kstep; const char* b2 = last ? nB : cB + (size_t)(t + 2) * kstep;
;             const char* a3 = a2 + kstep; const char* b3 = b2 + kstep;
;             if (last && has_next) S.a_ready(nxt);
;             if constexpr (SP2) {
;             PG8_LDB(B0, 0, 0); PG8_LDB(B1, 0, 1); PG8_SCHED; PG8_LDA(At, 0, 0); PG8_STAGE(PG8_SA(1, 1), a1 + hstep, voffA);
;             PG8_WAIT_V(8); PG8_WAIT_L(0); PG8_BAR; PG8_MMA(0, 0, At, B0); PG8_MMA(0, 1, At, B1); PG8_BAR; PG8_SCHED;
.LBB0_31:
	s_ashr_i32 s47, s46, 31
	s_lshl_b64 s[16:17], s[46:47], 20
	v_readlane_b32 s28, v251, 7
	v_readlane_b32 s29, v251, 8
	s_add_u32 s48, s28, s16
	s_addc_u32 s49, s29, s17
	s_and_b64 s[16:17], s[38:39], exec
	s_cselect_b32 s19, s49, s1
	s_cselect_b32 s23, s48, s0
	s_ashr_i32 s45, s44, 31
	s_lshl_b64 s[16:17], s[44:45], 20
	s_add_u32 s50, s13, s16
	s_addc_u32 s51, s22, s17
	s_and_b64 s[16:17], s[38:39], exec
	s_cselect_b32 s28, s51, s11
	s_cselect_b32 s29, s50, s10
	s_add_u32 s0, s0, 0x80080
	s_addc_u32 s1, s1, 0
	s_add_u32 s45, s10, 0x100
	s_addc_u32 s47, s11, 0
	s_mov_b32 s52, -2
	s_add_u32 s10, s0, 0xfff80080
	s_addc_u32 s11, s1, -1
	s_add_i32 s53, 0, 0x10000
	s_cmp_eq_u32 s52, 28
	s_cselect_b32 s17, s19, s11
	s_cselect_b32 s16, s23, s10
	v_add_u32_e32 v146, s53, v149
	s_cselect_b32 s11, s28, s47
	s_cselect_b32 s10, s29, s45
	s_add_i32 s56, 0, 0x14000
	ds_read_b128 v[138:141], v146
	ds_read_b128 v[142:145], v146 offset:1024
	ds_read_b128 v[152:155], v146 offset:2048
	ds_read_b128 v[156:159], v146 offset:3072
	v_add_u32_e32 v146, s56, v149
	ds_read_b128 v[184:187], v146
	ds_read_b128 v[188:191], v146 offset:1024
	ds_read_b128 v[192:195], v146 offset:2048
	ds_read_b128 v[196:199], v146 offset:3072
	v_lshl_add_u64 v[146:147], s[0:1], 0, v[134:135]
	s_add_i32 m0, s35, 0xc000
	ds_read_b128 v[200:203], v151
	ds_read_b128 v[214:217], v151 offset:1024
	ds_read_b128 v[218:221], v151 offset:2048
	ds_read_b128 v[222:225], v151 offset:3072
	ds_read_b128 v[226:229], v151 offset:4096
	ds_read_b128 v[230:233], v151 offset:5120
	ds_read_b128 v[234:237], v151 offset:6144
	ds_read_b128 v[238:241], v151 offset:7168
	global_load_lds_dwordx4 v[146:147], off
	v_lshl_add_u64 v[146:147], s[0:1], 0, v[136:137]
	s_add_i32 m0, s35, 0xe000
	s_nop 0
	global_load_lds_dwordx4 v[146:147], off
	s_waitcnt vmcnt(8)
	s_waitcnt lgkmcnt(0)
	s_barrier
	s_setprio 1
	s_waitcnt lgkmcnt(0)
	v_mfma_f32_16x16x32_bf16 v[124:127], v[138:141], v[200:203], 0
	v_mfma_f32_16x16x32_bf16 v[120:123], v[152:155], v[200:203], 0
	v_mfma_f32_16x16x32_bf16 v[108:111], v[138:141], v[218:221], 0
	v_mfma_f32_16x16x32_bf16 v[104:107], v[152:155], v[218:221], 0
	v_mfma_f32_16x16x32_bf16 v[92:95], v[138:141], v[226:229], 0
	v_mfma_f32_16x16x32_bf16 v[88:91], v[152:155], v[226:229], 0
	v_mfma_f32_16x16x32_bf16 v[76:79], v[138:141], v[234:237], 0
	v_mfma_f32_16x16x32_bf16 v[72:75], v[152:155], v[234:237], 0
	v_mfma_f32_16x16x32_bf16 v[124:127], v[142:145], v[214:217], v[124:127]
	v_mfma_f32_16x16x32_bf16 v[120:123], v[156:159], v[214:217], v[120:123]
	v_mfma_f32_16x16x32_bf16 v[108:111], v[142:145], v[222:225], v[108:111]
	v_mfma_f32_16x16x32_bf16 v[104:107], v[156:159], v[222:225], v[104:107]
	v_mfma_f32_16x16x32_bf16 v[92:95], v[142:145], v[230:233], v[92:95]
	v_mfma_f32_16x16x32_bf16 v[88:91], v[156:159], v[230:233], v[88:91]
	v_mfma_f32_16x16x32_bf16 v[76:79], v[142:145], v[238:241], v[76:79]
	v_mfma_f32_16x16x32_bf16 v[72:75], v[156:159], v[238:241], v[72:75]
	s_setprio 0
	s_setprio 1
	v_mfma_f32_16x16x32_bf16 v[116:119], v[184:187], v[200:203], 0
	v_mfma_f32_16x16x32_bf16 v[112:115], v[192:195], v[200:203], 0
	v_mfma_f32_16x16x32_bf16 v[100:103], v[184:187], v[218:221], 0
	v_mfma_f32_16x16x32_bf16 v[96:99], v[192:195], v[218:221], 0
	v_mfma_f32_16x16x32_bf16 v[84:87], v[184:187], v[226:229], 0
	v_mfma_f32_16x16x32_bf16 v[80:83], v[192:195], v[226:229], 0
	v_mfma_f32_16x16x32_bf16 v[68:71], v[184:187], v[234:237], 0
	v_mfma_f32_16x16x32_bf16 v[64:67], v[192:195], v[234:237], 0
	v_mfma_f32_16x16x32_bf16 v[116:119], v[188:191], v[214:217], v[116:119]
	v_mfma_f32_16x16x32_bf16 v[112:115], v[196:199], v[214:217], v[112:115]
	v_mfma_f32_16x16x32_bf16 v[100:103], v[188:191], v[222:225], v[100:103]
	v_mfma_f32_16x16x32_bf16 v[96:99], v[196:199], v[222:225], v[96:99]
	v_mfma_f32_16x16x32_bf16 v[84:87], v[188:191], v[230:233], v[84:87]
	v_mfma_f32_16x16x32_bf16 v[80:83], v[196:199], v[230:233], v[80:83]
	v_mfma_f32_16x16x32_bf16 v[68:71], v[188:191], v[238:241], v[68:71]
	v_mfma_f32_16x16x32_bf16 v[64:67], v[196:199], v[238:241], v[64:67]
	s_setprio 0
	s_barrier
	s_add_i32 s53, s53, s34
	v_lshl_add_u64 v[146:147], s[10:11], 0, v[160:161]
	s_mov_b32 m0, s53
	ds_read_b128 v[200:203], v151 offset:16384
	ds_read_b128 v[214:217], v151 offset:17408
	ds_read_b128 v[218:221], v151 offset:18432
	ds_read_b128 v[222:225], v151 offset:19456
	ds_read_b128 v[226:229], v151 offset:20480
	ds_read_b128 v[230:233], v151 offset:21504
	ds_read_b128 v[234:237], v151 offset:22528
	ds_read_b128 v[238:241], v151 offset:23552
	global_load_lds_dwordx4 v[146:147], off
	s_add_i32 m0, s53, 0x2000
	s_add_u32 s60, s10, 0x80000
	v_lshl_add_u64 v[162:163], s[10:11], 0, v[128:129]
	s_addc_u32 s61, s11, 0
	s_add_i32 s53, s56, s34
	global_load_lds_dwordx4 v[162:163], off
	v_lshl_add_u64 v[242:243], s[60:61], 0, v[160:161]
	s_mov_b32 m0, s53
	v_lshl_add_u64 v[244:245], s[16:17], 0, v[130:131]
	global_load_lds_dwordx4 v[242:243], off
	v_lshl_add_u64 v[242:243], s[60:61], 0, v[128:129]
	s_add_i32 m0, s53, 0x2000
	s_nop 0
	global_load_lds_dwordx4 v[242:243], off
	v_lshl_add_u64 v[242:243], s[16:17], 0, v[132:133]
	s_mov_b32 m0, s35
	s_nop 0
	global_load_lds_dwordx4 v[242:243], off
	s_mov_b32 m0, s36
	s_nop 0
	global_load_lds_dwordx4 v[244:245], off
	s_waitcnt vmcnt(8)
	s_waitcnt lgkmcnt(0)
	s_barrier
; #define PG8_STAGE(bufoff, gbase, voff) do { _Pragma("unroll") for (int _i = 0; _i < 2; ++_i) \
;         __builtin_amdgcn_global_load_lds((const unsigned*)((const char*)(gbase) + (voff)[_i]), (PG8_LAS unsigned*)(lds + (bufoff) + ldsw + _i * 8192), 16, 0, 0); } while (0)
; #define PG8_WAIT_V(n) asm volatile("s_waitcnt vmcnt(" #n ")" ::: "memory")
; #define PG8_WAIT_L(n) asm volatile("s_waitcnt lgkmcnt(" #n ")" ::: "memory")
; #define PG8_BAR __builtin_amdgcn_s_barrier()
; #define PG8_SCHED __builtin_amdgcn_sched_barrier(0)
; template <class Epi, class Sched, bool ALIGN_EPI = false, bool SP2 = false, bool F8 = false>
; __device__ __forceinline__ void gemm_phase(PG8_LAS unsigned char* lds, const Gemm g, const Sched& S, const Epi& E) {
;     ...
;             PG8_WAIT_V(8); PG8_WAIT_L(0); PG8_BAR; PG8_MMA(0, 0, At, B0); PG8_MMA(0, 1, At, B1); PG8_BAR; PG8_SCHED;
;             PG8_LDA(At, 0, 1); PG8_STAGE(PG8_SB(0, 0), b2, voffB); PG8_STAGE(PG8_SB(0, 1), b2 + hstep, voffB); PG8_STAGE(PG8_SA(0, 0), a2, voffA);
;             PG8_WAIT_V(8); PG8_WAIT_L(0); PG8_BAR; PG8_MMA(1, 0, At, B0); PG8_MMA(1, 1, At, B1); PG8_BAR; PG8_SCHED;
;             PG8_LDB(B0, 1, 0); PG8_LDB(B1, 1, 1); PG8_SCHED; PG8_LDA(At, 1, 0); PG8_STAGE(PG8_SA(0, 1), a2 + hstep, voffA);
;             PG8_WAIT_V(8); PG8_WAIT_L(0); PG8_BAR; PG8_MMA(0, 0, At, B0); PG8_MMA(0, 1, At, B1); PG8_BAR; PG8_SCHED;
	s_setprio 1
	s_waitcnt lgkmcnt(0)
	v_mfma_f32_16x16x32_bf16 v[60:63], v[138:141], v[200:203], 0
	v_mfma_f32_16x16x32_bf16 v[56:59], v[152:155], v[200:203], 0
	v_mfma_f32_16x16x32_bf16 v[44:47], v[138:141], v[218:221], 0
	v_mfma_f32_16x16x32_bf16 v[40:43], v[152:155], v[218:221], 0
	v_mfma_f32_16x16x32_bf16 v[28:31], v[138:141], v[226:229], 0
	v_mfma_f32_16x16x32_bf16 v[24:27], v[152:155], v[226:229], 0
	v_mfma_f32_16x16x32_bf16 v[12:15], v[138:141], v[234:237], 0
	v_mfma_f32_16x16x32_bf16 v[8:11], v[152:155], v[234:237], 0
	v_mfma_f32_16x16x32_bf16 v[60:63], v[142:145], v[214:217], v[60:63]
	v_mfma_f32_16x16x32_bf16 v[56:59], v[156:159], v[214:217], v[56:59]
	v_mfma_f32_16x16x32_bf16 v[44:47], v[142:145], v[222:225], v[44:47]
	v_mfma_f32_16x16x32_bf16 v[40:43], v[156:159], v[222:225], v[40:43]
	v_mfma_f32_16x16x32_bf16 v[28:31], v[142:145], v[230:233], v[28:31]
	v_mfma_f32_16x16x32_bf16 v[24:27], v[156:159], v[230:233], v[24:27]
	v_mfma_f32_16x16x32_bf16 v[12:15], v[142:145], v[238:241], v[12:15]
	v_mfma_f32_16x16x32_bf16 v[8:11], v[156:159], v[238:241], v[8:11]
	s_setprio 0
	s_setprio 1
	v_mfma_f32_16x16x32_bf16 v[52:55], v[184:187], v[200:203], 0
	v_mfma_f32_16x16x32_bf16 v[48:51], v[192:195], v[200:203], 0
	v_mfma_f32_16x16x32_bf16 v[36:39], v[184:187], v[218:221], 0
	v_mfma_f32_16x16x32_bf16 v[32:35], v[192:195], v[218:221], 0
	v_mfma_f32_16x16x32_bf16 v[20:23], v[184:187], v[226:229], 0
	v_mfma_f32_16x16x32_bf16 v[16:19], v[192:195], v[226:229], 0
	v_mfma_f32_16x16x32_bf16 v[4:7], v[184:187], v[234:237], 0
	v_mfma_f32_16x16x32_bf16 v[0:3], v[192:195], v[234:237], 0
	v_mfma_f32_16x16x32_bf16 v[52:55], v[188:191], v[214:217], v[52:55]
	v_mfma_f32_16x16x32_bf16 v[48:51], v[196:199], v[214:217], v[48:51]
	v_mfma_f32_16x16x32_bf16 v[36:39], v[188:191], v[222:225], v[36:39]
	v_mfma_f32_16x16x32_bf16 v[32:35], v[196:199], v[222:225], v[32:35]
	v_mfma_f32_16x16x32_bf16 v[20:23], v[188:191], v[230:233], v[20:23]
	v_mfma_f32_16x16x32_bf16 v[16:19], v[196:199], v[230:233], v[16:19]
	v_mfma_f32_16x16x32_bf16 v[4:7], v[188:191], v[238:241], v[4:7]
	v_mfma_f32_16x16x32_bf16 v[0:3], v[196:199], v[238:241], v[0:3]
	s_setprio 0
	s_barrier
	s_add_i32 s53, 0, 0x18000
	s_add_i32 s56, 0, 0x1c000
	v_add_u32_e32 v156, s53, v149
	v_add_u32_e32 v196, s56, v149
	ds_read_b128 v[138:141], v156
	ds_read_b128 v[142:145], v156 offset:1024
	ds_read_b128 v[152:155], v156 offset:2048
	ds_read_b128 v[156:159], v156 offset:3072
	ds_read_b128 v[184:187], v196
	ds_read_b128 v[188:191], v196 offset:1024
	ds_read_b128 v[192:195], v196 offset:2048
	ds_read_b128 v[196:199], v196 offset:3072
	s_add_u32 s16, s16, 0x80000
	s_addc_u32 s17, s17, 0
	s_mov_b32 m0, s37
	v_lshl_add_u64 v[246:247], s[16:17], 0, v[132:133]
	ds_read_b128 v[200:203], v151 offset:32768
	ds_read_b128 v[214:217], v151 offset:33792
	ds_read_b128 v[218:221], v151 offset:34816
	ds_read_b128 v[222:225], v151 offset:35840
	ds_read_b128 v[226:229], v151 offset:36864
	ds_read_b128 v[230:233], v151 offset:37888
	ds_read_b128 v[234:237], v151 offset:38912
	ds_read_b128 v[238:241], v151 offset:39936
	global_load_lds_dwordx4 v[246:247], off
	v_lshl_add_u64 v[246:247], s[16:17], 0, v[130:131]
	s_mov_b32 m0, s54
	s_nop 0
	global_load_lds_dwordx4 v[246:247], off
	s_waitcnt vmcnt(8)
	s_waitcnt lgkmcnt(0)
	s_barrier
	s_setprio 1
	s_waitcnt lgkmcnt(0)
	v_mfma_f32_16x16x32_bf16 v[124:127], v[138:141], v[200:203], v[124:127]
	v_mfma_f32_16x16x32_bf16 v[120:123], v[152:155], v[200:203], v[120:123]
	v_mfma_f32_16x16x32_bf16 v[108:111], v[138:141], v[218:221], v[108:111]
	v_mfma_f32_16x16x32_bf16 v[104:107], v[152:155], v[218:221], v[104:107]
	v_mfma_f32_16x16x32_bf16 v[92:95], v[138:141], v[226:229], v[92:95]
	v_mfma_f32_16x16x32_bf16 v[88:91], v[152:155], v[226:229], v[88:91]
	v_mfma_f32_16x16x32_bf16 v[76:79], v[138:141], v[234:237], v[76:79]
	v_mfma_f32_16x16x32_bf16 v[72:75], v[152:155], v[234:237], v[72:75]
	v_mfma_f32_16x16x32_bf16 v[124:127], v[142:145], v[214:217], v[124:127]
	v_mfma_f32_16x16x32_bf16 v[120:123], v[156:159], v[214:217], v[120:123]
	v_mfma_f32_16x16x32_bf16 v[108:111], v[142:145], v[222:225], v[108:111]
	v_mfma_f32_16x16x32_bf16 v[104:107], v[156:159], v[222:225], v[104:107]
	v_mfma_f32_16x16x32_bf16 v[92:95], v[142:145], v[230:233], v[92:95]
	v_mfma_f32_16x16x32_bf16 v[88:91], v[156:159], v[230:233], v[88:91]
	v_mfma_f32_16x16x32_bf16 v[76:79], v[142:145], v[238:241], v[76:79]
	v_mfma_f32_16x16x32_bf16 v[72:75], v[156:159], v[238:241], v[72:75]
	s_setprio 0
	s_setprio 1
	v_mfma_f32_16x16x32_bf16 v[116:119], v[184:187], v[200:203], v[116:119]
	v_mfma_f32_16x16x32_bf16 v[112:115], v[192:195], v[200:203], v[112:115]
	v_mfma_f32_16x16x32_bf16 v[100:103], v[184:187], v[218:221], v[100:103]
	v_mfma_f32_16x16x32_bf16 v[96:99], v[192:195], v[218:221], v[96:99]
	v_mfma_f32_16x16x32_bf16 v[84:87], v[184:187], v[226:229], v[84:87]
	v_mfma_f32_16x16x32_bf16 v[80:83], v[192:195], v[226:229], v[80:83]
	v_mfma_f32_16x16x32_bf16 v[68:71], v[184:187], v[234:237], v[68:71]
	v_mfma_f32_16x16x32_bf16 v[64:67], v[192:195], v[234:237], v[64:67]
	v_mfma_f32_16x16x32_bf16 v[116:119], v[188:191], v[214:217], v[116:119]
	v_mfma_f32_16x16x32_bf16 v[112:115], v[196:199], v[214:217], v[112:115]
	v_mfma_f32_16x16x32_bf16 v[100:103], v[188:191], v[222:225], v[100:103]
	v_mfma_f32_16x16x32_bf16 v[96:99], v[196:199], v[222:225], v[96:99]
	v_mfma_f32_16x16x32_bf16 v[84:87], v[188:191], v[230:233], v[84:87]
	v_mfma_f32_16x16x32_bf16 v[80:83], v[196:199], v[230:233], v[80:83]
	v_mfma_f32_16x16x32_bf16 v[68:71], v[188:191], v[238:241], v[68:71]
	v_mfma_f32_16x16x32_bf16 v[64:67], v[196:199], v[238:241], v[64:67]
	s_setprio 0
	s_barrier
; #define PG8_STAGE(bufoff, gbase, voff) do { _Pragma("unroll") for (int _i = 0; _i < 2; ++_i) \
;         __builtin_amdgcn_global_load_lds((const unsigned*)((const char*)(gbase) + (voff)[_i]), (PG8_LAS unsigned*)(lds + (bufoff) + ldsw + _i * 8192), 16, 0, 0); } while (0)
; #define PG8_WAIT_V(n) asm volatile("s_waitcnt vmcnt(" #n ")" ::: "memory")
; #define PG8_WAIT_L(n) asm volatile("s_waitcnt lgkmcnt(" #n ")" ::: "memory")
; #define PG8_BAR __builtin_amdgcn_s_barrier()
; #define PG8_SCHED __builtin_amdgcn_sched_barrier(0)
; template <class Epi, class Sched, bool ALIGN_EPI = false, bool SP2 = false, bool F8 = false>
; __device__ __forceinline__ void gemm_phase(PG8_LAS unsigned char* lds, const Gemm g, const Sched& S, const Epi& E) {
;     ...
;         for (int t = 0; t < nt; t += 2) {
;             const bool last = (t == nt - 2);
;             const char* a1 = cA + (size_t)(t + 1) * kstep;
;             const char* a2 = last ? nA : cA + (size_t)(t + 2) * kstep; const char* b2 = last ? nB : cB + (size_t)(t + 2) * kstep;
;     ...
;             PG8_WAIT_V(8); PG8_WAIT_L(0); PG8_BAR; PG8_MMA(0, 0, At, B0); PG8_MMA(0, 1, At, B1); PG8_BAR; PG8_SCHED;
;             PG8_LDA(At, 1, 1); PG8_STAGE(PG8_SB(1, 0), b3, voffB); PG8_STAGE(PG8_SB(1, 1), b3 + hstep, voffB); PG8_STAGE(PG8_SA(1, 0), a3, voffA);
;             PG8_WAIT_V(8); PG8_WAIT_L(0); PG8_BAR; PG8_MMA(1, 0, At, B0); PG8_MMA(1, 1, At, B1); PG8_BAR; PG8_SCHED;
	s_add_i32 s16, s53, s34
	v_lshl_add_u64 v[146:147], v[146:147], 0, s[14:15]
	s_mov_b32 m0, s16
	ds_read_b128 v[200:203], v151 offset:49152
	ds_read_b128 v[214:217], v151 offset:50176
	ds_read_b128 v[218:221], v151 offset:51200
	ds_read_b128 v[222:225], v151 offset:52224
	ds_read_b128 v[226:229], v151 offset:53248
	ds_read_b128 v[230:233], v151 offset:54272
	ds_read_b128 v[234:237], v151 offset:55296
	ds_read_b128 v[238:241], v151 offset:56320
	global_load_lds_dwordx4 v[146:147], off
	s_add_i32 m0, s16, 0x2000
	s_add_u32 s10, s10, 0x80080
	v_lshl_add_u64 v[146:147], v[162:163], 0, s[14:15]
	s_addc_u32 s11, s11, 0
	s_add_i32 s16, s56, s34
	global_load_lds_dwordx4 v[146:147], off
	v_lshl_add_u64 v[146:147], s[10:11], 0, v[160:161]
	s_mov_b32 m0, s16
	s_nop 0
	global_load_lds_dwordx4 v[146:147], off
	v_lshl_add_u64 v[146:147], s[10:11], 0, v[128:129]
	s_add_i32 m0, s16, 0x2000
	s_nop 0
	global_load_lds_dwordx4 v[146:147], off
	v_lshl_add_u64 v[146:147], v[242:243], 0, s[14:15]
	s_mov_b32 m0, s55
	s_nop 0
	global_load_lds_dwordx4 v[146:147], off
	v_lshl_add_u64 v[146:147], v[244:245], 0, s[14:15]
	s_mov_b32 m0, s58
	s_nop 0
	global_load_lds_dwordx4 v[146:147], off
	s_waitcnt vmcnt(8)
	s_waitcnt lgkmcnt(0)
	s_barrier
	s_setprio 1
	s_waitcnt lgkmcnt(0)
	v_mfma_f32_16x16x32_bf16 v[60:63], v[138:141], v[200:203], v[60:63]
	v_mfma_f32_16x16x32_bf16 v[56:59], v[152:155], v[200:203], v[56:59]
	v_mfma_f32_16x16x32_bf16 v[44:47], v[138:141], v[218:221], v[44:47]
	v_mfma_f32_16x16x32_bf16 v[40:43], v[152:155], v[218:221], v[40:43]
	v_mfma_f32_16x16x32_bf16 v[28:31], v[138:141], v[226:229], v[28:31]
	v_mfma_f32_16x16x32_bf16 v[24:27], v[152:155], v[226:229], v[24:27]
	v_mfma_f32_16x16x32_bf16 v[12:15], v[138:141], v[234:237], v[12:15]
	v_mfma_f32_16x16x32_bf16 v[8:11], v[152:155], v[234:237], v[8:11]
	v_mfma_f32_16x16x32_bf16 v[60:63], v[142:145], v[214:217], v[60:63]
	v_mfma_f32_16x16x32_bf16 v[56:59], v[156:159], v[214:217], v[56:59]
	v_mfma_f32_16x16x32_bf16 v[44:47], v[142:145], v[222:225], v[44:47]
	v_mfma_f32_16x16x32_bf16 v[40:43], v[156:159], v[222:225], v[40:43]
	v_mfma_f32_16x16x32_bf16 v[28:31], v[142:145], v[230:233], v[28:31]
	v_mfma_f32_16x16x32_bf16 v[24:27], v[156:159], v[230:233], v[24:27]
	v_mfma_f32_16x16x32_bf16 v[12:15], v[142:145], v[238:241], v[12:15]
	v_mfma_f32_16x16x32_bf16 v[8:11], v[156:159], v[238:241], v[8:11]
	s_setprio 0
	s_setprio 1
	v_mfma_f32_16x16x32_bf16 v[52:55], v[184:187], v[200:203], v[52:55]
	v_mfma_f32_16x16x32_bf16 v[48:51], v[192:195], v[200:203], v[48:51]
	v_mfma_f32_16x16x32_bf16 v[36:39], v[184:187], v[218:221], v[36:39]
	v_mfma_f32_16x16x32_bf16 v[32:35], v[192:195], v[218:221], v[32:35]
	v_mfma_f32_16x16x32_bf16 v[20:23], v[184:187], v[226:229], v[20:23]
	v_mfma_f32_16x16x32_bf16 v[16:19], v[192:195], v[226:229], v[16:19]
	v_mfma_f32_16x16x32_bf16 v[4:7], v[184:187], v[234:237], v[4:7]
	v_mfma_f32_16x16x32_bf16 v[0:3], v[192:195], v[234:237], v[0:3]
	v_mfma_f32_16x16x32_bf16 v[52:55], v[188:191], v[214:217], v[52:55]
	v_mfma_f32_16x16x32_bf16 v[48:51], v[196:199], v[214:217], v[48:51]
	v_mfma_f32_16x16x32_bf16 v[36:39], v[188:191], v[222:225], v[36:39]
	v_mfma_f32_16x16x32_bf16 v[32:35], v[196:199], v[222:225], v[32:35]
	v_mfma_f32_16x16x32_bf16 v[20:23], v[188:191], v[230:233], v[20:23]
	v_mfma_f32_16x16x32_bf16 v[16:19], v[196:199], v[230:233], v[16:19]
	v_mfma_f32_16x16x32_bf16 v[4:7], v[188:191], v[238:241], v[4:7]
	v_mfma_f32_16x16x32_bf16 v[0:3], v[196:199], v[238:241], v[0:3]
	s_setprio 0
	s_barrier
	s_add_i32 s52, s52, 2
	s_add_u32 s0, s0, 0x100
	s_addc_u32 s1, s1, 0
	s_add_u32 s45, s45, 0x100
	s_addc_u32 s47, s47, 0
	s_cmp_gt_u32 s52, 29
	s_cbranch_scc0 .LBB0_32
	s_branch .Lgk_after_32

; #define PG8_BAR __builtin_amdgcn_s_barrier()
; template <class Epi, class Sched, bool ALIGN_EPI = false, bool SP2 = false, bool F8 = false>
; __device__ __forceinline__ void gemm_phase(PG8_LAS unsigned char* lds, const Gemm g, const Sched& S, const Epi& E) {
;     ...
;         if constexpr (ALIGN_EPI) { if (wr == 0) PG8_BAR; }
.Lgk_after_32:
	s_and_b64 vcc, exec, s[4:5]
	s_cbranch_vccz .LBB0_35
	s_barrier

; #define PG8_STAGE(bufoff, gbase, voff) do { _Pragma("unroll") for (int _i = 0; _i < 2; ++_i) \
;         __builtin_amdgcn_global_load_lds((const unsigned*)((const char*)(gbase) + (voff)[_i]), (PG8_LAS unsigned*)(lds + (bufoff) + ldsw + _i * 8192), 16, 0, 0); } while (0)
; #define PG8_WAIT_V(n) asm volatile("s_waitcnt vmcnt(" #n ")" ::: "memory")
; #define PG8_WAIT_L(n) asm volatile("s_waitcnt lgkmcnt(" #n ")" ::: "memory")
; #define PG8_BAR __builtin_amdgcn_s_barrier()
; #define PG8_SCHED __builtin_amdgcn_sched_barrier(0)
; template <class Epi, class Sched, bool ALIGN_EPI = false, bool SP2 = false, bool F8 = false>
; __device__ __forceinline__ void gemm_phase(PG8_LAS unsigned char* lds, const Gemm g, const Sched& S, const Epi& E) {
;     ...
;         const bool has_next = S.next(ui + 1, nxt);
;         const char* nA = has_next ? (const char*)g.A + (size_t)nxt.pm * tstep : cA; const char* nB = has_next ? (const char*)g.Bt + (size_t)nxt.pn * tstep : cB;
;         for (int t = 0; t < nt; t += 2) {
;             const bool last = (t == nt - 2);
;             const char* a1 = cA + (size_t)(t + 1) * kstep;
;             const char* a2 = last ? nA : cA + (size_t)(t + 2) * kstep; const char* b2 = last ? nB : cB + (size_t)(t + 2) * kstep;
;             const char* a3 = a2 + kstep; const char* b3 = b2 + kstep;
;             if (last && has_next) S.a_ready(nxt);
;             if constexpr (SP2) {
;             PG8_LDB(B0, 0, 0); PG8_LDB(B1, 0, 1); PG8_SCHED; PG8_LDA(At, 0, 0); PG8_STAGE(PG8_SA(1, 1), a1 + hstep, voffA);
;             PG8_WAIT_V(8); PG8_WAIT_L(0); PG8_BAR; PG8_MMA(0, 0, At, B0); PG8_MMA(0, 1, At, B1); PG8_BAR; PG8_SCHED;
.LBB0_58:
	s_ashr_i32 s49, s48, 31
	s_lshl_b64 s[8:9], s[48:49], 20
	s_add_u32 s50, s26, s8
	s_addc_u32 s51, s27, s9
	s_and_b64 s[8:9], s[40:41], exec
	s_cselect_b32 s1, s51, s37
	s_cselect_b32 s8, s50, s36
	s_ashr_i32 s47, s46, 31
	s_lshl_b64 s[28:29], s[46:47], 20
	s_add_u32 s54, s13, s28
	s_addc_u32 s55, s22, s29
	s_and_b64 s[28:29], s[40:41], exec
	s_cselect_b32 s9, s55, s59
	s_cselect_b32 s11, s54, s58
	s_add_u32 s36, s36, 0x80080
	s_addc_u32 s37, s37, 0
	s_add_u32 s19, s58, 0x100
	s_addc_u32 s23, s59, 0
	s_mov_b32 s28, -2
	s_add_u32 s29, s36, 0xfff80080
	s_addc_u32 s34, s37, -1
	s_add_i32 s35, 0, 0x10000
	s_cmp_eq_u32 s28, 28
	s_cselect_b32 s61, s1, s34
	s_cselect_b32 s60, s8, s29
	s_cselect_b32 s59, s9, s23
	s_cselect_b32 s58, s11, s19
	s_add_i32 s29, 0, 0x14000
	v_add_u32_e32 v154, s35, v151
	v_add_u32_e32 v158, s29, v151
	ds_read_b128 v[138:141], v154
	ds_read_b128 v[142:145], v154 offset:1024
	ds_read_b128 v[146:149], v154 offset:2048
	ds_read_b128 v[154:157], v154 offset:3072
	ds_read_b128 v[184:187], v158
	ds_read_b128 v[188:191], v158 offset:1024
	ds_read_b128 v[192:195], v158 offset:2048
	ds_read_b128 v[196:199], v158 offset:3072
	v_lshl_add_u64 v[158:159], s[36:37], 0, v[134:135]
	s_add_i32 m0, s17, 0xc000
	ds_read_b128 v[200:203], v153
	ds_read_b128 v[214:217], v153 offset:1024
	ds_read_b128 v[218:221], v153 offset:2048
	ds_read_b128 v[222:225], v153 offset:3072
	ds_read_b128 v[226:229], v153 offset:4096
	ds_read_b128 v[230:233], v153 offset:5120
	ds_read_b128 v[234:237], v153 offset:6144
	ds_read_b128 v[238:241], v153 offset:7168
	global_load_lds_dwordx4 v[158:159], off
	v_lshl_add_u64 v[158:159], s[36:37], 0, v[136:137]
	s_add_i32 m0, s17, 0xe000
	s_nop 0
	global_load_lds_dwordx4 v[158:159], off
	s_waitcnt vmcnt(8)
	s_waitcnt lgkmcnt(0)
	s_barrier
	s_setprio 1
	s_waitcnt lgkmcnt(0)
	v_mfma_f32_16x16x32_bf16 v[124:127], v[138:141], v[200:203], 0
	v_mfma_f32_16x16x32_bf16 v[120:123], v[146:149], v[200:203], 0
	v_mfma_f32_16x16x32_bf16 v[108:111], v[138:141], v[218:221], 0
	v_mfma_f32_16x16x32_bf16 v[104:107], v[146:149], v[218:221], 0
	v_mfma_f32_16x16x32_bf16 v[92:95], v[138:141], v[226:229], 0
	v_mfma_f32_16x16x32_bf16 v[88:91], v[146:149], v[226:229], 0
	v_mfma_f32_16x16x32_bf16 v[76:79], v[138:141], v[234:237], 0
	v_mfma_f32_16x16x32_bf16 v[72:75], v[146:149], v[234:237], 0
	v_mfma_f32_16x16x32_bf16 v[124:127], v[142:145], v[214:217], v[124:127]
	v_mfma_f32_16x16x32_bf16 v[120:123], v[154:157], v[214:217], v[120:123]
	v_mfma_f32_16x16x32_bf16 v[108:111], v[142:145], v[222:225], v[108:111]
	v_mfma_f32_16x16x32_bf16 v[104:107], v[154:157], v[222:225], v[104:107]
	v_mfma_f32_16x16x32_bf16 v[92:95], v[142:145], v[230:233], v[92:95]
	v_mfma_f32_16x16x32_bf16 v[88:91], v[154:157], v[230:233], v[88:91]
	v_mfma_f32_16x16x32_bf16 v[76:79], v[142:145], v[238:241], v[76:79]
	v_mfma_f32_16x16x32_bf16 v[72:75], v[154:157], v[238:241], v[72:75]
	s_setprio 0
	s_setprio 1
	v_mfma_f32_16x16x32_bf16 v[116:119], v[184:187], v[200:203], 0
	v_mfma_f32_16x16x32_bf16 v[112:115], v[192:195], v[200:203], 0
	v_mfma_f32_16x16x32_bf16 v[100:103], v[184:187], v[218:221], 0
	v_mfma_f32_16x16x32_bf16 v[96:99], v[192:195], v[218:221], 0
	v_mfma_f32_16x16x32_bf16 v[84:87], v[184:187], v[226:229], 0
	v_mfma_f32_16x16x32_bf16 v[80:83], v[192:195], v[226:229], 0
	v_mfma_f32_16x16x32_bf16 v[68:71], v[184:187], v[234:237], 0
	v_mfma_f32_16x16x32_bf16 v[64:67], v[192:195], v[234:237], 0
	v_mfma_f32_16x16x32_bf16 v[116:119], v[188:191], v[214:217], v[116:119]
	v_mfma_f32_16x16x32_bf16 v[112:115], v[196:199], v[214:217], v[112:115]
	v_mfma_f32_16x16x32_bf16 v[100:103], v[188:191], v[222:225], v[100:103]
	v_mfma_f32_16x16x32_bf16 v[96:99], v[196:199], v[222:225], v[96:99]
	v_mfma_f32_16x16x32_bf16 v[84:87], v[188:191], v[230:233], v[84:87]
	v_mfma_f32_16x16x32_bf16 v[80:83], v[196:199], v[230:233], v[80:83]
	v_mfma_f32_16x16x32_bf16 v[68:71], v[188:191], v[238:241], v[68:71]
	v_mfma_f32_16x16x32_bf16 v[64:67], v[196:199], v[238:241], v[64:67]
	s_setprio 0
	s_barrier
	s_add_i32 s34, s35, s64
	v_lshl_add_u64 v[158:159], s[58:59], 0, v[160:161]
	s_mov_b32 m0, s34
	ds_read_b128 v[200:203], v153 offset:16384
	ds_read_b128 v[214:217], v153 offset:17408
	ds_read_b128 v[218:221], v153 offset:18432
	ds_read_b128 v[222:225], v153 offset:19456
	ds_read_b128 v[226:229], v153 offset:20480
	ds_read_b128 v[230:233], v153 offset:21504
	ds_read_b128 v[234:237], v153 offset:22528
	ds_read_b128 v[238:241], v153 offset:23552
	global_load_lds_dwordx4 v[158:159], off
	s_add_i32 m0, s34, 0x2000
	s_add_u32 s34, s58, 0x80000
	v_lshl_add_u64 v[162:163], s[58:59], 0, v[132:133]
	s_addc_u32 s35, s59, 0
	s_add_i32 s29, s29, s64
	global_load_lds_dwordx4 v[162:163], off
	v_lshl_add_u64 v[242:243], s[34:35], 0, v[160:161]
	s_mov_b32 m0, s29
	v_lshl_add_u64 v[244:245], s[60:61], 0, v[130:131]
	global_load_lds_dwordx4 v[242:243], off
	v_lshl_add_u64 v[242:243], s[34:35], 0, v[132:133]
	s_add_i32 m0, s29, 0x2000
	s_nop 0
	global_load_lds_dwordx4 v[242:243], off
	v_lshl_add_u64 v[242:243], s[60:61], 0, v[128:129]
	s_mov_b32 m0, s17
	s_nop 0
	global_load_lds_dwordx4 v[242:243], off
	s_mov_b32 m0, s65
	s_nop 0
	global_load_lds_dwordx4 v[244:245], off
	s_waitcnt vmcnt(8)
	s_waitcnt lgkmcnt(0)
	s_barrier
; #define PG8_STAGE(bufoff, gbase, voff) do { _Pragma("unroll") for (int _i = 0; _i < 2; ++_i) \
;         __builtin_amdgcn_global_load_lds((const unsigned*)((const char*)(gbase) + (voff)[_i]), (PG8_LAS unsigned*)(lds + (bufoff) + ldsw + _i * 8192), 16, 0, 0); } while (0)
; #define PG8_WAIT_V(n) asm volatile("s_waitcnt vmcnt(" #n ")" ::: "memory")
; #define PG8_WAIT_L(n) asm volatile("s_waitcnt lgkmcnt(" #n ")" ::: "memory")
; #define PG8_BAR __builtin_amdgcn_s_barrier()
; #define PG8_SCHED __builtin_amdgcn_sched_barrier(0)
; template <class Epi, class Sched, bool ALIGN_EPI = false, bool SP2 = false, bool F8 = false>
; __device__ __forceinline__ void gemm_phase(PG8_LAS unsigned char* lds, const Gemm g, const Sched& S, const Epi& E) {
;     ...
;             PG8_WAIT_V(8); PG8_WAIT_L(0); PG8_BAR; PG8_MMA(0, 0, At, B0); PG8_MMA(0, 1, At, B1); PG8_BAR; PG8_SCHED;
;             PG8_LDA(At, 0, 1); PG8_STAGE(PG8_SB(0, 0), b2, voffB); PG8_STAGE(PG8_SB(0, 1), b2 + hstep, voffB); PG8_STAGE(PG8_SA(0, 0), a2, voffA);
;             PG8_WAIT_V(8); PG8_WAIT_L(0); PG8_BAR; PG8_MMA(1, 0, At, B0); PG8_MMA(1, 1, At, B1); PG8_BAR; PG8_SCHED;
;             PG8_LDB(B0, 1, 0); PG8_LDB(B1, 1, 1); PG8_SCHED; PG8_LDA(At, 1, 0); PG8_STAGE(PG8_SA(0, 1), a2 + hstep, voffA);
;             PG8_WAIT_V(8); PG8_WAIT_L(0); PG8_BAR; PG8_MMA(0, 0, At, B0); PG8_MMA(0, 1, At, B1); PG8_BAR; PG8_SCHED;
	s_setprio 1
	s_waitcnt lgkmcnt(0)
	v_mfma_f32_16x16x32_bf16 v[60:63], v[138:141], v[200:203], 0
	v_mfma_f32_16x16x32_bf16 v[56:59], v[146:149], v[200:203], 0
	v_mfma_f32_16x16x32_bf16 v[44:47], v[138:141], v[218:221], 0
	v_mfma_f32_16x16x32_bf16 v[40:43], v[146:149], v[218:221], 0
	v_mfma_f32_16x16x32_bf16 v[28:31], v[138:141], v[226:229], 0
	v_mfma_f32_16x16x32_bf16 v[24:27], v[146:149], v[226:229], 0
	v_mfma_f32_16x16x32_bf16 v[12:15], v[138:141], v[234:237], 0
	v_mfma_f32_16x16x32_bf16 v[8:11], v[146:149], v[234:237], 0
	v_mfma_f32_16x16x32_bf16 v[60:63], v[142:145], v[214:217], v[60:63]
	v_mfma_f32_16x16x32_bf16 v[56:59], v[154:157], v[214:217], v[56:59]
	v_mfma_f32_16x16x32_bf16 v[44:47], v[142:145], v[222:225], v[44:47]
	v_mfma_f32_16x16x32_bf16 v[40:43], v[154:157], v[222:225], v[40:43]
	v_mfma_f32_16x16x32_bf16 v[28:31], v[142:145], v[230:233], v[28:31]
	v_mfma_f32_16x16x32_bf16 v[24:27], v[154:157], v[230:233], v[24:27]
	v_mfma_f32_16x16x32_bf16 v[12:15], v[142:145], v[238:241], v[12:15]
	v_mfma_f32_16x16x32_bf16 v[8:11], v[154:157], v[238:241], v[8:11]
	s_setprio 0
	s_setprio 1
	v_mfma_f32_16x16x32_bf16 v[52:55], v[184:187], v[200:203], 0
	v_mfma_f32_16x16x32_bf16 v[48:51], v[192:195], v[200:203], 0
	v_mfma_f32_16x16x32_bf16 v[36:39], v[184:187], v[218:221], 0
	v_mfma_f32_16x16x32_bf16 v[32:35], v[192:195], v[218:221], 0
	v_mfma_f32_16x16x32_bf16 v[20:23], v[184:187], v[226:229], 0
	v_mfma_f32_16x16x32_bf16 v[16:19], v[192:195], v[226:229], 0
	v_mfma_f32_16x16x32_bf16 v[4:7], v[184:187], v[234:237], 0
	v_mfma_f32_16x16x32_bf16 v[0:3], v[192:195], v[234:237], 0
	v_mfma_f32_16x16x32_bf16 v[52:55], v[188:191], v[214:217], v[52:55]
	v_mfma_f32_16x16x32_bf16 v[48:51], v[196:199], v[214:217], v[48:51]
	v_mfma_f32_16x16x32_bf16 v[36:39], v[188:191], v[222:225], v[36:39]
	v_mfma_f32_16x16x32_bf16 v[32:35], v[196:199], v[222:225], v[32:35]
	v_mfma_f32_16x16x32_bf16 v[20:23], v[188:191], v[230:233], v[20:23]
	v_mfma_f32_16x16x32_bf16 v[16:19], v[196:199], v[230:233], v[16:19]
	v_mfma_f32_16x16x32_bf16 v[4:7], v[188:191], v[238:241], v[4:7]
	v_mfma_f32_16x16x32_bf16 v[0:3], v[196:199], v[238:241], v[0:3]
	s_setprio 0
	s_barrier
	s_add_i32 s29, 0, 0x18000
	s_add_i32 s47, 0, 0x1c000
	v_add_u32_e32 v154, s29, v151
	v_add_u32_e32 v196, s47, v151
	ds_read_b128 v[138:141], v154
	ds_read_b128 v[142:145], v154 offset:1024
	ds_read_b128 v[146:149], v154 offset:2048
	ds_read_b128 v[154:157], v154 offset:3072
	ds_read_b128 v[184:187], v196
	ds_read_b128 v[188:191], v196 offset:1024
	ds_read_b128 v[192:195], v196 offset:2048
	ds_read_b128 v[196:199], v196 offset:3072
	s_add_u32 s34, s60, 0x80000
	s_addc_u32 s35, s61, 0
	s_mov_b32 m0, s74
	v_lshl_add_u64 v[246:247], s[34:35], 0, v[128:129]
	ds_read_b128 v[200:203], v153 offset:32768
	ds_read_b128 v[214:217], v153 offset:33792
	ds_read_b128 v[218:221], v153 offset:34816
	ds_read_b128 v[222:225], v153 offset:35840
	ds_read_b128 v[226:229], v153 offset:36864
	ds_read_b128 v[230:233], v153 offset:37888
	ds_read_b128 v[234:237], v153 offset:38912
	ds_read_b128 v[238:241], v153 offset:39936
	global_load_lds_dwordx4 v[246:247], off
	v_lshl_add_u64 v[246:247], s[34:35], 0, v[130:131]
	s_mov_b32 m0, s75
	s_nop 0
	global_load_lds_dwordx4 v[246:247], off
	s_waitcnt vmcnt(8)
	s_waitcnt lgkmcnt(0)
	s_barrier
	s_setprio 1
	s_waitcnt lgkmcnt(0)
	v_mfma_f32_16x16x32_bf16 v[124:127], v[138:141], v[200:203], v[124:127]
	v_mfma_f32_16x16x32_bf16 v[120:123], v[146:149], v[200:203], v[120:123]
	v_mfma_f32_16x16x32_bf16 v[108:111], v[138:141], v[218:221], v[108:111]
	v_mfma_f32_16x16x32_bf16 v[104:107], v[146:149], v[218:221], v[104:107]
	v_mfma_f32_16x16x32_bf16 v[92:95], v[138:141], v[226:229], v[92:95]
	v_mfma_f32_16x16x32_bf16 v[88:91], v[146:149], v[226:229], v[88:91]
	v_mfma_f32_16x16x32_bf16 v[76:79], v[138:141], v[234:237], v[76:79]
	v_mfma_f32_16x16x32_bf16 v[72:75], v[146:149], v[234:237], v[72:75]
	v_mfma_f32_16x16x32_bf16 v[124:127], v[142:145], v[214:217], v[124:127]
	v_mfma_f32_16x16x32_bf16 v[120:123], v[154:157], v[214:217], v[120:123]
	v_mfma_f32_16x16x32_bf16 v[108:111], v[142:145], v[222:225], v[108:111]
	v_mfma_f32_16x16x32_bf16 v[104:107], v[154:157], v[222:225], v[104:107]
	v_mfma_f32_16x16x32_bf16 v[92:95], v[142:145], v[230:233], v[92:95]
	v_mfma_f32_16x16x32_bf16 v[88:91], v[154:157], v[230:233], v[88:91]
	v_mfma_f32_16x16x32_bf16 v[76:79], v[142:145], v[238:241], v[76:79]
	v_mfma_f32_16x16x32_bf16 v[72:75], v[154:157], v[238:241], v[72:75]
	s_setprio 0
	s_setprio 1
	v_mfma_f32_16x16x32_bf16 v[116:119], v[184:187], v[200:203], v[116:119]
	v_mfma_f32_16x16x32_bf16 v[112:115], v[192:195], v[200:203], v[112:115]
	v_mfma_f32_16x16x32_bf16 v[100:103], v[184:187], v[218:221], v[100:103]
	v_mfma_f32_16x16x32_bf16 v[96:99], v[192:195], v[218:221], v[96:99]
	v_mfma_f32_16x16x32_bf16 v[84:87], v[184:187], v[226:229], v[84:87]
	v_mfma_f32_16x16x32_bf16 v[80:83], v[192:195], v[226:229], v[80:83]
	v_mfma_f32_16x16x32_bf16 v[68:71], v[184:187], v[234:237], v[68:71]
	v_mfma_f32_16x16x32_bf16 v[64:67], v[192:195], v[234:237], v[64:67]
	v_mfma_f32_16x16x32_bf16 v[116:119], v[188:191], v[214:217], v[116:119]
	v_mfma_f32_16x16x32_bf16 v[112:115], v[196:199], v[214:217], v[112:115]
	v_mfma_f32_16x16x32_bf16 v[100:103], v[188:191], v[222:225], v[100:103]
	v_mfma_f32_16x16x32_bf16 v[96:99], v[196:199], v[222:225], v[96:99]
	v_mfma_f32_16x16x32_bf16 v[84:87], v[188:191], v[230:233], v[84:87]
	v_mfma_f32_16x16x32_bf16 v[80:83], v[196:199], v[230:233], v[80:83]
	v_mfma_f32_16x16x32_bf16 v[68:71], v[188:191], v[238:241], v[68:71]
	v_mfma_f32_16x16x32_bf16 v[64:67], v[196:199], v[238:241], v[64:67]
	s_setprio 0
	s_barrier
; #define PG8_STAGE(bufoff, gbase, voff) do { _Pragma("unroll") for (int _i = 0; _i < 2; ++_i) \
;         __builtin_amdgcn_global_load_lds((const unsigned*)((const char*)(gbase) + (voff)[_i]), (PG8_LAS unsigned*)(lds + (bufoff) + ldsw + _i * 8192), 16, 0, 0); } while (0)
; #define PG8_WAIT_V(n) asm volatile("s_waitcnt vmcnt(" #n ")" ::: "memory")
; #define PG8_WAIT_L(n) asm volatile("s_waitcnt lgkmcnt(" #n ")" ::: "memory")
; #define PG8_BAR __builtin_amdgcn_s_barrier()
; #define PG8_SCHED __builtin_amdgcn_sched_barrier(0)
; template <class Epi, class Sched, bool ALIGN_EPI = false, bool SP2 = false, bool F8 = false>
; __device__ __forceinline__ void gemm_phase(PG8_LAS unsigned char* lds, const Gemm g, const Sched& S, const Epi& E) {
;     ...
;             PG8_LDA(At, 1, 1); PG8_STAGE(PG8_SB(1, 0), b3, voffB); PG8_STAGE(PG8_SB(1, 1), b3 + hstep, voffB); PG8_STAGE(PG8_SA(1, 0), a3, voffA);
;             PG8_WAIT_V(8); PG8_WAIT_L(0); PG8_BAR; PG8_MMA(1, 0, At, B0); PG8_MMA(1, 1, At, B1); PG8_BAR; PG8_SCHED;
	s_add_i32 s29, s29, s64
	v_lshl_add_u64 v[158:159], v[158:159], 0, s[14:15]
	s_mov_b32 m0, s29
	ds_read_b128 v[200:203], v153 offset:49152
	ds_read_b128 v[214:217], v153 offset:50176
	ds_read_b128 v[218:221], v153 offset:51200
	ds_read_b128 v[222:225], v153 offset:52224
	ds_read_b128 v[226:229], v153 offset:53248
	ds_read_b128 v[230:233], v153 offset:54272
	ds_read_b128 v[234:237], v153 offset:55296
	ds_read_b128 v[238:241], v153 offset:56320
	global_load_lds_dwordx4 v[158:159], off
	s_add_i32 m0, s29, 0x2000
	s_add_u32 s34, s58, 0x80080
	v_lshl_add_u64 v[158:159], v[162:163], 0, s[14:15]
	s_addc_u32 s35, s59, 0
	s_add_i32 s29, s47, s64
	global_load_lds_dwordx4 v[158:159], off
	v_lshl_add_u64 v[158:159], s[34:35], 0, v[160:161]
	s_mov_b32 m0, s29
	s_nop 0
	global_load_lds_dwordx4 v[158:159], off
	v_lshl_add_u64 v[158:159], s[34:35], 0, v[132:133]
	s_add_i32 m0, s29, 0x2000
	s_nop 0
	global_load_lds_dwordx4 v[158:159], off
	v_lshl_add_u64 v[158:159], v[242:243], 0, s[14:15]
	s_mov_b32 m0, s52
	s_nop 0
	global_load_lds_dwordx4 v[158:159], off
	v_lshl_add_u64 v[158:159], v[244:245], 0, s[14:15]
	s_mov_b32 m0, s53
	s_nop 0
	global_load_lds_dwordx4 v[158:159], off
	s_waitcnt vmcnt(8)
	s_waitcnt lgkmcnt(0)
	s_barrier
	s_setprio 1
	s_waitcnt lgkmcnt(0)
	v_mfma_f32_16x16x32_bf16 v[60:63], v[138:141], v[200:203], v[60:63]
	v_mfma_f32_16x16x32_bf16 v[56:59], v[146:149], v[200:203], v[56:59]
	v_mfma_f32_16x16x32_bf16 v[44:47], v[138:141], v[218:221], v[44:47]
	v_mfma_f32_16x16x32_bf16 v[40:43], v[146:149], v[218:221], v[40:43]
	v_mfma_f32_16x16x32_bf16 v[28:31], v[138:141], v[226:229], v[28:31]
	v_mfma_f32_16x16x32_bf16 v[24:27], v[146:149], v[226:229], v[24:27]
	v_mfma_f32_16x16x32_bf16 v[12:15], v[138:141], v[234:237], v[12:15]
	v_mfma_f32_16x16x32_bf16 v[8:11], v[146:149], v[234:237], v[8:11]
	v_mfma_f32_16x16x32_bf16 v[60:63], v[142:145], v[214:217], v[60:63]
	v_mfma_f32_16x16x32_bf16 v[56:59], v[154:157], v[214:217], v[56:59]
	v_mfma_f32_16x16x32_bf16 v[44:47], v[142:145], v[222:225], v[44:47]
	v_mfma_f32_16x16x32_bf16 v[40:43], v[154:157], v[222:225], v[40:43]
	v_mfma_f32_16x16x32_bf16 v[28:31], v[142:145], v[230:233], v[28:31]
	v_mfma_f32_16x16x32_bf16 v[24:27], v[154:157], v[230:233], v[24:27]
	v_mfma_f32_16x16x32_bf16 v[12:15], v[142:145], v[238:241], v[12:15]
	v_mfma_f32_16x16x32_bf16 v[8:11], v[154:157], v[238:241], v[8:11]
	s_setprio 0
	s_setprio 1
	v_mfma_f32_16x16x32_bf16 v[52:55], v[184:187], v[200:203], v[52:55]
	v_mfma_f32_16x16x32_bf16 v[48:51], v[192:195], v[200:203], v[48:51]
	v_mfma_f32_16x16x32_bf16 v[36:39], v[184:187], v[218:221], v[36:39]
	v_mfma_f32_16x16x32_bf16 v[32:35], v[192:195], v[218:221], v[32:35]
	v_mfma_f32_16x16x32_bf16 v[20:23], v[184:187], v[226:229], v[20:23]
	v_mfma_f32_16x16x32_bf16 v[16:19], v[192:195], v[226:229], v[16:19]
	v_mfma_f32_16x16x32_bf16 v[4:7], v[184:187], v[234:237], v[4:7]
	v_mfma_f32_16x16x32_bf16 v[0:3], v[192:195], v[234:237], v[0:3]
	v_mfma_f32_16x16x32_bf16 v[52:55], v[188:191], v[214:217], v[52:55]
	v_mfma_f32_16x16x32_bf16 v[48:51], v[196:199], v[214:217], v[48:51]
	v_mfma_f32_16x16x32_bf16 v[36:39], v[188:191], v[222:225], v[36:39]
	v_mfma_f32_16x16x32_bf16 v[32:35], v[196:199], v[222:225], v[32:35]
	v_mfma_f32_16x16x32_bf16 v[20:23], v[188:191], v[230:233], v[20:23]
	v_mfma_f32_16x16x32_bf16 v[16:19], v[196:199], v[230:233], v[16:19]
	v_mfma_f32_16x16x32_bf16 v[4:7], v[188:191], v[238:241], v[4:7]
	v_mfma_f32_16x16x32_bf16 v[0:3], v[196:199], v[238:241], v[0:3]
	s_setprio 0
	s_barrier
	s_add_i32 s28, s28, 2
	s_add_u32 s36, s36, 0x100
	s_addc_u32 s37, s37, 0
	s_add_u32 s19, s19, 0x100
	s_addc_u32 s23, s23, 0
	s_cmp_gt_u32 s28, 29
	s_cbranch_scc0 .LBB0_59
	s_branch .Lgk_after_59

; #define PG8_BAR __builtin_amdgcn_s_barrier()
; template <class Epi, class Sched, bool ALIGN_EPI = false, bool SP2 = false, bool F8 = false>
; __device__ __forceinline__ void gemm_phase(PG8_LAS unsigned char* lds, const Gemm g, const Sched& S, const Epi& E) {
;     ...
;         if constexpr (ALIGN_EPI) { if (wr == 0) PG8_BAR; }
.Lgk_after_59:
	s_and_b64 vcc, exec, s[44:45]
	s_cbranch_vccz .LBB0_62
	s_barrier

; #define PG8_STAGE(bufoff, gbase, voff) do { _Pragma("unroll") for (int _i = 0; _i < 2; ++_i) \
;         __builtin_amdgcn_global_load_lds((const unsigned*)((const char*)(gbase) + (voff)[_i]), (PG8_LAS unsigned*)(lds + (bufoff) + ldsw + _i * 8192), 16, 0, 0); } while (0)
; #define PG8_WAIT_V(n) asm volatile("s_waitcnt vmcnt(" #n ")" ::: "memory")
; #define PG8_WAIT_L(n) asm volatile("s_waitcnt lgkmcnt(" #n ")" ::: "memory")
; #define PG8_BAR __builtin_amdgcn_s_barrier()
; #define PG8_SCHED __builtin_amdgcn_sched_barrier(0)
; template <class Epi, class Sched, bool ALIGN_EPI = false, bool SP2 = false, bool F8 = false>
; __device__ __forceinline__ void gemm_phase(PG8_LAS unsigned char* lds, const Gemm g, const Sched& S, const Epi& E) {
;     ...
;         const bool has_next = S.next(ui + 1, nxt);
;         const char* nA = has_next ? (const char*)g.A + (size_t)nxt.pm * tstep : cA; const char* nB = has_next ? (const char*)g.Bt + (size_t)nxt.pn * tstep : cB;
;         for (int t = 0; t < nt; t += 2) {
;             const bool last = (t == nt - 2);
;             const char* a1 = cA + (size_t)(t + 1) * kstep;
;             const char* a2 = last ? nA : cA + (size_t)(t + 2) * kstep; const char* b2 = last ? nB : cB + (size_t)(t + 2) * kstep;
;             const char* a3 = a2 + kstep; const char* b3 = b2 + kstep;
;             if (last && has_next) S.a_ready(nxt);
;             if constexpr (SP2) {
;             PG8_LDB(B0, 0, 0); PG8_LDB(B1, 0, 1); PG8_SCHED; PG8_LDA(At, 0, 0); PG8_STAGE(PG8_SA(1, 1), a1 + hstep, voffA);
;             PG8_WAIT_V(8); PG8_WAIT_L(0); PG8_BAR; PG8_MMA(0, 0, At, B0); PG8_MMA(0, 1, At, B1); PG8_BAR; PG8_SCHED;
;             PG8_LDA(At, 0, 1); PG8_STAGE(PG8_SB(0, 0), b2, voffB); PG8_STAGE(PG8_SB(0, 1), b2 + hstep, voffB); PG8_STAGE(PG8_SA(0, 0), a2, voffA);
;             PG8_WAIT_V(8); PG8_WAIT_L(0); PG8_BAR; PG8_MMA(1, 0, At, B0); PG8_MMA(1, 1, At, B1); PG8_BAR; PG8_SCHED;
.LBB0_96:
	s_ashr_i32 s17, s16, 31
	s_lshl_b64 s[28:29], s[16:17], 18
	s_add_u32 s36, s62, s28
	s_addc_u32 s37, s63, s29
	s_and_b64 s[28:29], s[38:39], exec
	s_cselect_b32 s17, s37, s43
	s_cselect_b32 s19, s36, s42
	s_ashr_i32 s11, s10, 31
	s_lshl_b64 s[28:29], s[10:11], 18
	s_add_u32 s40, s13, s28
	s_addc_u32 s41, s22, s29
	s_and_b64 s[28:29], s[38:39], exec
	s_cselect_b32 s11, s41, s45
	s_cselect_b32 s23, s40, s44
	s_add_u32 s42, s42, 0x20080
	s_addc_u32 s43, s43, 0
	s_add_u32 s28, s44, 0x100
	s_addc_u32 s29, s45, 0
	s_mov_b32 s54, -2
	s_add_u32 s44, s42, 0xfffe0080
	s_addc_u32 s45, s43, -1
	s_add_i32 s55, 0, 0x10000
	s_cmp_eq_u32 s54, 4
	s_cselect_b32 s47, s17, s45
	s_cselect_b32 s46, s19, s44
	s_cselect_b32 s45, s11, s29
	s_cselect_b32 s44, s23, s28
	s_add_i32 s56, 0, 0x14000
	v_add_u32_e32 v154, s55, v143
	v_add_u32_e32 v158, s56, v143
	ds_read_b128 v[138:141], v154
	ds_read_b128 v[146:149], v154 offset:1024
	ds_read_b128 v[150:153], v154 offset:2048
	ds_read_b128 v[154:157], v154 offset:3072
	ds_read_b128 v[184:187], v158
	ds_read_b128 v[188:191], v158 offset:1024
	ds_read_b128 v[192:195], v158 offset:2048
	ds_read_b128 v[196:199], v158 offset:3072
	v_lshl_add_u64 v[158:159], s[42:43], 0, v[134:135]
	s_add_i32 m0, s35, 0xc000
	ds_read_b128 v[200:203], v145
	ds_read_b128 v[214:217], v145 offset:1024
	ds_read_b128 v[218:221], v145 offset:2048
	ds_read_b128 v[222:225], v145 offset:3072
	ds_read_b128 v[226:229], v145 offset:4096
	ds_read_b128 v[230:233], v145 offset:5120
	ds_read_b128 v[234:237], v145 offset:6144
	ds_read_b128 v[238:241], v145 offset:7168
	global_load_lds_dwordx4 v[158:159], off
	v_lshl_add_u64 v[158:159], s[42:43], 0, v[136:137]
	s_add_i32 m0, s35, 0xe000
	s_nop 0
	global_load_lds_dwordx4 v[158:159], off
	s_waitcnt vmcnt(8)
	s_waitcnt lgkmcnt(0)
	s_barrier
	s_setprio 1
	s_waitcnt lgkmcnt(0)
	v_mfma_f32_16x16x32_bf16 v[124:127], v[138:141], v[200:203], 0
	v_mfma_f32_16x16x32_bf16 v[120:123], v[150:153], v[200:203], 0
	v_mfma_f32_16x16x32_bf16 v[108:111], v[138:141], v[218:221], 0
	v_mfma_f32_16x16x32_bf16 v[104:107], v[150:153], v[218:221], 0
	v_mfma_f32_16x16x32_bf16 v[92:95], v[138:141], v[226:229], 0
	v_mfma_f32_16x16x32_bf16 v[88:91], v[150:153], v[226:229], 0
	v_mfma_f32_16x16x32_bf16 v[76:79], v[138:141], v[234:237], 0
	v_mfma_f32_16x16x32_bf16 v[72:75], v[150:153], v[234:237], 0
	v_mfma_f32_16x16x32_bf16 v[124:127], v[146:149], v[214:217], v[124:127]
	v_mfma_f32_16x16x32_bf16 v[120:123], v[154:157], v[214:217], v[120:123]
	v_mfma_f32_16x16x32_bf16 v[108:111], v[146:149], v[222:225], v[108:111]
	v_mfma_f32_16x16x32_bf16 v[104:107], v[154:157], v[222:225], v[104:107]
	v_mfma_f32_16x16x32_bf16 v[92:95], v[146:149], v[230:233], v[92:95]
	v_mfma_f32_16x16x32_bf16 v[88:91], v[154:157], v[230:233], v[88:91]
	v_mfma_f32_16x16x32_bf16 v[76:79], v[146:149], v[238:241], v[76:79]
	v_mfma_f32_16x16x32_bf16 v[72:75], v[154:157], v[238:241], v[72:75]
	s_setprio 0
	s_setprio 1
	v_mfma_f32_16x16x32_bf16 v[116:119], v[184:187], v[200:203], 0
	v_mfma_f32_16x16x32_bf16 v[112:115], v[192:195], v[200:203], 0
	v_mfma_f32_16x16x32_bf16 v[100:103], v[184:187], v[218:221], 0
	v_mfma_f32_16x16x32_bf16 v[96:99], v[192:195], v[218:221], 0
	v_mfma_f32_16x16x32_bf16 v[84:87], v[184:187], v[226:229], 0
	v_mfma_f32_16x16x32_bf16 v[80:83], v[192:195], v[226:229], 0
	v_mfma_f32_16x16x32_bf16 v[68:71], v[184:187], v[234:237], 0
	v_mfma_f32_16x16x32_bf16 v[64:67], v[192:195], v[234:237], 0
	v_mfma_f32_16x16x32_bf16 v[116:119], v[188:191], v[214:217], v[116:119]
	v_mfma_f32_16x16x32_bf16 v[112:115], v[196:199], v[214:217], v[112:115]
	v_mfma_f32_16x16x32_bf16 v[100:103], v[188:191], v[222:225], v[100:103]
	v_mfma_f32_16x16x32_bf16 v[96:99], v[196:199], v[222:225], v[96:99]
	v_mfma_f32_16x16x32_bf16 v[84:87], v[188:191], v[230:233], v[84:87]
	v_mfma_f32_16x16x32_bf16 v[80:83], v[196:199], v[230:233], v[80:83]
	v_mfma_f32_16x16x32_bf16 v[68:71], v[188:191], v[238:241], v[68:71]
	v_mfma_f32_16x16x32_bf16 v[64:67], v[196:199], v[238:241], v[64:67]
	s_setprio 0
	s_barrier
	s_add_i32 s55, s55, s34
	v_lshl_add_u64 v[158:159], s[44:45], 0, v[160:161]
	s_mov_b32 m0, s55
	ds_read_b128 v[200:203], v145 offset:16384
	ds_read_b128 v[214:217], v145 offset:17408
	ds_read_b128 v[218:221], v145 offset:18432
	ds_read_b128 v[222:225], v145 offset:19456
	ds_read_b128 v[226:229], v145 offset:20480
	ds_read_b128 v[230:233], v145 offset:21504
	ds_read_b128 v[234:237], v145 offset:22528
	ds_read_b128 v[238:241], v145 offset:23552
	global_load_lds_dwordx4 v[158:159], off
	s_add_i32 m0, s55, 0x2000
	s_add_u32 s58, s44, 0x20000
	v_lshl_add_u64 v[162:163], s[44:45], 0, v[128:129]
	s_addc_u32 s59, s45, 0
	s_add_i32 s55, s56, s34
	global_load_lds_dwordx4 v[162:163], off
	v_lshl_add_u64 v[242:243], s[58:59], 0, v[160:161]
	s_mov_b32 m0, s55
	v_lshl_add_u64 v[244:245], s[46:47], 0, v[130:131]
	global_load_lds_dwordx4 v[242:243], off
	v_lshl_add_u64 v[242:243], s[58:59], 0, v[128:129]
	s_add_i32 m0, s55, 0x2000
	s_nop 0
	global_load_lds_dwordx4 v[242:243], off
	v_lshl_add_u64 v[242:243], s[46:47], 0, v[132:133]
	s_mov_b32 m0, s35
	s_nop 0
	global_load_lds_dwordx4 v[242:243], off
	s_mov_b32 m0, s48
	s_nop 0
	global_load_lds_dwordx4 v[244:245], off
	s_waitcnt vmcnt(8)
	s_waitcnt lgkmcnt(0)
	s_barrier
; #define PG8_STAGE(bufoff, gbase, voff) do { _Pragma("unroll") for (int _i = 0; _i < 2; ++_i) \
;         __builtin_amdgcn_global_load_lds((const unsigned*)((const char*)(gbase) + (voff)[_i]), (PG8_LAS unsigned*)(lds + (bufoff) + ldsw + _i * 8192), 16, 0, 0); } while (0)
; #define PG8_WAIT_V(n) asm volatile("s_waitcnt vmcnt(" #n ")" ::: "memory")
; #define PG8_WAIT_L(n) asm volatile("s_waitcnt lgkmcnt(" #n ")" ::: "memory")
; #define PG8_BAR __builtin_amdgcn_s_barrier()
; #define PG8_SCHED __builtin_amdgcn_sched_barrier(0)
; template <class Epi, class Sched, bool ALIGN_EPI = false, bool SP2 = false, bool F8 = false>
; __device__ __forceinline__ void gemm_phase(PG8_LAS unsigned char* lds, const Gemm g, const Sched& S, const Epi& E) {
;     ...
;             PG8_WAIT_V(8); PG8_WAIT_L(0); PG8_BAR; PG8_MMA(1, 0, At, B0); PG8_MMA(1, 1, At, B1); PG8_BAR; PG8_SCHED;
;             PG8_LDB(B0, 1, 0); PG8_LDB(B1, 1, 1); PG8_SCHED; PG8_LDA(At, 1, 0); PG8_STAGE(PG8_SA(0, 1), a2 + hstep, voffA);
;             PG8_WAIT_V(8); PG8_WAIT_L(0); PG8_BAR; PG8_MMA(0, 0, At, B0); PG8_MMA(0, 1, At, B1); PG8_BAR; PG8_SCHED;
	s_setprio 1
	s_waitcnt lgkmcnt(0)
	v_mfma_f32_16x16x32_bf16 v[60:63], v[138:141], v[200:203], 0
	v_mfma_f32_16x16x32_bf16 v[56:59], v[150:153], v[200:203], 0
	v_mfma_f32_16x16x32_bf16 v[44:47], v[138:141], v[218:221], 0
	v_mfma_f32_16x16x32_bf16 v[40:43], v[150:153], v[218:221], 0
	v_mfma_f32_16x16x32_bf16 v[28:31], v[138:141], v[226:229], 0
	v_mfma_f32_16x16x32_bf16 v[24:27], v[150:153], v[226:229], 0
	v_mfma_f32_16x16x32_bf16 v[12:15], v[138:141], v[234:237], 0
	v_mfma_f32_16x16x32_bf16 v[8:11], v[150:153], v[234:237], 0
	v_mfma_f32_16x16x32_bf16 v[60:63], v[146:149], v[214:217], v[60:63]
	v_mfma_f32_16x16x32_bf16 v[56:59], v[154:157], v[214:217], v[56:59]
	v_mfma_f32_16x16x32_bf16 v[44:47], v[146:149], v[222:225], v[44:47]
	v_mfma_f32_16x16x32_bf16 v[40:43], v[154:157], v[222:225], v[40:43]
	v_mfma_f32_16x16x32_bf16 v[28:31], v[146:149], v[230:233], v[28:31]
	v_mfma_f32_16x16x32_bf16 v[24:27], v[154:157], v[230:233], v[24:27]
	v_mfma_f32_16x16x32_bf16 v[12:15], v[146:149], v[238:241], v[12:15]
	v_mfma_f32_16x16x32_bf16 v[8:11], v[154:157], v[238:241], v[8:11]
	s_setprio 0
	s_setprio 1
	v_mfma_f32_16x16x32_bf16 v[52:55], v[184:187], v[200:203], 0
	v_mfma_f32_16x16x32_bf16 v[48:51], v[192:195], v[200:203], 0
	v_mfma_f32_16x16x32_bf16 v[36:39], v[184:187], v[218:221], 0
	v_mfma_f32_16x16x32_bf16 v[32:35], v[192:195], v[218:221], 0
	v_mfma_f32_16x16x32_bf16 v[20:23], v[184:187], v[226:229], 0
	v_mfma_f32_16x16x32_bf16 v[16:19], v[192:195], v[226:229], 0
	v_mfma_f32_16x16x32_bf16 v[4:7], v[184:187], v[234:237], 0
	v_mfma_f32_16x16x32_bf16 v[0:3], v[192:195], v[234:237], 0
	v_mfma_f32_16x16x32_bf16 v[52:55], v[188:191], v[214:217], v[52:55]
	v_mfma_f32_16x16x32_bf16 v[48:51], v[196:199], v[214:217], v[48:51]
	v_mfma_f32_16x16x32_bf16 v[36:39], v[188:191], v[222:225], v[36:39]
	v_mfma_f32_16x16x32_bf16 v[32:35], v[196:199], v[222:225], v[32:35]
	v_mfma_f32_16x16x32_bf16 v[20:23], v[188:191], v[230:233], v[20:23]
	v_mfma_f32_16x16x32_bf16 v[16:19], v[196:199], v[230:233], v[16:19]
	v_mfma_f32_16x16x32_bf16 v[4:7], v[188:191], v[238:241], v[4:7]
	v_mfma_f32_16x16x32_bf16 v[0:3], v[196:199], v[238:241], v[0:3]
	s_setprio 0
	s_barrier
	s_add_i32 s55, 0, 0x18000
	s_add_i32 s56, 0, 0x1c000
	v_add_u32_e32 v154, s55, v143
	v_add_u32_e32 v196, s56, v143
	ds_read_b128 v[138:141], v154
	ds_read_b128 v[146:149], v154 offset:1024
	ds_read_b128 v[150:153], v154 offset:2048
	ds_read_b128 v[154:157], v154 offset:3072
	ds_read_b128 v[184:187], v196
	ds_read_b128 v[188:191], v196 offset:1024
	ds_read_b128 v[192:195], v196 offset:2048
	ds_read_b128 v[196:199], v196 offset:3072
	s_add_u32 s46, s46, 0x20000
	s_addc_u32 s47, s47, 0
	s_mov_b32 m0, s49
	v_lshl_add_u64 v[246:247], s[46:47], 0, v[132:133]
	ds_read_b128 v[200:203], v145 offset:32768
	ds_read_b128 v[214:217], v145 offset:33792
	ds_read_b128 v[218:221], v145 offset:34816
	ds_read_b128 v[222:225], v145 offset:35840
	ds_read_b128 v[226:229], v145 offset:36864
	ds_read_b128 v[230:233], v145 offset:37888
	ds_read_b128 v[234:237], v145 offset:38912
	ds_read_b128 v[238:241], v145 offset:39936
	global_load_lds_dwordx4 v[246:247], off
	v_lshl_add_u64 v[246:247], s[46:47], 0, v[130:131]
	s_mov_b32 m0, s50
	s_nop 0
	global_load_lds_dwordx4 v[246:247], off
	s_waitcnt vmcnt(8)
	s_waitcnt lgkmcnt(0)
	s_barrier
	s_setprio 1
	s_waitcnt lgkmcnt(0)
	v_mfma_f32_16x16x32_bf16 v[124:127], v[138:141], v[200:203], v[124:127]
	v_mfma_f32_16x16x32_bf16 v[120:123], v[150:153], v[200:203], v[120:123]
	v_mfma_f32_16x16x32_bf16 v[108:111], v[138:141], v[218:221], v[108:111]
	v_mfma_f32_16x16x32_bf16 v[104:107], v[150:153], v[218:221], v[104:107]
	v_mfma_f32_16x16x32_bf16 v[92:95], v[138:141], v[226:229], v[92:95]
	v_mfma_f32_16x16x32_bf16 v[88:91], v[150:153], v[226:229], v[88:91]
	v_mfma_f32_16x16x32_bf16 v[76:79], v[138:141], v[234:237], v[76:79]
	v_mfma_f32_16x16x32_bf16 v[72:75], v[150:153], v[234:237], v[72:75]
	v_mfma_f32_16x16x32_bf16 v[124:127], v[146:149], v[214:217], v[124:127]
	v_mfma_f32_16x16x32_bf16 v[120:123], v[154:157], v[214:217], v[120:123]
	v_mfma_f32_16x16x32_bf16 v[108:111], v[146:149], v[222:225], v[108:111]
	v_mfma_f32_16x16x32_bf16 v[104:107], v[154:157], v[222:225], v[104:107]
	v_mfma_f32_16x16x32_bf16 v[92:95], v[146:149], v[230:233], v[92:95]
	v_mfma_f32_16x16x32_bf16 v[88:91], v[154:157], v[230:233], v[88:91]
	v_mfma_f32_16x16x32_bf16 v[76:79], v[146:149], v[238:241], v[76:79]
	v_mfma_f32_16x16x32_bf16 v[72:75], v[154:157], v[238:241], v[72:75]
	s_setprio 0
	s_setprio 1
	v_mfma_f32_16x16x32_bf16 v[116:119], v[184:187], v[200:203], v[116:119]
	v_mfma_f32_16x16x32_bf16 v[112:115], v[192:195], v[200:203], v[112:115]
	v_mfma_f32_16x16x32_bf16 v[100:103], v[184:187], v[218:221], v[100:103]
	v_mfma_f32_16x16x32_bf16 v[96:99], v[192:195], v[218:221], v[96:99]
	v_mfma_f32_16x16x32_bf16 v[84:87], v[184:187], v[226:229], v[84:87]
	v_mfma_f32_16x16x32_bf16 v[80:83], v[192:195], v[226:229], v[80:83]
	v_mfma_f32_16x16x32_bf16 v[68:71], v[184:187], v[234:237], v[68:71]
	v_mfma_f32_16x16x32_bf16 v[64:67], v[192:195], v[234:237], v[64:67]
	v_mfma_f32_16x16x32_bf16 v[116:119], v[188:191], v[214:217], v[116:119]
	v_mfma_f32_16x16x32_bf16 v[112:115], v[196:199], v[214:217], v[112:115]
	v_mfma_f32_16x16x32_bf16 v[100:103], v[188:191], v[222:225], v[100:103]
	v_mfma_f32_16x16x32_bf16 v[96:99], v[196:199], v[222:225], v[96:99]
	v_mfma_f32_16x16x32_bf16 v[84:87], v[188:191], v[230:233], v[84:87]
	v_mfma_f32_16x16x32_bf16 v[80:83], v[196:199], v[230:233], v[80:83]
	v_mfma_f32_16x16x32_bf16 v[68:71], v[188:191], v[238:241], v[68:71]
	v_mfma_f32_16x16x32_bf16 v[64:67], v[196:199], v[238:241], v[64:67]
	s_setprio 0
	s_barrier
; #define PG8_STAGE(bufoff, gbase, voff) do { _Pragma("unroll") for (int _i = 0; _i < 2; ++_i) \
;         __builtin_amdgcn_global_load_lds((const unsigned*)((const char*)(gbase) + (voff)[_i]), (PG8_LAS unsigned*)(lds + (bufoff) + ldsw + _i * 8192), 16, 0, 0); } while (0)
; #define PG8_WAIT_V(n) asm volatile("s_waitcnt vmcnt(" #n ")" ::: "memory")
; #define PG8_WAIT_L(n) asm volatile("s_waitcnt lgkmcnt(" #n ")" ::: "memory")
; #define PG8_BAR __builtin_amdgcn_s_barrier()
; #define PG8_SCHED __builtin_amdgcn_sched_barrier(0)
; template <class Epi, class Sched, bool ALIGN_EPI = false, bool SP2 = false, bool F8 = false>
; __device__ __forceinline__ void gemm_phase(PG8_LAS unsigned char* lds, const Gemm g, const Sched& S, const Epi& E) {
;     ...
;             PG8_LDA(At, 1, 1); PG8_STAGE(PG8_SB(1, 0), b3, voffB); PG8_STAGE(PG8_SB(1, 1), b3 + hstep, voffB); PG8_STAGE(PG8_SA(1, 0), a3, voffA);
;             PG8_WAIT_V(8); PG8_WAIT_L(0); PG8_BAR; PG8_MMA(1, 0, At, B0); PG8_MMA(1, 1, At, B1); PG8_BAR; PG8_SCHED;
	s_add_i32 s46, s55, s34
	v_lshl_add_u64 v[158:159], v[158:159], 0, s[14:15]
	s_mov_b32 m0, s46
	ds_read_b128 v[200:203], v145 offset:49152
	ds_read_b128 v[214:217], v145 offset:50176
	ds_read_b128 v[218:221], v145 offset:51200
	ds_read_b128 v[222:225], v145 offset:52224
	ds_read_b128 v[226:229], v145 offset:53248
	ds_read_b128 v[230:233], v145 offset:54272
	ds_read_b128 v[234:237], v145 offset:55296
	ds_read_b128 v[238:241], v145 offset:56320
	global_load_lds_dwordx4 v[158:159], off
	s_add_i32 m0, s46, 0x2000
	s_add_u32 s44, s44, 0x20080
	v_lshl_add_u64 v[158:159], v[162:163], 0, s[14:15]
	s_addc_u32 s45, s45, 0
	s_add_i32 s46, s56, s34
	global_load_lds_dwordx4 v[158:159], off
	v_lshl_add_u64 v[158:159], s[44:45], 0, v[160:161]
	s_mov_b32 m0, s46
	s_nop 0
	global_load_lds_dwordx4 v[158:159], off
	v_lshl_add_u64 v[158:159], s[44:45], 0, v[128:129]
	s_add_i32 m0, s46, 0x2000
	s_nop 0
	global_load_lds_dwordx4 v[158:159], off
	v_lshl_add_u64 v[158:159], v[242:243], 0, s[14:15]
	s_mov_b32 m0, s51
	s_nop 0
	global_load_lds_dwordx4 v[158:159], off
	v_lshl_add_u64 v[158:159], v[244:245], 0, s[14:15]
	s_mov_b32 m0, s52
	s_nop 0
	global_load_lds_dwordx4 v[158:159], off
	s_waitcnt vmcnt(8)
	s_waitcnt lgkmcnt(0)
	s_barrier
	s_setprio 1
	s_waitcnt lgkmcnt(0)
	v_mfma_f32_16x16x32_bf16 v[60:63], v[138:141], v[200:203], v[60:63]
	v_mfma_f32_16x16x32_bf16 v[56:59], v[150:153], v[200:203], v[56:59]
	v_mfma_f32_16x16x32_bf16 v[44:47], v[138:141], v[218:221], v[44:47]
	v_mfma_f32_16x16x32_bf16 v[40:43], v[150:153], v[218:221], v[40:43]
	v_mfma_f32_16x16x32_bf16 v[28:31], v[138:141], v[226:229], v[28:31]
	v_mfma_f32_16x16x32_bf16 v[24:27], v[150:153], v[226:229], v[24:27]
	v_mfma_f32_16x16x32_bf16 v[12:15], v[138:141], v[234:237], v[12:15]
	v_mfma_f32_16x16x32_bf16 v[8:11], v[150:153], v[234:237], v[8:11]
	v_mfma_f32_16x16x32_bf16 v[60:63], v[146:149], v[214:217], v[60:63]
	v_mfma_f32_16x16x32_bf16 v[56:59], v[154:157], v[214:217], v[56:59]
	v_mfma_f32_16x16x32_bf16 v[44:47], v[146:149], v[222:225], v[44:47]
	v_mfma_f32_16x16x32_bf16 v[40:43], v[154:157], v[222:225], v[40:43]
	v_mfma_f32_16x16x32_bf16 v[28:31], v[146:149], v[230:233], v[28:31]
	v_mfma_f32_16x16x32_bf16 v[24:27], v[154:157], v[230:233], v[24:27]
	v_mfma_f32_16x16x32_bf16 v[12:15], v[146:149], v[238:241], v[12:15]
	v_mfma_f32_16x16x32_bf16 v[8:11], v[154:157], v[238:241], v[8:11]
	s_setprio 0
	s_setprio 1
	v_mfma_f32_16x16x32_bf16 v[52:55], v[184:187], v[200:203], v[52:55]
	v_mfma_f32_16x16x32_bf16 v[48:51], v[192:195], v[200:203], v[48:51]
	v_mfma_f32_16x16x32_bf16 v[36:39], v[184:187], v[218:221], v[36:39]
	v_mfma_f32_16x16x32_bf16 v[32:35], v[192:195], v[218:221], v[32:35]
	v_mfma_f32_16x16x32_bf16 v[20:23], v[184:187], v[226:229], v[20:23]
	v_mfma_f32_16x16x32_bf16 v[16:19], v[192:195], v[226:229], v[16:19]
	v_mfma_f32_16x16x32_bf16 v[4:7], v[184:187], v[234:237], v[4:7]
	v_mfma_f32_16x16x32_bf16 v[0:3], v[192:195], v[234:237], v[0:3]
	v_mfma_f32_16x16x32_bf16 v[52:55], v[188:191], v[214:217], v[52:55]
	v_mfma_f32_16x16x32_bf16 v[48:51], v[196:199], v[214:217], v[48:51]
	v_mfma_f32_16x16x32_bf16 v[36:39], v[188:191], v[222:225], v[36:39]
	v_mfma_f32_16x16x32_bf16 v[32:35], v[196:199], v[222:225], v[32:35]
	v_mfma_f32_16x16x32_bf16 v[20:23], v[188:191], v[230:233], v[20:23]
	v_mfma_f32_16x16x32_bf16 v[16:19], v[196:199], v[230:233], v[16:19]
	v_mfma_f32_16x16x32_bf16 v[4:7], v[188:191], v[238:241], v[4:7]
	v_mfma_f32_16x16x32_bf16 v[0:3], v[196:199], v[238:241], v[0:3]
	s_setprio 0
	s_barrier
	s_add_i32 s54, s54, 2
	s_add_u32 s42, s42, 0x100
	s_addc_u32 s43, s43, 0
	s_add_u32 s28, s28, 0x100
	s_addc_u32 s29, s29, 0
	s_cmp_gt_u32 s54, 5
	s_cbranch_scc0 .LBB0_97
	s_branch .Lgk_after_97

; #define PG8_STAGE(bufoff, gbase, voff) do { _Pragma("unroll") for (int _i = 0; _i < 2; ++_i) \
;         __builtin_amdgcn_global_load_lds((const unsigned*)((const char*)(gbase) + (voff)[_i]), (PG8_LAS unsigned*)(lds + (bufoff) + ldsw + _i * 8192), 16, 0, 0); } while (0)
; #define PG8_WAIT_V(n) asm volatile("s_waitcnt vmcnt(" #n ")" ::: "memory")
; #define PG8_WAIT_L(n) asm volatile("s_waitcnt lgkmcnt(" #n ")" ::: "memory")
; #define PG8_BAR __builtin_amdgcn_s_barrier()
; #define PG8_SCHED __builtin_amdgcn_sched_barrier(0)
; template <class Epi, class Sched, bool ALIGN_EPI = false, bool SP2 = false, bool F8 = false>
; __device__ __forceinline__ void gemm_phase(PG8_LAS unsigned char* lds, const Gemm g, const Sched& S, const Epi& E) {
;     ...
;         const bool has_next = S.next(ui + 1, nxt);
;         const char* nA = has_next ? (const char*)g.A + (size_t)nxt.pm * tstep : cA; const char* nB = has_next ? (const char*)g.Bt + (size_t)nxt.pn * tstep : cB;
;         for (int t = 0; t < nt; t += 2) {
;             const bool last = (t == nt - 2);
;             const char* a1 = cA + (size_t)(t + 1) * kstep;
;             const char* a2 = last ? nA : cA + (size_t)(t + 2) * kstep; const char* b2 = last ? nB : cB + (size_t)(t + 2) * kstep;
;             const char* a3 = a2 + kstep; const char* b3 = b2 + kstep;
;             if (last && has_next) S.a_ready(nxt);
;             if constexpr (SP2) {
;             PG8_LDB(B0, 0, 0); PG8_LDB(B1, 0, 1); PG8_SCHED; PG8_LDA(At, 0, 0); PG8_STAGE(PG8_SA(1, 1), a1 + hstep, voffA);
;             PG8_WAIT_V(8); PG8_WAIT_L(0); PG8_BAR; PG8_MMA(0, 0, At, B0); PG8_MMA(0, 1, At, B1); PG8_BAR; PG8_SCHED;
;             PG8_LDA(At, 0, 1); PG8_STAGE(PG8_SB(0, 0), b2, voffB); PG8_STAGE(PG8_SB(0, 1), b2 + hstep, voffB); PG8_STAGE(PG8_SA(0, 0), a2, voffA);
;             PG8_WAIT_V(8); PG8_WAIT_L(0); PG8_BAR; PG8_MMA(1, 0, At, B0); PG8_MMA(1, 1, At, B1); PG8_BAR; PG8_SCHED;
.LBB0_116:
	s_ashr_i32 s41, s40, 31
	s_lshl_b64 s[28:29], s[40:41], 19
	s_add_u32 s42, s96, s28
	v_readlane_b32 s17, v253, 22
	s_addc_u32 s43, s17, s29
	s_and_b64 s[28:29], s[38:39], exec
	s_cselect_b32 s19, s43, s11
	s_cselect_b32 s23, s42, s10
	s_ashr_i32 s17, s16, 31
	s_lshl_b64 s[28:29], s[16:17], 19
	s_add_u32 s44, s22, s28
	s_addc_u32 s45, s34, s29
	s_and_b64 s[28:29], s[38:39], exec
	s_cselect_b32 s17, s45, s37
	s_cselect_b32 s28, s44, s36
	s_add_u32 s10, s10, 0x40080
	s_addc_u32 s11, s11, 0
	s_add_u32 s29, s36, 0x100
	s_addc_u32 s41, s37, 0
	s_mov_b32 s54, -2
	s_add_u32 s36, s10, 0xfffc0080
	s_addc_u32 s37, s11, -1
	s_add_i32 s55, 0, 0x10000
	s_cmp_eq_u32 s54, 12
	s_cselect_b32 s47, s19, s37
	s_cselect_b32 s46, s23, s36
	v_add_u32_e32 v142, s55, v145
	s_cselect_b32 s37, s17, s41
	s_cselect_b32 s36, s28, s29
	s_add_i32 s56, 0, 0x14000
	ds_read_b128 v[138:141], v142
	ds_read_b128 v[148:151], v142 offset:1024
	ds_read_b128 v[152:155], v142 offset:2048
	ds_read_b128 v[156:159], v142 offset:3072
	v_add_u32_e32 v142, s56, v145
	ds_read_b128 v[184:187], v142
	ds_read_b128 v[188:191], v142 offset:1024
	ds_read_b128 v[192:195], v142 offset:2048
	ds_read_b128 v[196:199], v142 offset:3072
	v_lshl_add_u64 v[142:143], s[10:11], 0, v[134:135]
	s_add_i32 m0, s35, 0xc000
	ds_read_b128 v[200:203], v147
	ds_read_b128 v[214:217], v147 offset:1024
	ds_read_b128 v[218:221], v147 offset:2048
	ds_read_b128 v[222:225], v147 offset:3072
	ds_read_b128 v[226:229], v147 offset:4096
	ds_read_b128 v[230:233], v147 offset:5120
	ds_read_b128 v[234:237], v147 offset:6144
	ds_read_b128 v[238:241], v147 offset:7168
	global_load_lds_dwordx4 v[142:143], off
	v_lshl_add_u64 v[142:143], s[10:11], 0, v[136:137]
	s_add_i32 m0, s35, 0xe000
	s_nop 0
	global_load_lds_dwordx4 v[142:143], off
	s_waitcnt vmcnt(8)
	s_waitcnt lgkmcnt(0)
	s_barrier
	s_setprio 1
	s_waitcnt lgkmcnt(0)
	v_mfma_f32_16x16x32_bf16 v[124:127], v[138:141], v[200:203], 0
	v_mfma_f32_16x16x32_bf16 v[120:123], v[152:155], v[200:203], 0
	v_mfma_f32_16x16x32_bf16 v[108:111], v[138:141], v[218:221], 0
	v_mfma_f32_16x16x32_bf16 v[104:107], v[152:155], v[218:221], 0
	v_mfma_f32_16x16x32_bf16 v[92:95], v[138:141], v[226:229], 0
	v_mfma_f32_16x16x32_bf16 v[88:91], v[152:155], v[226:229], 0
	v_mfma_f32_16x16x32_bf16 v[76:79], v[138:141], v[234:237], 0
	v_mfma_f32_16x16x32_bf16 v[72:75], v[152:155], v[234:237], 0
	v_mfma_f32_16x16x32_bf16 v[124:127], v[148:151], v[214:217], v[124:127]
	v_mfma_f32_16x16x32_bf16 v[120:123], v[156:159], v[214:217], v[120:123]
	v_mfma_f32_16x16x32_bf16 v[108:111], v[148:151], v[222:225], v[108:111]
	v_mfma_f32_16x16x32_bf16 v[104:107], v[156:159], v[222:225], v[104:107]
	v_mfma_f32_16x16x32_bf16 v[92:95], v[148:151], v[230:233], v[92:95]
	v_mfma_f32_16x16x32_bf16 v[88:91], v[156:159], v[230:233], v[88:91]
	v_mfma_f32_16x16x32_bf16 v[76:79], v[148:151], v[238:241], v[76:79]
	v_mfma_f32_16x16x32_bf16 v[72:75], v[156:159], v[238:241], v[72:75]
	s_setprio 0
	s_setprio 1
	v_mfma_f32_16x16x32_bf16 v[116:119], v[184:187], v[200:203], 0
	v_mfma_f32_16x16x32_bf16 v[112:115], v[192:195], v[200:203], 0
	v_mfma_f32_16x16x32_bf16 v[100:103], v[184:187], v[218:221], 0
	v_mfma_f32_16x16x32_bf16 v[96:99], v[192:195], v[218:221], 0
	v_mfma_f32_16x16x32_bf16 v[84:87], v[184:187], v[226:229], 0
	v_mfma_f32_16x16x32_bf16 v[80:83], v[192:195], v[226:229], 0
	v_mfma_f32_16x16x32_bf16 v[68:71], v[184:187], v[234:237], 0
	v_mfma_f32_16x16x32_bf16 v[64:67], v[192:195], v[234:237], 0
	v_mfma_f32_16x16x32_bf16 v[116:119], v[188:191], v[214:217], v[116:119]
	v_mfma_f32_16x16x32_bf16 v[112:115], v[196:199], v[214:217], v[112:115]
	v_mfma_f32_16x16x32_bf16 v[100:103], v[188:191], v[222:225], v[100:103]
	v_mfma_f32_16x16x32_bf16 v[96:99], v[196:199], v[222:225], v[96:99]
	v_mfma_f32_16x16x32_bf16 v[84:87], v[188:191], v[230:233], v[84:87]
	v_mfma_f32_16x16x32_bf16 v[80:83], v[196:199], v[230:233], v[80:83]
	v_mfma_f32_16x16x32_bf16 v[68:71], v[188:191], v[238:241], v[68:71]
	v_mfma_f32_16x16x32_bf16 v[64:67], v[196:199], v[238:241], v[64:67]
	s_setprio 0
	s_barrier
	s_add_i32 s55, s55, s13
	v_lshl_add_u64 v[142:143], s[36:37], 0, v[160:161]
	s_mov_b32 m0, s55
	ds_read_b128 v[200:203], v147 offset:16384
	ds_read_b128 v[214:217], v147 offset:17408
	ds_read_b128 v[218:221], v147 offset:18432
	ds_read_b128 v[222:225], v147 offset:19456
	ds_read_b128 v[226:229], v147 offset:20480
	ds_read_b128 v[230:233], v147 offset:21504
	ds_read_b128 v[234:237], v147 offset:22528
	ds_read_b128 v[238:241], v147 offset:23552
	global_load_lds_dwordx4 v[142:143], off
	s_add_i32 m0, s55, 0x2000
	s_add_u32 s58, s36, 0x40000
	v_lshl_add_u64 v[162:163], s[36:37], 0, v[128:129]
	s_addc_u32 s59, s37, 0
	s_add_i32 s55, s56, s13
	global_load_lds_dwordx4 v[162:163], off
	v_lshl_add_u64 v[242:243], s[58:59], 0, v[160:161]
	s_mov_b32 m0, s55
	v_lshl_add_u64 v[244:245], s[46:47], 0, v[130:131]
	global_load_lds_dwordx4 v[242:243], off
	v_lshl_add_u64 v[242:243], s[58:59], 0, v[128:129]
	s_add_i32 m0, s55, 0x2000
	s_nop 0
	global_load_lds_dwordx4 v[242:243], off
	v_lshl_add_u64 v[242:243], s[46:47], 0, v[132:133]
	s_mov_b32 m0, s35
	s_nop 0
	global_load_lds_dwordx4 v[242:243], off
	s_mov_b32 m0, s48
	s_nop 0
	global_load_lds_dwordx4 v[244:245], off
	s_waitcnt vmcnt(8)
	s_waitcnt lgkmcnt(0)
	s_barrier
; #define PG8_STAGE(bufoff, gbase, voff) do { _Pragma("unroll") for (int _i = 0; _i < 2; ++_i) \
;         __builtin_amdgcn_global_load_lds((const unsigned*)((const char*)(gbase) + (voff)[_i]), (PG8_LAS unsigned*)(lds + (bufoff) + ldsw + _i * 8192), 16, 0, 0); } while (0)
; #define PG8_WAIT_V(n) asm volatile("s_waitcnt vmcnt(" #n ")" ::: "memory")
; #define PG8_WAIT_L(n) asm volatile("s_waitcnt lgkmcnt(" #n ")" ::: "memory")
; #define PG8_BAR __builtin_amdgcn_s_barrier()
; #define PG8_SCHED __builtin_amdgcn_sched_barrier(0)
; template <class Epi, class Sched, bool ALIGN_EPI = false, bool SP2 = false, bool F8 = false>
; __device__ __forceinline__ void gemm_phase(PG8_LAS unsigned char* lds, const Gemm g, const Sched& S, const Epi& E) {
;     ...
;             PG8_WAIT_V(8); PG8_WAIT_L(0); PG8_BAR; PG8_MMA(1, 0, At, B0); PG8_MMA(1, 1, At, B1); PG8_BAR; PG8_SCHED;
;             PG8_LDB(B0, 1, 0); PG8_LDB(B1, 1, 1); PG8_SCHED; PG8_LDA(At, 1, 0); PG8_STAGE(PG8_SA(0, 1), a2 + hstep, voffA);
;             PG8_WAIT_V(8); PG8_WAIT_L(0); PG8_BAR; PG8_MMA(0, 0, At, B0); PG8_MMA(0, 1, At, B1); PG8_BAR; PG8_SCHED;
	s_setprio 1
	s_waitcnt lgkmcnt(0)
	v_mfma_f32_16x16x32_bf16 v[60:63], v[138:141], v[200:203], 0
	v_mfma_f32_16x16x32_bf16 v[56:59], v[152:155], v[200:203], 0
	v_mfma_f32_16x16x32_bf16 v[44:47], v[138:141], v[218:221], 0
	v_mfma_f32_16x16x32_bf16 v[40:43], v[152:155], v[218:221], 0
	v_mfma_f32_16x16x32_bf16 v[28:31], v[138:141], v[226:229], 0
	v_mfma_f32_16x16x32_bf16 v[24:27], v[152:155], v[226:229], 0
	v_mfma_f32_16x16x32_bf16 v[12:15], v[138:141], v[234:237], 0
	v_mfma_f32_16x16x32_bf16 v[8:11], v[152:155], v[234:237], 0
	v_mfma_f32_16x16x32_bf16 v[60:63], v[148:151], v[214:217], v[60:63]
	v_mfma_f32_16x16x32_bf16 v[56:59], v[156:159], v[214:217], v[56:59]
	v_mfma_f32_16x16x32_bf16 v[44:47], v[148:151], v[222:225], v[44:47]
	v_mfma_f32_16x16x32_bf16 v[40:43], v[156:159], v[222:225], v[40:43]
	v_mfma_f32_16x16x32_bf16 v[28:31], v[148:151], v[230:233], v[28:31]
	v_mfma_f32_16x16x32_bf16 v[24:27], v[156:159], v[230:233], v[24:27]
	v_mfma_f32_16x16x32_bf16 v[12:15], v[148:151], v[238:241], v[12:15]
	v_mfma_f32_16x16x32_bf16 v[8:11], v[156:159], v[238:241], v[8:11]
	s_setprio 0
	s_setprio 1
	v_mfma_f32_16x16x32_bf16 v[52:55], v[184:187], v[200:203], 0
	v_mfma_f32_16x16x32_bf16 v[48:51], v[192:195], v[200:203], 0
	v_mfma_f32_16x16x32_bf16 v[36:39], v[184:187], v[218:221], 0
	v_mfma_f32_16x16x32_bf16 v[32:35], v[192:195], v[218:221], 0
	v_mfma_f32_16x16x32_bf16 v[20:23], v[184:187], v[226:229], 0
	v_mfma_f32_16x16x32_bf16 v[16:19], v[192:195], v[226:229], 0
	v_mfma_f32_16x16x32_bf16 v[4:7], v[184:187], v[234:237], 0
	v_mfma_f32_16x16x32_bf16 v[0:3], v[192:195], v[234:237], 0
	v_mfma_f32_16x16x32_bf16 v[52:55], v[188:191], v[214:217], v[52:55]
	v_mfma_f32_16x16x32_bf16 v[48:51], v[196:199], v[214:217], v[48:51]
	v_mfma_f32_16x16x32_bf16 v[36:39], v[188:191], v[222:225], v[36:39]
	v_mfma_f32_16x16x32_bf16 v[32:35], v[196:199], v[222:225], v[32:35]
	v_mfma_f32_16x16x32_bf16 v[20:23], v[188:191], v[230:233], v[20:23]
	v_mfma_f32_16x16x32_bf16 v[16:19], v[196:199], v[230:233], v[16:19]
	v_mfma_f32_16x16x32_bf16 v[4:7], v[188:191], v[238:241], v[4:7]
	v_mfma_f32_16x16x32_bf16 v[0:3], v[196:199], v[238:241], v[0:3]
	s_setprio 0
	s_barrier
	s_add_i32 s55, 0, 0x18000
	s_add_i32 s56, 0, 0x1c000
	v_add_u32_e32 v156, s55, v145
	v_add_u32_e32 v196, s56, v145
	ds_read_b128 v[138:141], v156
	ds_read_b128 v[148:151], v156 offset:1024
	ds_read_b128 v[152:155], v156 offset:2048
	ds_read_b128 v[156:159], v156 offset:3072
	ds_read_b128 v[184:187], v196
	ds_read_b128 v[188:191], v196 offset:1024
	ds_read_b128 v[192:195], v196 offset:2048
	ds_read_b128 v[196:199], v196 offset:3072
	s_add_u32 s46, s46, 0x40000
	s_addc_u32 s47, s47, 0
	s_mov_b32 m0, s49
	v_lshl_add_u64 v[246:247], s[46:47], 0, v[132:133]
	ds_read_b128 v[200:203], v147 offset:32768
	ds_read_b128 v[214:217], v147 offset:33792
	ds_read_b128 v[218:221], v147 offset:34816
	ds_read_b128 v[222:225], v147 offset:35840
	ds_read_b128 v[226:229], v147 offset:36864
	ds_read_b128 v[230:233], v147 offset:37888
	ds_read_b128 v[234:237], v147 offset:38912
	ds_read_b128 v[238:241], v147 offset:39936
	global_load_lds_dwordx4 v[246:247], off
	v_lshl_add_u64 v[246:247], s[46:47], 0, v[130:131]
	s_mov_b32 m0, s50
	s_nop 0
	global_load_lds_dwordx4 v[246:247], off
	s_waitcnt vmcnt(8)
	s_waitcnt lgkmcnt(0)
	s_barrier
	s_setprio 1
	s_waitcnt lgkmcnt(0)
	v_mfma_f32_16x16x32_bf16 v[124:127], v[138:141], v[200:203], v[124:127]
	v_mfma_f32_16x16x32_bf16 v[120:123], v[152:155], v[200:203], v[120:123]
	v_mfma_f32_16x16x32_bf16 v[108:111], v[138:141], v[218:221], v[108:111]
	v_mfma_f32_16x16x32_bf16 v[104:107], v[152:155], v[218:221], v[104:107]
	v_mfma_f32_16x16x32_bf16 v[92:95], v[138:141], v[226:229], v[92:95]
	v_mfma_f32_16x16x32_bf16 v[88:91], v[152:155], v[226:229], v[88:91]
	v_mfma_f32_16x16x32_bf16 v[76:79], v[138:141], v[234:237], v[76:79]
	v_mfma_f32_16x16x32_bf16 v[72:75], v[152:155], v[234:237], v[72:75]
	v_mfma_f32_16x16x32_bf16 v[124:127], v[148:151], v[214:217], v[124:127]
	v_mfma_f32_16x16x32_bf16 v[120:123], v[156:159], v[214:217], v[120:123]
	v_mfma_f32_16x16x32_bf16 v[108:111], v[148:151], v[222:225], v[108:111]
	v_mfma_f32_16x16x32_bf16 v[104:107], v[156:159], v[222:225], v[104:107]
	v_mfma_f32_16x16x32_bf16 v[92:95], v[148:151], v[230:233], v[92:95]
	v_mfma_f32_16x16x32_bf16 v[88:91], v[156:159], v[230:233], v[88:91]
	v_mfma_f32_16x16x32_bf16 v[76:79], v[148:151], v[238:241], v[76:79]
	v_mfma_f32_16x16x32_bf16 v[72:75], v[156:159], v[238:241], v[72:75]
	s_setprio 0
	s_setprio 1
	v_mfma_f32_16x16x32_bf16 v[116:119], v[184:187], v[200:203], v[116:119]
	v_mfma_f32_16x16x32_bf16 v[112:115], v[192:195], v[200:203], v[112:115]
	v_mfma_f32_16x16x32_bf16 v[100:103], v[184:187], v[218:221], v[100:103]
	v_mfma_f32_16x16x32_bf16 v[96:99], v[192:195], v[218:221], v[96:99]
	v_mfma_f32_16x16x32_bf16 v[84:87], v[184:187], v[226:229], v[84:87]
	v_mfma_f32_16x16x32_bf16 v[80:83], v[192:195], v[226:229], v[80:83]
	v_mfma_f32_16x16x32_bf16 v[68:71], v[184:187], v[234:237], v[68:71]
	v_mfma_f32_16x16x32_bf16 v[64:67], v[192:195], v[234:237], v[64:67]
	v_mfma_f32_16x16x32_bf16 v[116:119], v[188:191], v[214:217], v[116:119]
	v_mfma_f32_16x16x32_bf16 v[112:115], v[196:199], v[214:217], v[112:115]
	v_mfma_f32_16x16x32_bf16 v[100:103], v[188:191], v[222:225], v[100:103]
	v_mfma_f32_16x16x32_bf16 v[96:99], v[196:199], v[222:225], v[96:99]
	v_mfma_f32_16x16x32_bf16 v[84:87], v[188:191], v[230:233], v[84:87]
	v_mfma_f32_16x16x32_bf16 v[80:83], v[196:199], v[230:233], v[80:83]
	v_mfma_f32_16x16x32_bf16 v[68:71], v[188:191], v[238:241], v[68:71]
	v_mfma_f32_16x16x32_bf16 v[64:67], v[196:199], v[238:241], v[64:67]
	s_setprio 0
	s_barrier
; #define PG8_STAGE(bufoff, gbase, voff) do { _Pragma("unroll") for (int _i = 0; _i < 2; ++_i) \
;         __builtin_amdgcn_global_load_lds((const unsigned*)((const char*)(gbase) + (voff)[_i]), (PG8_LAS unsigned*)(lds + (bufoff) + ldsw + _i * 8192), 16, 0, 0); } while (0)
; #define PG8_WAIT_V(n) asm volatile("s_waitcnt vmcnt(" #n ")" ::: "memory")
; #define PG8_WAIT_L(n) asm volatile("s_waitcnt lgkmcnt(" #n ")" ::: "memory")
; #define PG8_BAR __builtin_amdgcn_s_barrier()
; #define PG8_SCHED __builtin_amdgcn_sched_barrier(0)
; template <class Epi, class Sched, bool ALIGN_EPI = false, bool SP2 = false, bool F8 = false>
; __device__ __forceinline__ void gemm_phase(PG8_LAS unsigned char* lds, const Gemm g, const Sched& S, const Epi& E) {
;     ...
;             PG8_LDA(At, 1, 1); PG8_STAGE(PG8_SB(1, 0), b3, voffB); PG8_STAGE(PG8_SB(1, 1), b3 + hstep, voffB); PG8_STAGE(PG8_SA(1, 0), a3, voffA);
;             PG8_WAIT_V(8); PG8_WAIT_L(0); PG8_BAR; PG8_MMA(1, 0, At, B0); PG8_MMA(1, 1, At, B1); PG8_BAR; PG8_SCHED;
	s_add_i32 s46, s55, s13
	v_lshl_add_u64 v[142:143], v[142:143], 0, s[14:15]
	s_mov_b32 m0, s46
	ds_read_b128 v[200:203], v147 offset:49152
	ds_read_b128 v[214:217], v147 offset:50176
	ds_read_b128 v[218:221], v147 offset:51200
	ds_read_b128 v[222:225], v147 offset:52224
	ds_read_b128 v[226:229], v147 offset:53248
	ds_read_b128 v[230:233], v147 offset:54272
	ds_read_b128 v[234:237], v147 offset:55296
	ds_read_b128 v[238:241], v147 offset:56320
	global_load_lds_dwordx4 v[142:143], off
	s_add_i32 m0, s46, 0x2000
	s_add_u32 s36, s36, 0x40080
	v_lshl_add_u64 v[142:143], v[162:163], 0, s[14:15]
	s_addc_u32 s37, s37, 0
	s_add_i32 s46, s56, s13
	global_load_lds_dwordx4 v[142:143], off
	v_lshl_add_u64 v[142:143], s[36:37], 0, v[160:161]
	s_mov_b32 m0, s46
	s_nop 0
	global_load_lds_dwordx4 v[142:143], off
	v_lshl_add_u64 v[142:143], s[36:37], 0, v[128:129]
	s_add_i32 m0, s46, 0x2000
	s_nop 0
	global_load_lds_dwordx4 v[142:143], off
	v_lshl_add_u64 v[142:143], v[242:243], 0, s[14:15]
	s_mov_b32 m0, s51
	s_nop 0
	global_load_lds_dwordx4 v[142:143], off
	v_lshl_add_u64 v[142:143], v[244:245], 0, s[14:15]
	s_mov_b32 m0, s52
	s_nop 0
	global_load_lds_dwordx4 v[142:143], off
	s_waitcnt vmcnt(8)
	s_waitcnt lgkmcnt(0)
	s_barrier
	s_setprio 1
	s_waitcnt lgkmcnt(0)
	v_mfma_f32_16x16x32_bf16 v[60:63], v[138:141], v[200:203], v[60:63]
	v_mfma_f32_16x16x32_bf16 v[56:59], v[152:155], v[200:203], v[56:59]
	v_mfma_f32_16x16x32_bf16 v[44:47], v[138:141], v[218:221], v[44:47]
	v_mfma_f32_16x16x32_bf16 v[40:43], v[152:155], v[218:221], v[40:43]
	v_mfma_f32_16x16x32_bf16 v[28:31], v[138:141], v[226:229], v[28:31]
	v_mfma_f32_16x16x32_bf16 v[24:27], v[152:155], v[226:229], v[24:27]
	v_mfma_f32_16x16x32_bf16 v[12:15], v[138:141], v[234:237], v[12:15]
	v_mfma_f32_16x16x32_bf16 v[8:11], v[152:155], v[234:237], v[8:11]
	v_mfma_f32_16x16x32_bf16 v[60:63], v[148:151], v[214:217], v[60:63]
	v_mfma_f32_16x16x32_bf16 v[56:59], v[156:159], v[214:217], v[56:59]
	v_mfma_f32_16x16x32_bf16 v[44:47], v[148:151], v[222:225], v[44:47]
	v_mfma_f32_16x16x32_bf16 v[40:43], v[156:159], v[222:225], v[40:43]
	v_mfma_f32_16x16x32_bf16 v[28:31], v[148:151], v[230:233], v[28:31]
	v_mfma_f32_16x16x32_bf16 v[24:27], v[156:159], v[230:233], v[24:27]
	v_mfma_f32_16x16x32_bf16 v[12:15], v[148:151], v[238:241], v[12:15]
	v_mfma_f32_16x16x32_bf16 v[8:11], v[156:159], v[238:241], v[8:11]
	s_setprio 0
	s_setprio 1
	v_mfma_f32_16x16x32_bf16 v[52:55], v[184:187], v[200:203], v[52:55]
	v_mfma_f32_16x16x32_bf16 v[48:51], v[192:195], v[200:203], v[48:51]
	v_mfma_f32_16x16x32_bf16 v[36:39], v[184:187], v[218:221], v[36:39]
	v_mfma_f32_16x16x32_bf16 v[32:35], v[192:195], v[218:221], v[32:35]
	v_mfma_f32_16x16x32_bf16 v[20:23], v[184:187], v[226:229], v[20:23]
	v_mfma_f32_16x16x32_bf16 v[16:19], v[192:195], v[226:229], v[16:19]
	v_mfma_f32_16x16x32_bf16 v[4:7], v[184:187], v[234:237], v[4:7]
	v_mfma_f32_16x16x32_bf16 v[0:3], v[192:195], v[234:237], v[0:3]
	v_mfma_f32_16x16x32_bf16 v[52:55], v[188:191], v[214:217], v[52:55]
	v_mfma_f32_16x16x32_bf16 v[48:51], v[196:199], v[214:217], v[48:51]
	v_mfma_f32_16x16x32_bf16 v[36:39], v[188:191], v[222:225], v[36:39]
	v_mfma_f32_16x16x32_bf16 v[32:35], v[196:199], v[222:225], v[32:35]
	v_mfma_f32_16x16x32_bf16 v[20:23], v[188:191], v[230:233], v[20:23]
	v_mfma_f32_16x16x32_bf16 v[16:19], v[196:199], v[230:233], v[16:19]
	v_mfma_f32_16x16x32_bf16 v[4:7], v[188:191], v[238:241], v[4:7]
	v_mfma_f32_16x16x32_bf16 v[0:3], v[196:199], v[238:241], v[0:3]
	s_setprio 0
	s_barrier
	s_add_i32 s54, s54, 2
	s_add_u32 s10, s10, 0x100
	s_addc_u32 s11, s11, 0
	s_add_u32 s29, s29, 0x100
	s_addc_u32 s41, s41, 0
	s_cmp_gt_u32 s54, 13
	s_cbranch_scc0 .LBB0_117
	s_branch .Lgk_after_117

; #define PG8_STAGE(bufoff, gbase, voff) do { _Pragma("unroll") for (int _i = 0; _i < 2; ++_i) \
;         __builtin_amdgcn_global_load_lds((const unsigned*)((const char*)(gbase) + (voff)[_i]), (PG8_LAS unsigned*)(lds + (bufoff) + ldsw + _i * 8192), 16, 0, 0); } while (0)
; #define PG8_WAIT_V(n) asm volatile("s_waitcnt vmcnt(" #n ")" ::: "memory")
; #define PG8_WAIT_L(n) asm volatile("s_waitcnt lgkmcnt(" #n ")" ::: "memory")
; #define PG8_BAR __builtin_amdgcn_s_barrier()
; #define PG8_SCHED __builtin_amdgcn_sched_barrier(0)
; template <class Epi, class Sched, bool ALIGN_EPI = false, bool SP2 = false, bool F8 = false>
; __device__ __forceinline__ void gemm_phase(PG8_LAS unsigned char* lds, const Gemm g, const Sched& S, const Epi& E) {
;     ...
;         const bool has_next = S.next(ui + 1, nxt);
;         const char* nA = has_next ? (const char*)g.A + (size_t)nxt.pm * tstep : cA; const char* nB = has_next ? (const char*)g.Bt + (size_t)nxt.pn * tstep : cB;
;         for (int t = 0; t < nt; t += 2) {
;             const bool last = (t == nt - 2);
;             const char* a1 = cA + (size_t)(t + 1) * kstep;
;             const char* a2 = last ? nA : cA + (size_t)(t + 2) * kstep; const char* b2 = last ? nB : cB + (size_t)(t + 2) * kstep;
;             const char* a3 = a2 + kstep; const char* b3 = b2 + kstep;
;             if (last && has_next) S.a_ready(nxt);
;             if constexpr (SP2) {
;             PG8_LDB(B0, 0, 0); PG8_LDB(B1, 0, 1); PG8_SCHED; PG8_LDA(At, 0, 0); PG8_STAGE(PG8_SA(1, 1), a1 + hstep, voffA);
;             PG8_WAIT_V(8); PG8_WAIT_L(0); PG8_BAR; PG8_MMA(0, 0, At, B0); PG8_MMA(0, 1, At, B1); PG8_BAR; PG8_SCHED;
;             PG8_LDA(At, 0, 1); PG8_STAGE(PG8_SB(0, 0), b2, voffB); PG8_STAGE(PG8_SB(0, 1), b2 + hstep, voffB); PG8_STAGE(PG8_SA(0, 0), a2, voffA);
;             PG8_WAIT_V(8); PG8_WAIT_L(0); PG8_BAR; PG8_MMA(1, 0, At, B0); PG8_MMA(1, 1, At, B1); PG8_BAR; PG8_SCHED;
.LBB0_1021:
	s_ashr_i32 s17, s16, 31
	s_lshl_b64 s[36:37], s[16:17], 19
	v_readlane_b32 s11, v253, 59
	s_add_u32 s36, s11, s36
	v_readlane_b32 s11, v253, 60
	s_addc_u32 s37, s11, s37
	s_and_b64 s[42:43], s[38:39], exec
	s_cselect_b32 s17, s37, s41
	s_cselect_b32 s50, s36, s40
	s_ashr_i32 s11, s10, 31
	s_lshl_b64 s[42:43], s[10:11], 19
	s_add_u32 s42, s13, s42
	s_addc_u32 s43, s19, s43
	s_and_b64 s[46:47], s[38:39], exec
	s_cselect_b32 s11, s43, s45
	s_cselect_b32 s51, s42, s44
	s_add_u32 s40, s40, 0x40080
	s_addc_u32 s41, s41, 0
	s_add_u32 s52, s44, 0x100
	s_addc_u32 s53, s45, 0
	s_mov_b32 s54, -2
	s_add_u32 s44, s40, 0xfffc0080
	s_addc_u32 s45, s41, -1
	s_add_i32 s55, 0, 0x10000
	s_cmp_eq_u32 s54, 12
	s_cselect_b32 s47, s17, s45
	s_cselect_b32 s46, s50, s44
	s_cselect_b32 s45, s11, s53
	s_cselect_b32 s44, s51, s52
	s_add_i32 s56, 0, 0x14000
	v_add_u32_e32 v0, s55, v215
	v_add_u32_e32 v12, s56, v215
	ds_read_b128 v[16:19], v0
	ds_read_b128 v[20:23], v0 offset:1024
	ds_read_b128 v[24:27], v0 offset:2048
	ds_read_b128 v[28:31], v0 offset:3072
	ds_read_b128 v[0:3], v12
	ds_read_b128 v[4:7], v12 offset:1024
	ds_read_b128 v[8:11], v12 offset:2048
	ds_read_b128 v[12:15], v12 offset:3072
	v_lshl_add_u64 v[242:243], s[40:41], 0, v[192:193]
	s_add_i32 m0, s23, 0xc000
	ds_read_b128 v[196:199], v217
	ds_read_b128 v[200:203], v217 offset:1024
	ds_read_b128 v[218:221], v217 offset:2048
	ds_read_b128 v[222:225], v217 offset:3072
	ds_read_b128 v[226:229], v217 offset:4096
	ds_read_b128 v[230:233], v217 offset:5120
	ds_read_b128 v[234:237], v217 offset:6144
	ds_read_b128 v[238:241], v217 offset:7168
	global_load_lds_dwordx4 v[242:243], off
	v_lshl_add_u64 v[242:243], s[40:41], 0, v[194:195]
	s_add_i32 m0, s23, 0xe000
	s_nop 0
	global_load_lds_dwordx4 v[242:243], off
	s_waitcnt vmcnt(8)
	s_waitcnt lgkmcnt(0)
	s_barrier
	s_setprio 1
	s_waitcnt lgkmcnt(0)
	v_mfma_scale_f32_16x16x128_f8f6f4 v[156:159], v[16:23], v[196:203], 0, v213, v213 op_sel_hi:[0,0,0]
	v_mfma_scale_f32_16x16x128_f8f6f4 v[152:155], v[24:31], v[196:203], 0, v213, v213 op_sel_hi:[0,0,0]
	v_mfma_scale_f32_16x16x128_f8f6f4 v[140:143], v[16:23], v[218:225], 0, v213, v213 op_sel_hi:[0,0,0]
	v_mfma_scale_f32_16x16x128_f8f6f4 v[136:139], v[24:31], v[218:225], 0, v213, v213 op_sel_hi:[0,0,0]
	v_mfma_scale_f32_16x16x128_f8f6f4 v[124:127], v[16:23], v[226:233], 0, v213, v213 op_sel_hi:[0,0,0]
	v_mfma_scale_f32_16x16x128_f8f6f4 v[120:123], v[24:31], v[226:233], 0, v213, v213 op_sel_hi:[0,0,0]
	v_mfma_scale_f32_16x16x128_f8f6f4 v[108:111], v[16:23], v[234:241], 0, v213, v213 op_sel_hi:[0,0,0]
	v_mfma_scale_f32_16x16x128_f8f6f4 v[104:107], v[24:31], v[234:241], 0, v213, v213 op_sel_hi:[0,0,0]
	s_setprio 0
	s_setprio 1
	v_mfma_scale_f32_16x16x128_f8f6f4 v[148:151], v[0:7], v[196:203], 0, v213, v213 op_sel_hi:[0,0,0]
	v_mfma_scale_f32_16x16x128_f8f6f4 v[144:147], v[8:15], v[196:203], 0, v213, v213 op_sel_hi:[0,0,0]
	v_mfma_scale_f32_16x16x128_f8f6f4 v[132:135], v[0:7], v[218:225], 0, v213, v213 op_sel_hi:[0,0,0]
	v_mfma_scale_f32_16x16x128_f8f6f4 v[128:131], v[8:15], v[218:225], 0, v213, v213 op_sel_hi:[0,0,0]
	v_mfma_scale_f32_16x16x128_f8f6f4 v[116:119], v[0:7], v[226:233], 0, v213, v213 op_sel_hi:[0,0,0]
	v_mfma_scale_f32_16x16x128_f8f6f4 v[112:115], v[8:15], v[226:233], 0, v213, v213 op_sel_hi:[0,0,0]
	v_mfma_scale_f32_16x16x128_f8f6f4 v[100:103], v[0:7], v[234:241], 0, v213, v213 op_sel_hi:[0,0,0]
	v_mfma_scale_f32_16x16x128_f8f6f4 v[96:99], v[8:15], v[234:241], 0, v213, v213 op_sel_hi:[0,0,0]
	s_setprio 0
	s_barrier
	s_add_i32 s55, s55, s22
	v_lshl_add_u64 v[196:197], s[44:45], 0, v[188:189]
	s_mov_b32 m0, s55
	ds_read_b128 v[218:221], v217 offset:16384
	ds_read_b128 v[222:225], v217 offset:17408
	ds_read_b128 v[226:229], v217 offset:18432
	ds_read_b128 v[230:233], v217 offset:19456
	ds_read_b128 v[234:237], v217 offset:20480
	ds_read_b128 v[238:241], v217 offset:21504
	ds_read_b128 v[242:245], v217 offset:22528
	ds_read_b128 v[246:249], v217 offset:23552
	global_load_lds_dwordx4 v[196:197], off
	s_add_i32 m0, s55, 0x2000
	s_add_u32 s58, s44, 0x40000
	v_lshl_add_u64 v[198:199], s[44:45], 0, v[184:185]
	s_addc_u32 s59, s45, 0
	s_add_i32 s55, s56, s22
	global_load_lds_dwordx4 v[198:199], off
	v_lshl_add_u64 v[200:201], s[58:59], 0, v[188:189]
	s_mov_b32 m0, s55
	v_lshl_add_u64 v[202:203], s[46:47], 0, v[186:187]
	global_load_lds_dwordx4 v[200:201], off
	v_lshl_add_u64 v[200:201], s[58:59], 0, v[184:185]
	s_add_i32 m0, s55, 0x2000
	s_nop 0
	global_load_lds_dwordx4 v[200:201], off
	v_lshl_add_u64 v[200:201], s[46:47], 0, v[190:191]
	s_mov_b32 m0, s23
	s_nop 0
	global_load_lds_dwordx4 v[200:201], off
	s_mov_b32 m0, s8
	s_nop 0
	global_load_lds_dwordx4 v[202:203], off
	s_waitcnt vmcnt(8)
	s_waitcnt lgkmcnt(0)
	s_barrier
	s_setprio 1
	s_waitcnt lgkmcnt(0)
	v_mfma_scale_f32_16x16x128_f8f6f4 v[92:95], v[16:23], v[218:225], 0, v213, v213 op_sel_hi:[0,0,0]
	v_mfma_scale_f32_16x16x128_f8f6f4 v[88:91], v[24:31], v[218:225], 0, v213, v213 op_sel_hi:[0,0,0]
	v_mfma_scale_f32_16x16x128_f8f6f4 v[76:79], v[16:23], v[226:233], 0, v213, v213 op_sel_hi:[0,0,0]
	v_mfma_scale_f32_16x16x128_f8f6f4 v[72:75], v[24:31], v[226:233], 0, v213, v213 op_sel_hi:[0,0,0]
	v_mfma_scale_f32_16x16x128_f8f6f4 v[60:63], v[16:23], v[234:241], 0, v213, v213 op_sel_hi:[0,0,0]
	v_mfma_scale_f32_16x16x128_f8f6f4 v[56:59], v[24:31], v[234:241], 0, v213, v213 op_sel_hi:[0,0,0]
	v_mfma_scale_f32_16x16x128_f8f6f4 v[44:47], v[16:23], v[242:249], 0, v213, v213 op_sel_hi:[0,0,0]
	v_mfma_scale_f32_16x16x128_f8f6f4 v[40:43], v[24:31], v[242:249], 0, v213, v213 op_sel_hi:[0,0,0]
	s_setprio 0
	s_setprio 1
	v_mfma_scale_f32_16x16x128_f8f6f4 v[84:87], v[0:7], v[218:225], 0, v213, v213 op_sel_hi:[0,0,0]
	v_mfma_scale_f32_16x16x128_f8f6f4 v[80:83], v[8:15], v[218:225], 0, v213, v213 op_sel_hi:[0,0,0]
	v_mfma_scale_f32_16x16x128_f8f6f4 v[68:71], v[0:7], v[226:233], 0, v213, v213 op_sel_hi:[0,0,0]
	v_mfma_scale_f32_16x16x128_f8f6f4 v[64:67], v[8:15], v[226:233], 0, v213, v213 op_sel_hi:[0,0,0]
	v_mfma_scale_f32_16x16x128_f8f6f4 v[52:55], v[0:7], v[234:241], 0, v213, v213 op_sel_hi:[0,0,0]
	v_mfma_scale_f32_16x16x128_f8f6f4 v[48:51], v[8:15], v[234:241], 0, v213, v213 op_sel_hi:[0,0,0]
	v_mfma_scale_f32_16x16x128_f8f6f4 v[36:39], v[0:7], v[242:249], 0, v213, v213 op_sel_hi:[0,0,0]
	v_mfma_scale_f32_16x16x128_f8f6f4 v[32:35], v[8:15], v[242:249], 0, v213, v213 op_sel_hi:[0,0,0]
	s_setprio 0
	s_barrier
; #define PG8_STAGE(bufoff, gbase, voff) do { _Pragma("unroll") for (int _i = 0; _i < 2; ++_i) \
;         __builtin_amdgcn_global_load_lds((const unsigned*)((const char*)(gbase) + (voff)[_i]), (PG8_LAS unsigned*)(lds + (bufoff) + ldsw + _i * 8192), 16, 0, 0); } while (0)
; #define PG8_WAIT_V(n) asm volatile("s_waitcnt vmcnt(" #n ")" ::: "memory")
; #define PG8_WAIT_L(n) asm volatile("s_waitcnt lgkmcnt(" #n ")" ::: "memory")
; #define PG8_BAR __builtin_amdgcn_s_barrier()
; #define PG8_SCHED __builtin_amdgcn_sched_barrier(0)
; template <class Epi, class Sched, bool ALIGN_EPI = false, bool SP2 = false, bool F8 = false>
; __device__ __forceinline__ void gemm_phase(PG8_LAS unsigned char* lds, const Gemm g, const Sched& S, const Epi& E) {
;     ...
;             PG8_LDB(B0, 1, 0); PG8_LDB(B1, 1, 1); PG8_SCHED; PG8_LDA(At, 1, 0); PG8_STAGE(PG8_SA(0, 1), a2 + hstep, voffA);
;             PG8_WAIT_V(8); PG8_WAIT_L(0); PG8_BAR; PG8_MMA(0, 0, At, B0); PG8_MMA(0, 1, At, B1); PG8_BAR; PG8_SCHED;
;             PG8_LDA(At, 1, 1); PG8_STAGE(PG8_SB(1, 0), b3, voffB); PG8_STAGE(PG8_SB(1, 1), b3 + hstep, voffB); PG8_STAGE(PG8_SA(1, 0), a3, voffA);
;             PG8_WAIT_V(8); PG8_WAIT_L(0); PG8_BAR; PG8_MMA(1, 0, At, B0); PG8_MMA(1, 1, At, B1); PG8_BAR; PG8_SCHED;
	s_add_i32 s55, 0, 0x18000
	s_add_i32 s56, 0, 0x1c000
	v_add_u32_e32 v12, s55, v215
	v_add_u32_e32 v28, s56, v215
	ds_read_b128 v[0:3], v12
	ds_read_b128 v[4:7], v12 offset:1024
	ds_read_b128 v[8:11], v12 offset:2048
	ds_read_b128 v[12:15], v12 offset:3072
	ds_read_b128 v[16:19], v28
	ds_read_b128 v[20:23], v28 offset:1024
	ds_read_b128 v[24:27], v28 offset:2048
	ds_read_b128 v[28:31], v28 offset:3072
	s_add_u32 s46, s46, 0x40000
	s_addc_u32 s47, s47, 0
	s_mov_b32 m0, s9
	v_lshl_add_u64 v[162:163], s[46:47], 0, v[190:191]
	ds_read_b128 v[218:221], v217 offset:32768
	ds_read_b128 v[222:225], v217 offset:33792
	ds_read_b128 v[226:229], v217 offset:34816
	ds_read_b128 v[230:233], v217 offset:35840
	ds_read_b128 v[234:237], v217 offset:36864
	ds_read_b128 v[238:241], v217 offset:37888
	ds_read_b128 v[242:245], v217 offset:38912
	ds_read_b128 v[246:249], v217 offset:39936
	global_load_lds_dwordx4 v[162:163], off
	v_lshl_add_u64 v[162:163], s[46:47], 0, v[186:187]
	s_mov_b32 m0, s28
	s_nop 0
	global_load_lds_dwordx4 v[162:163], off
	s_waitcnt vmcnt(8)
	s_waitcnt lgkmcnt(0)
	s_barrier
	s_setprio 1
	s_waitcnt lgkmcnt(0)
	v_mfma_scale_f32_16x16x128_f8f6f4 v[156:159], v[0:7], v[218:225], v[156:159], v213, v213 op_sel_hi:[0,0,0]
	v_mfma_scale_f32_16x16x128_f8f6f4 v[152:155], v[8:15], v[218:225], v[152:155], v213, v213 op_sel_hi:[0,0,0]
	v_mfma_scale_f32_16x16x128_f8f6f4 v[140:143], v[0:7], v[226:233], v[140:143], v213, v213 op_sel_hi:[0,0,0]
	v_mfma_scale_f32_16x16x128_f8f6f4 v[136:139], v[8:15], v[226:233], v[136:139], v213, v213 op_sel_hi:[0,0,0]
	v_mfma_scale_f32_16x16x128_f8f6f4 v[124:127], v[0:7], v[234:241], v[124:127], v213, v213 op_sel_hi:[0,0,0]
	v_mfma_scale_f32_16x16x128_f8f6f4 v[120:123], v[8:15], v[234:241], v[120:123], v213, v213 op_sel_hi:[0,0,0]
	v_mfma_scale_f32_16x16x128_f8f6f4 v[108:111], v[0:7], v[242:249], v[108:111], v213, v213 op_sel_hi:[0,0,0]
	v_mfma_scale_f32_16x16x128_f8f6f4 v[104:107], v[8:15], v[242:249], v[104:107], v213, v213 op_sel_hi:[0,0,0]
	s_setprio 0
	s_setprio 1
	v_mfma_scale_f32_16x16x128_f8f6f4 v[148:151], v[16:23], v[218:225], v[148:151], v213, v213 op_sel_hi:[0,0,0]
	v_mfma_scale_f32_16x16x128_f8f6f4 v[144:147], v[24:31], v[218:225], v[144:147], v213, v213 op_sel_hi:[0,0,0]
	v_mfma_scale_f32_16x16x128_f8f6f4 v[132:135], v[16:23], v[226:233], v[132:135], v213, v213 op_sel_hi:[0,0,0]
	v_mfma_scale_f32_16x16x128_f8f6f4 v[128:131], v[24:31], v[226:233], v[128:131], v213, v213 op_sel_hi:[0,0,0]
	v_mfma_scale_f32_16x16x128_f8f6f4 v[116:119], v[16:23], v[234:241], v[116:119], v213, v213 op_sel_hi:[0,0,0]
	v_mfma_scale_f32_16x16x128_f8f6f4 v[112:115], v[24:31], v[234:241], v[112:115], v213, v213 op_sel_hi:[0,0,0]
	v_mfma_scale_f32_16x16x128_f8f6f4 v[100:103], v[16:23], v[242:249], v[100:103], v213, v213 op_sel_hi:[0,0,0]
	v_mfma_scale_f32_16x16x128_f8f6f4 v[96:99], v[24:31], v[242:249], v[96:99], v213, v213 op_sel_hi:[0,0,0]
	s_setprio 0
	s_barrier
	s_add_i32 s46, s55, s22
	v_lshl_add_u64 v[162:163], v[196:197], 0, s[14:15]
	s_mov_b32 m0, s46
	ds_read_b128 v[218:221], v217 offset:49152
	ds_read_b128 v[222:225], v217 offset:50176
	ds_read_b128 v[226:229], v217 offset:51200
	ds_read_b128 v[230:233], v217 offset:52224
	ds_read_b128 v[234:237], v217 offset:53248
	ds_read_b128 v[238:241], v217 offset:54272
	ds_read_b128 v[242:245], v217 offset:55296
	ds_read_b128 v[246:249], v217 offset:56320
	global_load_lds_dwordx4 v[162:163], off
	s_add_i32 m0, s46, 0x2000
	s_add_u32 s44, s44, 0x40080
	v_lshl_add_u64 v[162:163], v[198:199], 0, s[14:15]
	s_addc_u32 s45, s45, 0
	s_add_i32 s46, s56, s22
	global_load_lds_dwordx4 v[162:163], off
	v_lshl_add_u64 v[162:163], s[44:45], 0, v[188:189]
	s_mov_b32 m0, s46
	s_nop 0
	global_load_lds_dwordx4 v[162:163], off
	v_lshl_add_u64 v[162:163], s[44:45], 0, v[184:185]
	s_add_i32 m0, s46, 0x2000
	s_nop 0
	global_load_lds_dwordx4 v[162:163], off
	v_lshl_add_u64 v[162:163], v[200:201], 0, s[14:15]
	s_mov_b32 m0, s29
	s_nop 0
	global_load_lds_dwordx4 v[162:163], off
	v_lshl_add_u64 v[162:163], v[202:203], 0, s[14:15]
	s_mov_b32 m0, s48
	s_nop 0
	global_load_lds_dwordx4 v[162:163], off
	s_waitcnt vmcnt(8)
	s_waitcnt lgkmcnt(0)
	s_barrier
	s_setprio 1
	s_waitcnt lgkmcnt(0)
	v_mfma_scale_f32_16x16x128_f8f6f4 v[92:95], v[0:7], v[218:225], v[92:95], v213, v213 op_sel_hi:[0,0,0]
	v_mfma_scale_f32_16x16x128_f8f6f4 v[88:91], v[8:15], v[218:225], v[88:91], v213, v213 op_sel_hi:[0,0,0]
	v_mfma_scale_f32_16x16x128_f8f6f4 v[76:79], v[0:7], v[226:233], v[76:79], v213, v213 op_sel_hi:[0,0,0]
	v_mfma_scale_f32_16x16x128_f8f6f4 v[72:75], v[8:15], v[226:233], v[72:75], v213, v213 op_sel_hi:[0,0,0]
	v_mfma_scale_f32_16x16x128_f8f6f4 v[60:63], v[0:7], v[234:241], v[60:63], v213, v213 op_sel_hi:[0,0,0]
	v_mfma_scale_f32_16x16x128_f8f6f4 v[56:59], v[8:15], v[234:241], v[56:59], v213, v213 op_sel_hi:[0,0,0]
	v_mfma_scale_f32_16x16x128_f8f6f4 v[44:47], v[0:7], v[242:249], v[44:47], v213, v213 op_sel_hi:[0,0,0]
	v_mfma_scale_f32_16x16x128_f8f6f4 v[40:43], v[8:15], v[242:249], v[40:43], v213, v213 op_sel_hi:[0,0,0]
	s_setprio 0
	s_setprio 1
	v_mfma_scale_f32_16x16x128_f8f6f4 v[84:87], v[16:23], v[218:225], v[84:87], v213, v213 op_sel_hi:[0,0,0]
	v_mfma_scale_f32_16x16x128_f8f6f4 v[80:83], v[24:31], v[218:225], v[80:83], v213, v213 op_sel_hi:[0,0,0]
	v_mfma_scale_f32_16x16x128_f8f6f4 v[68:71], v[16:23], v[226:233], v[68:71], v213, v213 op_sel_hi:[0,0,0]
	v_mfma_scale_f32_16x16x128_f8f6f4 v[64:67], v[24:31], v[226:233], v[64:67], v213, v213 op_sel_hi:[0,0,0]
	v_mfma_scale_f32_16x16x128_f8f6f4 v[52:55], v[16:23], v[234:241], v[52:55], v213, v213 op_sel_hi:[0,0,0]
	v_mfma_scale_f32_16x16x128_f8f6f4 v[48:51], v[24:31], v[234:241], v[48:51], v213, v213 op_sel_hi:[0,0,0]
	v_mfma_scale_f32_16x16x128_f8f6f4 v[36:39], v[16:23], v[242:249], v[36:39], v213, v213 op_sel_hi:[0,0,0]
	v_mfma_scale_f32_16x16x128_f8f6f4 v[32:35], v[24:31], v[242:249], v[32:35], v213, v213 op_sel_hi:[0,0,0]
	s_setprio 0
	s_barrier
	s_add_i32 s54, s54, 2
	s_add_u32 s40, s40, 0x100
	s_addc_u32 s41, s41, 0
	s_add_u32 s52, s52, 0x100
	s_addc_u32 s53, s53, 0
	s_cmp_gt_u32 s54, 13
	s_cbranch_scc0 .LBB0_1022
	s_branch .Lgk_after_1022

; #define PG8_STAGE(bufoff, gbase, voff) do { _Pragma("unroll") for (int _i = 0; _i < 2; ++_i) \
;         __builtin_amdgcn_global_load_lds((const unsigned*)((const char*)(gbase) + (voff)[_i]), (PG8_LAS unsigned*)(lds + (bufoff) + ldsw + _i * 8192), 16, 0, 0); } while (0)
; #define PG8_WAIT_V(n) asm volatile("s_waitcnt vmcnt(" #n ")" ::: "memory")
; #define PG8_WAIT_L(n) asm volatile("s_waitcnt lgkmcnt(" #n ")" ::: "memory")
; #define PG8_BAR __builtin_amdgcn_s_barrier()
; #define PG8_SCHED __builtin_amdgcn_sched_barrier(0)
; template <class Epi, class Sched, bool ALIGN_EPI = false, bool SP2 = false, bool F8 = false>
; __device__ __forceinline__ void gemm_phase(PG8_LAS unsigned char* lds, const Gemm g, const Sched& S, const Epi& E) {
;     ...
;         const bool has_next = S.next(ui + 1, nxt);
;         const char* nA = has_next ? (const char*)g.A + (size_t)nxt.pm * tstep : cA; const char* nB = has_next ? (const char*)g.Bt + (size_t)nxt.pn * tstep : cB;
;         for (int t = 0; t < nt; t += 2) {
;             const bool last = (t == nt - 2);
;             const char* a1 = cA + (size_t)(t + 1) * kstep;
;             const char* a2 = last ? nA : cA + (size_t)(t + 2) * kstep; const char* b2 = last ? nB : cB + (size_t)(t + 2) * kstep;
;             const char* a3 = a2 + kstep; const char* b3 = b2 + kstep;
;             if (last && has_next) S.a_ready(nxt);
;             if constexpr (SP2) {
;             PG8_LDB(B0, 0, 0); PG8_LDB(B1, 0, 1); PG8_SCHED; PG8_LDA(At, 0, 0); PG8_STAGE(PG8_SA(1, 1), a1 + hstep, voffA);
;             PG8_WAIT_V(8); PG8_WAIT_L(0); PG8_BAR; PG8_MMA(0, 0, At, B0); PG8_MMA(0, 1, At, B1); PG8_BAR; PG8_SCHED;
;             PG8_LDA(At, 0, 1); PG8_STAGE(PG8_SB(0, 0), b2, voffB); PG8_STAGE(PG8_SB(0, 1), b2 + hstep, voffB); PG8_STAGE(PG8_SA(0, 0), a2, voffA);
;             PG8_WAIT_V(8); PG8_WAIT_L(0); PG8_BAR; PG8_MMA(1, 0, At, B0); PG8_MMA(1, 1, At, B1); PG8_BAR; PG8_SCHED;
.LBB0_1101:
	s_ashr_i32 s17, s16, 31
	s_lshl_b64 s[36:37], s[16:17], 20
	v_readlane_b32 s40, v251, 7
	v_readlane_b32 s41, v251, 8
	s_add_u32 s36, s40, s36
	s_addc_u32 s37, s41, s37
	s_and_b64 s[40:41], s[38:39], exec
	s_cselect_b32 s17, s37, s43
	s_cselect_b32 s48, s36, s42
	s_ashr_i32 s11, s10, 31
	s_lshl_b64 s[40:41], s[10:11], 20
	v_readlane_b32 s11, v250, 22
	s_add_u32 s40, s11, s40
	v_readlane_b32 s11, v250, 23
	s_addc_u32 s41, s11, s41
	s_and_b64 s[46:47], s[38:39], exec
	s_cselect_b32 s11, s41, s45
	s_cselect_b32 s49, s40, s44
	s_add_u32 s42, s42, 0x80080
	s_addc_u32 s43, s43, 0
	s_add_u32 s50, s44, 0x100
	s_addc_u32 s51, s45, 0
	s_mov_b32 s52, -2
	s_add_u32 s44, s42, 0xfff80080
	s_addc_u32 s45, s43, -1
	s_add_i32 s53, 0, 0x10000
	s_cmp_eq_u32 s52, 28
	s_cselect_b32 s47, s17, s45
	s_cselect_b32 s46, s48, s44
	s_cselect_b32 s45, s11, s51
	s_cselect_b32 s44, s49, s50
	s_add_i32 s56, 0, 0x14000
	v_add_u32_e32 v154, s53, v139
	v_add_u32_e32 v158, s56, v139
	ds_read_b128 v[142:145], v154
	ds_read_b128 v[146:149], v154 offset:1024
	ds_read_b128 v[150:153], v154 offset:2048
	ds_read_b128 v[154:157], v154 offset:3072
	ds_read_b128 v[184:187], v158
	ds_read_b128 v[188:191], v158 offset:1024
	ds_read_b128 v[192:195], v158 offset:2048
	ds_read_b128 v[196:199], v158 offset:3072
	v_lshl_add_u64 v[158:159], s[42:43], 0, v[134:135]
	s_add_i32 m0, s9, 0xc000
	ds_read_b128 v[200:203], v141
	ds_read_b128 v[214:217], v141 offset:1024
	ds_read_b128 v[218:221], v141 offset:2048
	ds_read_b128 v[222:225], v141 offset:3072
	ds_read_b128 v[226:229], v141 offset:4096
	ds_read_b128 v[230:233], v141 offset:5120
	ds_read_b128 v[234:237], v141 offset:6144
	ds_read_b128 v[238:241], v141 offset:7168
	global_load_lds_dwordx4 v[158:159], off
	v_lshl_add_u64 v[158:159], s[42:43], 0, v[136:137]
	s_add_i32 m0, s9, 0xe000
	s_nop 0
	global_load_lds_dwordx4 v[158:159], off
	s_waitcnt vmcnt(8)
	s_waitcnt lgkmcnt(0)
	s_barrier
	s_setprio 1
	s_waitcnt lgkmcnt(0)
	v_mfma_f32_16x16x32_bf16 v[124:127], v[142:145], v[200:203], 0
	v_mfma_f32_16x16x32_bf16 v[120:123], v[150:153], v[200:203], 0
	v_mfma_f32_16x16x32_bf16 v[116:119], v[142:145], v[218:221], 0
	v_mfma_f32_16x16x32_bf16 v[112:115], v[150:153], v[218:221], 0
	v_mfma_f32_16x16x32_bf16 v[108:111], v[142:145], v[226:229], 0
	v_mfma_f32_16x16x32_bf16 v[100:103], v[150:153], v[226:229], 0
	v_mfma_f32_16x16x32_bf16 v[92:95], v[142:145], v[234:237], 0
	v_mfma_f32_16x16x32_bf16 v[84:87], v[150:153], v[234:237], 0
	v_mfma_f32_16x16x32_bf16 v[124:127], v[146:149], v[214:217], v[124:127]
	v_mfma_f32_16x16x32_bf16 v[120:123], v[154:157], v[214:217], v[120:123]
	v_mfma_f32_16x16x32_bf16 v[116:119], v[146:149], v[222:225], v[116:119]
	v_mfma_f32_16x16x32_bf16 v[112:115], v[154:157], v[222:225], v[112:115]
	v_mfma_f32_16x16x32_bf16 v[108:111], v[146:149], v[230:233], v[108:111]
	v_mfma_f32_16x16x32_bf16 v[100:103], v[154:157], v[230:233], v[100:103]
	v_mfma_f32_16x16x32_bf16 v[92:95], v[146:149], v[238:241], v[92:95]
	v_mfma_f32_16x16x32_bf16 v[84:87], v[154:157], v[238:241], v[84:87]
	s_setprio 0
	s_setprio 1
	v_mfma_f32_16x16x32_bf16 v[104:107], v[184:187], v[200:203], 0
	v_mfma_f32_16x16x32_bf16 v[96:99], v[192:195], v[200:203], 0
	v_mfma_f32_16x16x32_bf16 v[88:91], v[184:187], v[218:221], 0
	v_mfma_f32_16x16x32_bf16 v[80:83], v[192:195], v[218:221], 0
	v_mfma_f32_16x16x32_bf16 v[76:79], v[184:187], v[226:229], 0
	v_mfma_f32_16x16x32_bf16 v[72:75], v[192:195], v[226:229], 0
	v_mfma_f32_16x16x32_bf16 v[68:71], v[184:187], v[234:237], 0
	v_mfma_f32_16x16x32_bf16 v[64:67], v[192:195], v[234:237], 0
	v_mfma_f32_16x16x32_bf16 v[104:107], v[188:191], v[214:217], v[104:107]
	v_mfma_f32_16x16x32_bf16 v[96:99], v[196:199], v[214:217], v[96:99]
	v_mfma_f32_16x16x32_bf16 v[88:91], v[188:191], v[222:225], v[88:91]
	v_mfma_f32_16x16x32_bf16 v[80:83], v[196:199], v[222:225], v[80:83]
	v_mfma_f32_16x16x32_bf16 v[76:79], v[188:191], v[230:233], v[76:79]
	v_mfma_f32_16x16x32_bf16 v[72:75], v[196:199], v[230:233], v[72:75]
	v_mfma_f32_16x16x32_bf16 v[68:71], v[188:191], v[238:241], v[68:71]
	v_mfma_f32_16x16x32_bf16 v[64:67], v[196:199], v[238:241], v[64:67]
	s_setprio 0
	s_barrier
	s_add_i32 s53, s53, s8
	v_lshl_add_u64 v[158:159], s[44:45], 0, v[160:161]
	s_mov_b32 m0, s53
	ds_read_b128 v[200:203], v141 offset:16384
	ds_read_b128 v[214:217], v141 offset:17408
	ds_read_b128 v[218:221], v141 offset:18432
	ds_read_b128 v[222:225], v141 offset:19456
	ds_read_b128 v[226:229], v141 offset:20480
	ds_read_b128 v[230:233], v141 offset:21504
	ds_read_b128 v[234:237], v141 offset:22528
	ds_read_b128 v[238:241], v141 offset:23552
	global_load_lds_dwordx4 v[158:159], off
	s_add_i32 m0, s53, 0x2000
	s_add_u32 s54, s44, 0x80000
	v_lshl_add_u64 v[162:163], s[44:45], 0, v[128:129]
	s_addc_u32 s55, s45, 0
	s_add_i32 s53, s56, s8
	global_load_lds_dwordx4 v[162:163], off
	v_lshl_add_u64 v[242:243], s[54:55], 0, v[160:161]
	s_mov_b32 m0, s53
	v_lshl_add_u64 v[244:245], s[46:47], 0, v[130:131]
	global_load_lds_dwordx4 v[242:243], off
	v_lshl_add_u64 v[242:243], s[54:55], 0, v[128:129]
	s_add_i32 m0, s53, 0x2000
	s_nop 0
	global_load_lds_dwordx4 v[242:243], off
	v_lshl_add_u64 v[242:243], s[46:47], 0, v[132:133]
	s_mov_b32 m0, s9
	s_nop 0
	global_load_lds_dwordx4 v[242:243], off
	s_mov_b32 m0, s13
	s_nop 0
	global_load_lds_dwordx4 v[244:245], off
	s_waitcnt vmcnt(8)
	s_waitcnt lgkmcnt(0)
	s_barrier
; #define PG8_STAGE(bufoff, gbase, voff) do { _Pragma("unroll") for (int _i = 0; _i < 2; ++_i) \
;         __builtin_amdgcn_global_load_lds((const unsigned*)((const char*)(gbase) + (voff)[_i]), (PG8_LAS unsigned*)(lds + (bufoff) + ldsw + _i * 8192), 16, 0, 0); } while (0)
; #define PG8_WAIT_V(n) asm volatile("s_waitcnt vmcnt(" #n ")" ::: "memory")
; #define PG8_WAIT_L(n) asm volatile("s_waitcnt lgkmcnt(" #n ")" ::: "memory")
; #define PG8_BAR __builtin_amdgcn_s_barrier()
; #define PG8_SCHED __builtin_amdgcn_sched_barrier(0)
; template <class Epi, class Sched, bool ALIGN_EPI = false, bool SP2 = false, bool F8 = false>
; __device__ __forceinline__ void gemm_phase(PG8_LAS unsigned char* lds, const Gemm g, const Sched& S, const Epi& E) {
;     ...
;             PG8_WAIT_V(8); PG8_WAIT_L(0); PG8_BAR; PG8_MMA(1, 0, At, B0); PG8_MMA(1, 1, At, B1); PG8_BAR; PG8_SCHED;
;             PG8_LDB(B0, 1, 0); PG8_LDB(B1, 1, 1); PG8_SCHED; PG8_LDA(At, 1, 0); PG8_STAGE(PG8_SA(0, 1), a2 + hstep, voffA);
;             PG8_WAIT_V(8); PG8_WAIT_L(0); PG8_BAR; PG8_MMA(0, 0, At, B0); PG8_MMA(0, 1, At, B1); PG8_BAR; PG8_SCHED;
	s_setprio 1
	s_waitcnt lgkmcnt(0)
	v_mfma_f32_16x16x32_bf16 v[60:63], v[142:145], v[200:203], 0
	v_mfma_f32_16x16x32_bf16 v[56:59], v[150:153], v[200:203], 0
	v_mfma_f32_16x16x32_bf16 v[52:55], v[142:145], v[218:221], 0
	v_mfma_f32_16x16x32_bf16 v[48:51], v[150:153], v[218:221], 0
	v_mfma_f32_16x16x32_bf16 v[44:47], v[142:145], v[226:229], 0
	v_mfma_f32_16x16x32_bf16 v[36:39], v[150:153], v[226:229], 0
	v_mfma_f32_16x16x32_bf16 v[28:31], v[142:145], v[234:237], 0
	v_mfma_f32_16x16x32_bf16 v[20:23], v[150:153], v[234:237], 0
	v_mfma_f32_16x16x32_bf16 v[60:63], v[146:149], v[214:217], v[60:63]
	v_mfma_f32_16x16x32_bf16 v[56:59], v[154:157], v[214:217], v[56:59]
	v_mfma_f32_16x16x32_bf16 v[52:55], v[146:149], v[222:225], v[52:55]
	v_mfma_f32_16x16x32_bf16 v[48:51], v[154:157], v[222:225], v[48:51]
	v_mfma_f32_16x16x32_bf16 v[44:47], v[146:149], v[230:233], v[44:47]
	v_mfma_f32_16x16x32_bf16 v[36:39], v[154:157], v[230:233], v[36:39]
	v_mfma_f32_16x16x32_bf16 v[28:31], v[146:149], v[238:241], v[28:31]
	v_mfma_f32_16x16x32_bf16 v[20:23], v[154:157], v[238:241], v[20:23]
	s_setprio 0
	s_setprio 1
	v_mfma_f32_16x16x32_bf16 v[40:43], v[184:187], v[200:203], 0
	v_mfma_f32_16x16x32_bf16 v[32:35], v[192:195], v[200:203], 0
	v_mfma_f32_16x16x32_bf16 v[24:27], v[184:187], v[218:221], 0
	v_mfma_f32_16x16x32_bf16 v[16:19], v[192:195], v[218:221], 0
	v_mfma_f32_16x16x32_bf16 v[12:15], v[184:187], v[226:229], 0
	v_mfma_f32_16x16x32_bf16 v[8:11], v[192:195], v[226:229], 0
	v_mfma_f32_16x16x32_bf16 v[4:7], v[184:187], v[234:237], 0
	v_mfma_f32_16x16x32_bf16 v[0:3], v[192:195], v[234:237], 0
	v_mfma_f32_16x16x32_bf16 v[40:43], v[188:191], v[214:217], v[40:43]
	v_mfma_f32_16x16x32_bf16 v[32:35], v[196:199], v[214:217], v[32:35]
	v_mfma_f32_16x16x32_bf16 v[24:27], v[188:191], v[222:225], v[24:27]
	v_mfma_f32_16x16x32_bf16 v[16:19], v[196:199], v[222:225], v[16:19]
	v_mfma_f32_16x16x32_bf16 v[12:15], v[188:191], v[230:233], v[12:15]
	v_mfma_f32_16x16x32_bf16 v[8:11], v[196:199], v[230:233], v[8:11]
	v_mfma_f32_16x16x32_bf16 v[4:7], v[188:191], v[238:241], v[4:7]
	v_mfma_f32_16x16x32_bf16 v[0:3], v[196:199], v[238:241], v[0:3]
	s_setprio 0
	s_barrier
	s_add_i32 s53, 0, 0x18000
	s_add_i32 s54, 0, 0x1c000
	v_add_u32_e32 v154, s53, v139
	v_add_u32_e32 v196, s54, v139
	ds_read_b128 v[142:145], v154
	ds_read_b128 v[146:149], v154 offset:1024
	ds_read_b128 v[150:153], v154 offset:2048
	ds_read_b128 v[154:157], v154 offset:3072
	ds_read_b128 v[184:187], v196
	ds_read_b128 v[188:191], v196 offset:1024
	ds_read_b128 v[192:195], v196 offset:2048
	ds_read_b128 v[196:199], v196 offset:3072
	s_add_u32 s46, s46, 0x80000
	s_addc_u32 s47, s47, 0
	s_mov_b32 m0, s19
	v_lshl_add_u64 v[246:247], s[46:47], 0, v[132:133]
	ds_read_b128 v[200:203], v141 offset:32768
	ds_read_b128 v[214:217], v141 offset:33792
	ds_read_b128 v[218:221], v141 offset:34816
	ds_read_b128 v[222:225], v141 offset:35840
	ds_read_b128 v[226:229], v141 offset:36864
	ds_read_b128 v[230:233], v141 offset:37888
	ds_read_b128 v[234:237], v141 offset:38912
	ds_read_b128 v[238:241], v141 offset:39936
	global_load_lds_dwordx4 v[246:247], off
	v_lshl_add_u64 v[246:247], s[46:47], 0, v[130:131]
	s_mov_b32 m0, s22
	s_nop 0
	global_load_lds_dwordx4 v[246:247], off
	s_waitcnt vmcnt(8)
	s_waitcnt lgkmcnt(0)
	s_barrier
	s_setprio 1
	s_waitcnt lgkmcnt(0)
	v_mfma_f32_16x16x32_bf16 v[124:127], v[142:145], v[200:203], v[124:127]
	v_mfma_f32_16x16x32_bf16 v[120:123], v[150:153], v[200:203], v[120:123]
	v_mfma_f32_16x16x32_bf16 v[116:119], v[142:145], v[218:221], v[116:119]
	v_mfma_f32_16x16x32_bf16 v[112:115], v[150:153], v[218:221], v[112:115]
	v_mfma_f32_16x16x32_bf16 v[108:111], v[142:145], v[226:229], v[108:111]
	v_mfma_f32_16x16x32_bf16 v[100:103], v[150:153], v[226:229], v[100:103]
	v_mfma_f32_16x16x32_bf16 v[92:95], v[142:145], v[234:237], v[92:95]
	v_mfma_f32_16x16x32_bf16 v[84:87], v[150:153], v[234:237], v[84:87]
	v_mfma_f32_16x16x32_bf16 v[124:127], v[146:149], v[214:217], v[124:127]
	v_mfma_f32_16x16x32_bf16 v[120:123], v[154:157], v[214:217], v[120:123]
	v_mfma_f32_16x16x32_bf16 v[116:119], v[146:149], v[222:225], v[116:119]
	v_mfma_f32_16x16x32_bf16 v[112:115], v[154:157], v[222:225], v[112:115]
	v_mfma_f32_16x16x32_bf16 v[108:111], v[146:149], v[230:233], v[108:111]
	v_mfma_f32_16x16x32_bf16 v[100:103], v[154:157], v[230:233], v[100:103]
	v_mfma_f32_16x16x32_bf16 v[92:95], v[146:149], v[238:241], v[92:95]
	v_mfma_f32_16x16x32_bf16 v[84:87], v[154:157], v[238:241], v[84:87]
	s_setprio 0
	s_setprio 1
	v_mfma_f32_16x16x32_bf16 v[104:107], v[184:187], v[200:203], v[104:107]
	v_mfma_f32_16x16x32_bf16 v[96:99], v[192:195], v[200:203], v[96:99]
	v_mfma_f32_16x16x32_bf16 v[88:91], v[184:187], v[218:221], v[88:91]
	v_mfma_f32_16x16x32_bf16 v[80:83], v[192:195], v[218:221], v[80:83]
	v_mfma_f32_16x16x32_bf16 v[76:79], v[184:187], v[226:229], v[76:79]
	v_mfma_f32_16x16x32_bf16 v[72:75], v[192:195], v[226:229], v[72:75]
	v_mfma_f32_16x16x32_bf16 v[68:71], v[184:187], v[234:237], v[68:71]
	v_mfma_f32_16x16x32_bf16 v[64:67], v[192:195], v[234:237], v[64:67]
	v_mfma_f32_16x16x32_bf16 v[104:107], v[188:191], v[214:217], v[104:107]
	v_mfma_f32_16x16x32_bf16 v[96:99], v[196:199], v[214:217], v[96:99]
	v_mfma_f32_16x16x32_bf16 v[88:91], v[188:191], v[222:225], v[88:91]
	v_mfma_f32_16x16x32_bf16 v[80:83], v[196:199], v[222:225], v[80:83]
	v_mfma_f32_16x16x32_bf16 v[76:79], v[188:191], v[230:233], v[76:79]
	v_mfma_f32_16x16x32_bf16 v[72:75], v[196:199], v[230:233], v[72:75]
	v_mfma_f32_16x16x32_bf16 v[68:71], v[188:191], v[238:241], v[68:71]
	v_mfma_f32_16x16x32_bf16 v[64:67], v[196:199], v[238:241], v[64:67]
	s_setprio 0
	s_barrier
; #define PG8_STAGE(bufoff, gbase, voff) do { _Pragma("unroll") for (int _i = 0; _i < 2; ++_i) \
;         __builtin_amdgcn_global_load_lds((const unsigned*)((const char*)(gbase) + (voff)[_i]), (PG8_LAS unsigned*)(lds + (bufoff) + ldsw + _i * 8192), 16, 0, 0); } while (0)
; #define PG8_WAIT_V(n) asm volatile("s_waitcnt vmcnt(" #n ")" ::: "memory")
; #define PG8_WAIT_L(n) asm volatile("s_waitcnt lgkmcnt(" #n ")" ::: "memory")
; #define PG8_BAR __builtin_amdgcn_s_barrier()
; #define PG8_SCHED __builtin_amdgcn_sched_barrier(0)
; template <class Epi, class Sched, bool ALIGN_EPI = false, bool SP2 = false, bool F8 = false>
; __device__ __forceinline__ void gemm_phase(PG8_LAS unsigned char* lds, const Gemm g, const Sched& S, const Epi& E) {
;     ...
;             PG8_LDA(At, 1, 1); PG8_STAGE(PG8_SB(1, 0), b3, voffB); PG8_STAGE(PG8_SB(1, 1), b3 + hstep, voffB); PG8_STAGE(PG8_SA(1, 0), a3, voffA);
;             PG8_WAIT_V(8); PG8_WAIT_L(0); PG8_BAR; PG8_MMA(1, 0, At, B0); PG8_MMA(1, 1, At, B1); PG8_BAR; PG8_SCHED;
	s_add_i32 s46, s53, s8
	v_lshl_add_u64 v[158:159], v[158:159], 0, s[14:15]
	s_mov_b32 m0, s46
	ds_read_b128 v[200:203], v141 offset:49152
	ds_read_b128 v[214:217], v141 offset:50176
	ds_read_b128 v[218:221], v141 offset:51200
	ds_read_b128 v[222:225], v141 offset:52224
	ds_read_b128 v[226:229], v141 offset:53248
	ds_read_b128 v[230:233], v141 offset:54272
	ds_read_b128 v[234:237], v141 offset:55296
	ds_read_b128 v[238:241], v141 offset:56320
	global_load_lds_dwordx4 v[158:159], off
	s_add_i32 m0, s46, 0x2000
	s_add_u32 s44, s44, 0x80080
	v_lshl_add_u64 v[158:159], v[162:163], 0, s[14:15]
	s_addc_u32 s45, s45, 0
	s_add_i32 s46, s54, s8
	global_load_lds_dwordx4 v[158:159], off
	v_lshl_add_u64 v[158:159], s[44:45], 0, v[160:161]
	s_mov_b32 m0, s46
	s_nop 0
	global_load_lds_dwordx4 v[158:159], off
	v_lshl_add_u64 v[158:159], s[44:45], 0, v[128:129]
	s_add_i32 m0, s46, 0x2000
	s_nop 0
	global_load_lds_dwordx4 v[158:159], off
	v_lshl_add_u64 v[158:159], v[242:243], 0, s[14:15]
	s_mov_b32 m0, s23
	s_nop 0
	global_load_lds_dwordx4 v[158:159], off
	v_lshl_add_u64 v[158:159], v[244:245], 0, s[14:15]
	s_mov_b32 m0, s28
	s_nop 0
	global_load_lds_dwordx4 v[158:159], off
	s_waitcnt vmcnt(8)
	s_waitcnt lgkmcnt(0)
	s_barrier
	s_setprio 1
	s_waitcnt lgkmcnt(0)
	v_mfma_f32_16x16x32_bf16 v[60:63], v[142:145], v[200:203], v[60:63]
	v_mfma_f32_16x16x32_bf16 v[56:59], v[150:153], v[200:203], v[56:59]
	v_mfma_f32_16x16x32_bf16 v[52:55], v[142:145], v[218:221], v[52:55]
	v_mfma_f32_16x16x32_bf16 v[48:51], v[150:153], v[218:221], v[48:51]
	v_mfma_f32_16x16x32_bf16 v[44:47], v[142:145], v[226:229], v[44:47]
	v_mfma_f32_16x16x32_bf16 v[36:39], v[150:153], v[226:229], v[36:39]
	v_mfma_f32_16x16x32_bf16 v[28:31], v[142:145], v[234:237], v[28:31]
	v_mfma_f32_16x16x32_bf16 v[20:23], v[150:153], v[234:237], v[20:23]
	v_mfma_f32_16x16x32_bf16 v[60:63], v[146:149], v[214:217], v[60:63]
	v_mfma_f32_16x16x32_bf16 v[56:59], v[154:157], v[214:217], v[56:59]
	v_mfma_f32_16x16x32_bf16 v[52:55], v[146:149], v[222:225], v[52:55]
	v_mfma_f32_16x16x32_bf16 v[48:51], v[154:157], v[222:225], v[48:51]
	v_mfma_f32_16x16x32_bf16 v[44:47], v[146:149], v[230:233], v[44:47]
	v_mfma_f32_16x16x32_bf16 v[36:39], v[154:157], v[230:233], v[36:39]
	v_mfma_f32_16x16x32_bf16 v[28:31], v[146:149], v[238:241], v[28:31]
	v_mfma_f32_16x16x32_bf16 v[20:23], v[154:157], v[238:241], v[20:23]
	s_setprio 0
	s_setprio 1
	v_mfma_f32_16x16x32_bf16 v[40:43], v[184:187], v[200:203], v[40:43]
	v_mfma_f32_16x16x32_bf16 v[32:35], v[192:195], v[200:203], v[32:35]
	v_mfma_f32_16x16x32_bf16 v[24:27], v[184:187], v[218:221], v[24:27]
	v_mfma_f32_16x16x32_bf16 v[16:19], v[192:195], v[218:221], v[16:19]
	v_mfma_f32_16x16x32_bf16 v[12:15], v[184:187], v[226:229], v[12:15]
	v_mfma_f32_16x16x32_bf16 v[8:11], v[192:195], v[226:229], v[8:11]
	v_mfma_f32_16x16x32_bf16 v[4:7], v[184:187], v[234:237], v[4:7]
	v_mfma_f32_16x16x32_bf16 v[0:3], v[192:195], v[234:237], v[0:3]
	v_mfma_f32_16x16x32_bf16 v[40:43], v[188:191], v[214:217], v[40:43]
	v_mfma_f32_16x16x32_bf16 v[32:35], v[196:199], v[214:217], v[32:35]
	v_mfma_f32_16x16x32_bf16 v[24:27], v[188:191], v[222:225], v[24:27]
	v_mfma_f32_16x16x32_bf16 v[16:19], v[196:199], v[222:225], v[16:19]
	v_mfma_f32_16x16x32_bf16 v[12:15], v[188:191], v[230:233], v[12:15]
	v_mfma_f32_16x16x32_bf16 v[8:11], v[196:199], v[230:233], v[8:11]
	v_mfma_f32_16x16x32_bf16 v[4:7], v[188:191], v[238:241], v[4:7]
	v_mfma_f32_16x16x32_bf16 v[0:3], v[196:199], v[238:241], v[0:3]
	s_setprio 0
	s_barrier
	s_add_i32 s52, s52, 2
	s_add_u32 s42, s42, 0x100
	s_addc_u32 s43, s43, 0
	s_add_u32 s50, s50, 0x100
	s_addc_u32 s51, s51, 0
	s_cmp_gt_u32 s52, 29
	s_cbranch_scc0 .LBB0_1102
	s_branch .Lgk_after_1102

; #define PG8_STAGE(bufoff, gbase, voff) do { _Pragma("unroll") for (int _i = 0; _i < 2; ++_i) \
;         __builtin_amdgcn_global_load_lds((const unsigned*)((const char*)(gbase) + (voff)[_i]), (PG8_LAS unsigned*)(lds + (bufoff) + ldsw + _i * 8192), 16, 0, 0); } while (0)
; #define PG8_WAIT_V(n) asm volatile("s_waitcnt vmcnt(" #n ")" ::: "memory")
; #define PG8_WAIT_L(n) asm volatile("s_waitcnt lgkmcnt(" #n ")" ::: "memory")
; #define PG8_BAR __builtin_amdgcn_s_barrier()
; #define PG8_SCHED __builtin_amdgcn_sched_barrier(0)
; template <class Epi, class Sched, bool ALIGN_EPI = false, bool SP2 = false, bool F8 = false>
; __device__ __forceinline__ void gemm_phase(PG8_LAS unsigned char* lds, const Gemm g, const Sched& S, const Epi& E) {
;     ...
;         const bool has_next = S.next(ui + 1, nxt);
;         const char* nA = has_next ? (const char*)g.A + (size_t)nxt.pm * tstep : cA; const char* nB = has_next ? (const char*)g.Bt + (size_t)nxt.pn * tstep : cB;
;         for (int t = 0; t < nt; t += 2) {
;             const bool last = (t == nt - 2);
;             const char* a1 = cA + (size_t)(t + 1) * kstep;
;             const char* a2 = last ? nA : cA + (size_t)(t + 2) * kstep; const char* b2 = last ? nB : cB + (size_t)(t + 2) * kstep;
;             const char* a3 = a2 + kstep; const char* b3 = b2 + kstep;
;             if (last && has_next) S.a_ready(nxt);
;             if constexpr (SP2) {
;             PG8_LDB(B0, 0, 0); PG8_LDB(B1, 0, 1); PG8_SCHED; PG8_LDA(At, 0, 0); PG8_STAGE(PG8_SA(1, 1), a1 + hstep, voffA);
;             PG8_WAIT_V(8); PG8_WAIT_L(0); PG8_BAR; PG8_MMA(0, 0, At, B0); PG8_MMA(0, 1, At, B1); PG8_BAR; PG8_SCHED;
;             PG8_LDA(At, 0, 1); PG8_STAGE(PG8_SB(0, 0), b2, voffB); PG8_STAGE(PG8_SB(0, 1), b2 + hstep, voffB); PG8_STAGE(PG8_SA(0, 0), a2, voffA);
;             PG8_WAIT_V(8); PG8_WAIT_L(0); PG8_BAR; PG8_MMA(1, 0, At, B0); PG8_MMA(1, 1, At, B1); PG8_BAR; PG8_SCHED;
.LBB0_1121:
	s_ashr_i32 s43, s42, 31
	s_lshl_b64 s[28:29], s[42:43], 19
	v_readlane_b32 s19, v253, 59
	s_add_u32 s44, s19, s28
	v_readlane_b32 s19, v253, 60
	s_addc_u32 s45, s19, s29
	s_and_b64 s[28:29], s[38:39], exec
	s_cselect_b32 s19, s45, s11
	s_cselect_b32 s23, s44, s10
	s_ashr_i32 s41, s40, 31
	s_lshl_b64 s[28:29], s[40:41], 19
	s_add_u32 s46, s22, s28
	s_addc_u32 s47, s50, s29
	s_and_b64 s[28:29], s[38:39], exec
	s_cselect_b32 s28, s47, s37
	s_cselect_b32 s29, s46, s36
	s_add_u32 s10, s10, 0x40080
	s_addc_u32 s11, s11, 0
	s_add_u32 s34, s36, 0x100
	s_addc_u32 s35, s37, 0
	s_mov_b32 s41, -2
	s_add_u32 s36, s10, 0xfffc0080
	s_addc_u32 s37, s11, -1
	s_add_i32 s43, 0, 0x10000
	s_cmp_eq_u32 s41, 12
	s_cselect_b32 s49, s19, s37
	s_cselect_b32 s48, s23, s36
	s_cselect_b32 s37, s28, s35
	s_cselect_b32 s36, s29, s34
	s_add_i32 s56, 0, 0x14000
	v_add_u32_e32 v0, s43, v213
	v_add_u32_e32 v12, s56, v213
	ds_read_b128 v[16:19], v0
	ds_read_b128 v[20:23], v0 offset:1024
	ds_read_b128 v[24:27], v0 offset:2048
	ds_read_b128 v[28:31], v0 offset:3072
	ds_read_b128 v[0:3], v12
	ds_read_b128 v[4:7], v12 offset:1024
	ds_read_b128 v[8:11], v12 offset:2048
	ds_read_b128 v[12:15], v12 offset:3072
	v_lshl_add_u64 v[162:163], s[10:11], 0, v[190:191]
	s_add_i32 m0, s51, 0xc000
	ds_read_b128 v[194:197], v215
	ds_read_b128 v[198:201], v215 offset:1024
	ds_read_b128 v[216:219], v215 offset:2048
	ds_read_b128 v[220:223], v215 offset:3072
	ds_read_b128 v[224:227], v215 offset:4096
	ds_read_b128 v[228:231], v215 offset:5120
	ds_read_b128 v[232:235], v215 offset:6144
	ds_read_b128 v[236:239], v215 offset:7168
	global_load_lds_dwordx4 v[162:163], off
	v_lshl_add_u64 v[162:163], s[10:11], 0, v[192:193]
	s_add_i32 m0, s51, 0xe000
	s_nop 0
	global_load_lds_dwordx4 v[162:163], off
	s_waitcnt vmcnt(8)
	s_waitcnt lgkmcnt(0)
	s_barrier
	s_setprio 1
	s_waitcnt lgkmcnt(0)
	v_mfma_scale_f32_16x16x128_f8f6f4 v[156:159], v[16:23], v[194:201], 0, v202, v202 op_sel_hi:[0,0,0]
	v_mfma_scale_f32_16x16x128_f8f6f4 v[152:155], v[24:31], v[194:201], 0, v202, v202 op_sel_hi:[0,0,0]
	v_mfma_scale_f32_16x16x128_f8f6f4 v[140:143], v[16:23], v[216:223], 0, v202, v202 op_sel_hi:[0,0,0]
	v_mfma_scale_f32_16x16x128_f8f6f4 v[136:139], v[24:31], v[216:223], 0, v202, v202 op_sel_hi:[0,0,0]
	v_mfma_scale_f32_16x16x128_f8f6f4 v[124:127], v[16:23], v[224:231], 0, v202, v202 op_sel_hi:[0,0,0]
	v_mfma_scale_f32_16x16x128_f8f6f4 v[120:123], v[24:31], v[224:231], 0, v202, v202 op_sel_hi:[0,0,0]
	v_mfma_scale_f32_16x16x128_f8f6f4 v[108:111], v[16:23], v[232:239], 0, v202, v202 op_sel_hi:[0,0,0]
	v_mfma_scale_f32_16x16x128_f8f6f4 v[104:107], v[24:31], v[232:239], 0, v202, v202 op_sel_hi:[0,0,0]
	s_setprio 0
	s_setprio 1
	v_mfma_scale_f32_16x16x128_f8f6f4 v[148:151], v[0:7], v[194:201], 0, v202, v202 op_sel_hi:[0,0,0]
	v_mfma_scale_f32_16x16x128_f8f6f4 v[144:147], v[8:15], v[194:201], 0, v202, v202 op_sel_hi:[0,0,0]
	v_mfma_scale_f32_16x16x128_f8f6f4 v[132:135], v[0:7], v[216:223], 0, v202, v202 op_sel_hi:[0,0,0]
	v_mfma_scale_f32_16x16x128_f8f6f4 v[128:131], v[8:15], v[216:223], 0, v202, v202 op_sel_hi:[0,0,0]
	v_mfma_scale_f32_16x16x128_f8f6f4 v[116:119], v[0:7], v[224:231], 0, v202, v202 op_sel_hi:[0,0,0]
	v_mfma_scale_f32_16x16x128_f8f6f4 v[112:115], v[8:15], v[224:231], 0, v202, v202 op_sel_hi:[0,0,0]
	v_mfma_scale_f32_16x16x128_f8f6f4 v[100:103], v[0:7], v[232:239], 0, v202, v202 op_sel_hi:[0,0,0]
	v_mfma_scale_f32_16x16x128_f8f6f4 v[96:99], v[8:15], v[232:239], 0, v202, v202 op_sel_hi:[0,0,0]
	s_setprio 0
	s_barrier
	s_add_i32 s43, s43, s13
	v_lshl_add_u64 v[194:195], s[36:37], 0, v[160:161]
	s_mov_b32 m0, s43
	ds_read_b128 v[216:219], v215 offset:16384
	ds_read_b128 v[220:223], v215 offset:17408
	ds_read_b128 v[224:227], v215 offset:18432
	ds_read_b128 v[228:231], v215 offset:19456
	ds_read_b128 v[232:235], v215 offset:20480
	ds_read_b128 v[236:239], v215 offset:21504
	ds_read_b128 v[240:243], v215 offset:22528
	ds_read_b128 v[244:247], v215 offset:23552
	global_load_lds_dwordx4 v[194:195], off
	s_add_i32 m0, s43, 0x2000
	s_add_u32 s60, s36, 0x40000
	v_lshl_add_u64 v[196:197], s[36:37], 0, v[184:185]
	s_addc_u32 s61, s37, 0
	s_add_i32 s43, s56, s13
	global_load_lds_dwordx4 v[196:197], off
	v_lshl_add_u64 v[162:163], s[60:61], 0, v[160:161]
	s_mov_b32 m0, s43
	v_lshl_add_u64 v[198:199], s[48:49], 0, v[188:189]
	global_load_lds_dwordx4 v[162:163], off
	v_lshl_add_u64 v[162:163], s[60:61], 0, v[184:185]
	s_add_i32 m0, s43, 0x2000
	v_lshl_add_u64 v[200:201], s[48:49], 0, v[186:187]
	global_load_lds_dwordx4 v[162:163], off
	s_mov_b32 m0, s51
	s_nop 0
	global_load_lds_dwordx4 v[198:199], off
	s_mov_b32 m0, s52
	s_nop 0
	global_load_lds_dwordx4 v[200:201], off
	s_waitcnt vmcnt(8)
	s_waitcnt lgkmcnt(0)
	s_barrier
	s_setprio 1
	s_waitcnt lgkmcnt(0)
	v_mfma_scale_f32_16x16x128_f8f6f4 v[92:95], v[16:23], v[216:223], 0, v202, v202 op_sel_hi:[0,0,0]
	v_mfma_scale_f32_16x16x128_f8f6f4 v[88:91], v[24:31], v[216:223], 0, v202, v202 op_sel_hi:[0,0,0]
	v_mfma_scale_f32_16x16x128_f8f6f4 v[76:79], v[16:23], v[224:231], 0, v202, v202 op_sel_hi:[0,0,0]
	v_mfma_scale_f32_16x16x128_f8f6f4 v[72:75], v[24:31], v[224:231], 0, v202, v202 op_sel_hi:[0,0,0]
	v_mfma_scale_f32_16x16x128_f8f6f4 v[60:63], v[16:23], v[232:239], 0, v202, v202 op_sel_hi:[0,0,0]
	v_mfma_scale_f32_16x16x128_f8f6f4 v[56:59], v[24:31], v[232:239], 0, v202, v202 op_sel_hi:[0,0,0]
	v_mfma_scale_f32_16x16x128_f8f6f4 v[44:47], v[16:23], v[240:247], 0, v202, v202 op_sel_hi:[0,0,0]
	v_mfma_scale_f32_16x16x128_f8f6f4 v[40:43], v[24:31], v[240:247], 0, v202, v202 op_sel_hi:[0,0,0]
	s_setprio 0
	s_setprio 1
	v_mfma_scale_f32_16x16x128_f8f6f4 v[84:87], v[0:7], v[216:223], 0, v202, v202 op_sel_hi:[0,0,0]
	v_mfma_scale_f32_16x16x128_f8f6f4 v[80:83], v[8:15], v[216:223], 0, v202, v202 op_sel_hi:[0,0,0]
	v_mfma_scale_f32_16x16x128_f8f6f4 v[68:71], v[0:7], v[224:231], 0, v202, v202 op_sel_hi:[0,0,0]
	v_mfma_scale_f32_16x16x128_f8f6f4 v[64:67], v[8:15], v[224:231], 0, v202, v202 op_sel_hi:[0,0,0]
	v_mfma_scale_f32_16x16x128_f8f6f4 v[52:55], v[0:7], v[232:239], 0, v202, v202 op_sel_hi:[0,0,0]
	v_mfma_scale_f32_16x16x128_f8f6f4 v[48:51], v[8:15], v[232:239], 0, v202, v202 op_sel_hi:[0,0,0]
	v_mfma_scale_f32_16x16x128_f8f6f4 v[36:39], v[0:7], v[240:247], 0, v202, v202 op_sel_hi:[0,0,0]
	v_mfma_scale_f32_16x16x128_f8f6f4 v[32:35], v[8:15], v[240:247], 0, v202, v202 op_sel_hi:[0,0,0]
	s_setprio 0
	s_barrier
; #define PG8_STAGE(bufoff, gbase, voff) do { _Pragma("unroll") for (int _i = 0; _i < 2; ++_i) \
;         __builtin_amdgcn_global_load_lds((const unsigned*)((const char*)(gbase) + (voff)[_i]), (PG8_LAS unsigned*)(lds + (bufoff) + ldsw + _i * 8192), 16, 0, 0); } while (0)
; #define PG8_WAIT_V(n) asm volatile("s_waitcnt vmcnt(" #n ")" ::: "memory")
; #define PG8_WAIT_L(n) asm volatile("s_waitcnt lgkmcnt(" #n ")" ::: "memory")
; #define PG8_BAR __builtin_amdgcn_s_barrier()
; #define PG8_SCHED __builtin_amdgcn_sched_barrier(0)
; template <class Epi, class Sched, bool ALIGN_EPI = false, bool SP2 = false, bool F8 = false>
; __device__ __forceinline__ void gemm_phase(PG8_LAS unsigned char* lds, const Gemm g, const Sched& S, const Epi& E) {
;     ...
;             PG8_LDB(B0, 1, 0); PG8_LDB(B1, 1, 1); PG8_SCHED; PG8_LDA(At, 1, 0); PG8_STAGE(PG8_SA(0, 1), a2 + hstep, voffA);
;             PG8_WAIT_V(8); PG8_WAIT_L(0); PG8_BAR; PG8_MMA(0, 0, At, B0); PG8_MMA(0, 1, At, B1); PG8_BAR; PG8_SCHED;
;             PG8_LDA(At, 1, 1); PG8_STAGE(PG8_SB(1, 0), b3, voffB); PG8_STAGE(PG8_SB(1, 1), b3 + hstep, voffB); PG8_STAGE(PG8_SA(1, 0), a3, voffA);
;             PG8_WAIT_V(8); PG8_WAIT_L(0); PG8_BAR; PG8_MMA(1, 0, At, B0); PG8_MMA(1, 1, At, B1); PG8_BAR; PG8_SCHED;
	s_add_i32 s43, 0, 0x18000
	s_add_i32 s56, 0, 0x1c000
	v_add_u32_e32 v12, s43, v213
	v_add_u32_e32 v28, s56, v213
	ds_read_b128 v[0:3], v12
	ds_read_b128 v[4:7], v12 offset:1024
	ds_read_b128 v[8:11], v12 offset:2048
	ds_read_b128 v[12:15], v12 offset:3072
	ds_read_b128 v[16:19], v28
	ds_read_b128 v[20:23], v28 offset:1024
	ds_read_b128 v[24:27], v28 offset:2048
	ds_read_b128 v[28:31], v28 offset:3072
	s_add_u32 s48, s48, 0x40000
	s_addc_u32 s49, s49, 0
	s_mov_b32 m0, s53
	v_lshl_add_u64 v[162:163], s[48:49], 0, v[188:189]
	ds_read_b128 v[216:219], v215 offset:32768
	ds_read_b128 v[220:223], v215 offset:33792
	ds_read_b128 v[224:227], v215 offset:34816
	ds_read_b128 v[228:231], v215 offset:35840
	ds_read_b128 v[232:235], v215 offset:36864
	ds_read_b128 v[236:239], v215 offset:37888
	ds_read_b128 v[240:243], v215 offset:38912
	ds_read_b128 v[244:247], v215 offset:39936
	global_load_lds_dwordx4 v[162:163], off
	v_lshl_add_u64 v[162:163], s[48:49], 0, v[186:187]
	s_mov_b32 m0, s54
	s_nop 0
	global_load_lds_dwordx4 v[162:163], off
	s_waitcnt vmcnt(8)
	s_waitcnt lgkmcnt(0)
	s_barrier
	s_setprio 1
	s_waitcnt lgkmcnt(0)
	v_mfma_scale_f32_16x16x128_f8f6f4 v[156:159], v[0:7], v[216:223], v[156:159], v202, v202 op_sel_hi:[0,0,0]
	v_mfma_scale_f32_16x16x128_f8f6f4 v[152:155], v[8:15], v[216:223], v[152:155], v202, v202 op_sel_hi:[0,0,0]
	v_mfma_scale_f32_16x16x128_f8f6f4 v[140:143], v[0:7], v[224:231], v[140:143], v202, v202 op_sel_hi:[0,0,0]
	v_mfma_scale_f32_16x16x128_f8f6f4 v[136:139], v[8:15], v[224:231], v[136:139], v202, v202 op_sel_hi:[0,0,0]
	v_mfma_scale_f32_16x16x128_f8f6f4 v[124:127], v[0:7], v[232:239], v[124:127], v202, v202 op_sel_hi:[0,0,0]
	v_mfma_scale_f32_16x16x128_f8f6f4 v[120:123], v[8:15], v[232:239], v[120:123], v202, v202 op_sel_hi:[0,0,0]
	v_mfma_scale_f32_16x16x128_f8f6f4 v[108:111], v[0:7], v[240:247], v[108:111], v202, v202 op_sel_hi:[0,0,0]
	v_mfma_scale_f32_16x16x128_f8f6f4 v[104:107], v[8:15], v[240:247], v[104:107], v202, v202 op_sel_hi:[0,0,0]
	s_setprio 0
	s_setprio 1
	v_mfma_scale_f32_16x16x128_f8f6f4 v[148:151], v[16:23], v[216:223], v[148:151], v202, v202 op_sel_hi:[0,0,0]
	v_mfma_scale_f32_16x16x128_f8f6f4 v[144:147], v[24:31], v[216:223], v[144:147], v202, v202 op_sel_hi:[0,0,0]
	v_mfma_scale_f32_16x16x128_f8f6f4 v[132:135], v[16:23], v[224:231], v[132:135], v202, v202 op_sel_hi:[0,0,0]
	v_mfma_scale_f32_16x16x128_f8f6f4 v[128:131], v[24:31], v[224:231], v[128:131], v202, v202 op_sel_hi:[0,0,0]
	v_mfma_scale_f32_16x16x128_f8f6f4 v[116:119], v[16:23], v[232:239], v[116:119], v202, v202 op_sel_hi:[0,0,0]
	v_mfma_scale_f32_16x16x128_f8f6f4 v[112:115], v[24:31], v[232:239], v[112:115], v202, v202 op_sel_hi:[0,0,0]
	v_mfma_scale_f32_16x16x128_f8f6f4 v[100:103], v[16:23], v[240:247], v[100:103], v202, v202 op_sel_hi:[0,0,0]
	v_mfma_scale_f32_16x16x128_f8f6f4 v[96:99], v[24:31], v[240:247], v[96:99], v202, v202 op_sel_hi:[0,0,0]
	s_setprio 0
	s_barrier
	s_add_i32 s43, s43, s13
	v_lshl_add_u64 v[162:163], v[194:195], 0, s[14:15]
	s_mov_b32 m0, s43
	ds_read_b128 v[216:219], v215 offset:49152
	ds_read_b128 v[220:223], v215 offset:50176
	ds_read_b128 v[224:227], v215 offset:51200
	ds_read_b128 v[228:231], v215 offset:52224
	ds_read_b128 v[232:235], v215 offset:53248
	ds_read_b128 v[236:239], v215 offset:54272
	ds_read_b128 v[240:243], v215 offset:55296
	ds_read_b128 v[244:247], v215 offset:56320
	global_load_lds_dwordx4 v[162:163], off
	s_add_i32 m0, s43, 0x2000
	s_add_u32 s36, s36, 0x40080
	v_lshl_add_u64 v[162:163], v[196:197], 0, s[14:15]
	s_addc_u32 s37, s37, 0
	s_add_i32 s43, s56, s13
	global_load_lds_dwordx4 v[162:163], off
	v_lshl_add_u64 v[162:163], s[36:37], 0, v[160:161]
	s_mov_b32 m0, s43
	s_nop 0
	global_load_lds_dwordx4 v[162:163], off
	v_lshl_add_u64 v[162:163], s[36:37], 0, v[184:185]
	s_add_i32 m0, s43, 0x2000
	s_nop 0
	global_load_lds_dwordx4 v[162:163], off
	v_lshl_add_u64 v[162:163], v[198:199], 0, s[14:15]
	s_mov_b32 m0, s55
	s_nop 0
	global_load_lds_dwordx4 v[162:163], off
	v_lshl_add_u64 v[162:163], v[200:201], 0, s[14:15]
	s_mov_b32 m0, s58
	s_nop 0
	global_load_lds_dwordx4 v[162:163], off
	s_waitcnt vmcnt(8)
	s_waitcnt lgkmcnt(0)
	s_barrier
	s_setprio 1
	s_waitcnt lgkmcnt(0)
	v_mfma_scale_f32_16x16x128_f8f6f4 v[92:95], v[0:7], v[216:223], v[92:95], v202, v202 op_sel_hi:[0,0,0]
	v_mfma_scale_f32_16x16x128_f8f6f4 v[88:91], v[8:15], v[216:223], v[88:91], v202, v202 op_sel_hi:[0,0,0]
	v_mfma_scale_f32_16x16x128_f8f6f4 v[76:79], v[0:7], v[224:231], v[76:79], v202, v202 op_sel_hi:[0,0,0]
	v_mfma_scale_f32_16x16x128_f8f6f4 v[72:75], v[8:15], v[224:231], v[72:75], v202, v202 op_sel_hi:[0,0,0]
	v_mfma_scale_f32_16x16x128_f8f6f4 v[60:63], v[0:7], v[232:239], v[60:63], v202, v202 op_sel_hi:[0,0,0]
	v_mfma_scale_f32_16x16x128_f8f6f4 v[56:59], v[8:15], v[232:239], v[56:59], v202, v202 op_sel_hi:[0,0,0]
	v_mfma_scale_f32_16x16x128_f8f6f4 v[44:47], v[0:7], v[240:247], v[44:47], v202, v202 op_sel_hi:[0,0,0]
	v_mfma_scale_f32_16x16x128_f8f6f4 v[40:43], v[8:15], v[240:247], v[40:43], v202, v202 op_sel_hi:[0,0,0]
	s_setprio 0
	s_setprio 1
	v_mfma_scale_f32_16x16x128_f8f6f4 v[84:87], v[16:23], v[216:223], v[84:87], v202, v202 op_sel_hi:[0,0,0]
	v_mfma_scale_f32_16x16x128_f8f6f4 v[80:83], v[24:31], v[216:223], v[80:83], v202, v202 op_sel_hi:[0,0,0]
	v_mfma_scale_f32_16x16x128_f8f6f4 v[68:71], v[16:23], v[224:231], v[68:71], v202, v202 op_sel_hi:[0,0,0]
	v_mfma_scale_f32_16x16x128_f8f6f4 v[64:67], v[24:31], v[224:231], v[64:67], v202, v202 op_sel_hi:[0,0,0]
	v_mfma_scale_f32_16x16x128_f8f6f4 v[52:55], v[16:23], v[232:239], v[52:55], v202, v202 op_sel_hi:[0,0,0]
	v_mfma_scale_f32_16x16x128_f8f6f4 v[48:51], v[24:31], v[232:239], v[48:51], v202, v202 op_sel_hi:[0,0,0]
	v_mfma_scale_f32_16x16x128_f8f6f4 v[36:39], v[16:23], v[240:247], v[36:39], v202, v202 op_sel_hi:[0,0,0]
	v_mfma_scale_f32_16x16x128_f8f6f4 v[32:35], v[24:31], v[240:247], v[32:35], v202, v202 op_sel_hi:[0,0,0]
	s_setprio 0
	s_barrier
	s_add_i32 s41, s41, 2
	s_add_u32 s10, s10, 0x100
	s_addc_u32 s11, s11, 0
	s_add_u32 s34, s34, 0x100
	s_addc_u32 s35, s35, 0
	s_cmp_gt_u32 s41, 13
	s_cbranch_scc0 .LBB0_1122
	s_branch .Lgk_after_1122

; #define PG8_BAR __builtin_amdgcn_s_barrier()
; template <class Epi, class Sched, bool ALIGN_EPI = false, bool SP2 = false, bool F8 = false>
; __device__ __forceinline__ void gemm_phase(PG8_LAS unsigned char* lds, const Gemm g, const Sched& S, const Epi& E) {
;     ...
;         if constexpr (ALIGN_EPI) { if (wr == 0) PG8_BAR; }
.Lgk_after_1122:
	s_and_b64 vcc, exec, s[16:17]
	s_cbranch_vccz .LBB0_1125
	s_barrier

; #define PG8_STAGE(bufoff, gbase, voff) do { _Pragma("unroll") for (int _i = 0; _i < 2; ++_i) \
;         __builtin_amdgcn_global_load_lds((const unsigned*)((const char*)(gbase) + (voff)[_i]), (PG8_LAS unsigned*)(lds + (bufoff) + ldsw + _i * 8192), 16, 0, 0); } while (0)
; #define PG8_WAIT_V(n) asm volatile("s_waitcnt vmcnt(" #n ")" ::: "memory")
; #define PG8_WAIT_L(n) asm volatile("s_waitcnt lgkmcnt(" #n ")" ::: "memory")
; #define PG8_BAR __builtin_amdgcn_s_barrier()
; #define PG8_SCHED __builtin_amdgcn_sched_barrier(0)
; template <class Epi, class Sched, bool ALIGN_EPI = false, bool SP2 = false, bool F8 = false>
; __device__ __forceinline__ void gemm_phase(PG8_LAS unsigned char* lds, const Gemm g, const Sched& S, const Epi& E) {
;     ...
;         const bool has_next = S.next(ui + 1, nxt);
;         const char* nA = has_next ? (const char*)g.A + (size_t)nxt.pm * tstep : cA; const char* nB = has_next ? (const char*)g.Bt + (size_t)nxt.pn * tstep : cB;
;         for (int t = 0; t < nt; t += 2) {
;             const bool last = (t == nt - 2);
;             const char* a1 = cA + (size_t)(t + 1) * kstep;
;             const char* a2 = last ? nA : cA + (size_t)(t + 2) * kstep; const char* b2 = last ? nB : cB + (size_t)(t + 2) * kstep;
;             const char* a3 = a2 + kstep; const char* b3 = b2 + kstep;
;             if (last && has_next) S.a_ready(nxt);
;             if constexpr (SP2) {
;             PG8_LDB(B0, 0, 0); PG8_LDB(B1, 0, 1); PG8_SCHED; PG8_LDA(At, 0, 0); PG8_STAGE(PG8_SA(1, 1), a1 + hstep, voffA);
;             PG8_WAIT_V(8); PG8_WAIT_L(0); PG8_BAR; PG8_MMA(0, 0, At, B0); PG8_MMA(0, 1, At, B1); PG8_BAR; PG8_SCHED;
;             PG8_LDA(At, 0, 1); PG8_STAGE(PG8_SB(0, 0), b2, voffB); PG8_STAGE(PG8_SB(0, 1), b2 + hstep, voffB); PG8_STAGE(PG8_SA(0, 0), a2, voffA);
;             PG8_WAIT_V(8); PG8_WAIT_L(0); PG8_BAR; PG8_MMA(1, 0, At, B0); PG8_MMA(1, 1, At, B1); PG8_BAR; PG8_SCHED;
.LBB0_1147:
	s_ashr_i32 s37, s36, 31
	s_lshl_b64 s[40:41], s[36:37], 22
	s_add_u32 s40, s20, s40
	s_addc_u32 s41, s21, s41
	s_and_b64 s[42:43], s[38:39], exec
	s_cselect_b32 s37, s41, s47
	s_cselect_b32 s52, s40, s46
	s_ashr_i32 s17, s16, 31
	s_lshl_b64 s[42:43], s[16:17], 22
	s_add_u32 s42, s13, s42
	s_addc_u32 s43, s19, s43
	s_and_b64 s[50:51], s[38:39], exec
	s_cselect_b32 s17, s43, s49
	s_cselect_b32 s53, s42, s48
	s_add_u32 s46, s46, 0x200080
	s_addc_u32 s47, s47, 0
	s_add_u32 s54, s48, 0x100
	s_addc_u32 s55, s49, 0
	s_mov_b32 s56, -2
	s_add_u32 s48, s46, 0xffe00080
	s_addc_u32 s49, s47, -1
	s_add_i32 s58, 0, 0x10000
	s_cmpk_eq_i32 s56, 0x7c
	s_cselect_b32 s51, s37, s49
	s_cselect_b32 s50, s52, s48
	s_cselect_b32 s49, s17, s55
	s_cselect_b32 s48, s53, s54
	s_add_i32 s60, 0, 0x14000
	v_add_u32_e32 v154, s58, v147
	v_add_u32_e32 v158, s60, v147
	ds_read_b128 v[138:141], v154
	ds_read_b128 v[142:145], v154 offset:1024
	ds_read_b128 v[150:153], v154 offset:2048
	ds_read_b128 v[154:157], v154 offset:3072
	ds_read_b128 v[184:187], v158
	ds_read_b128 v[188:191], v158 offset:1024
	ds_read_b128 v[192:195], v158 offset:2048
	ds_read_b128 v[196:199], v158 offset:3072
	v_lshl_add_u64 v[158:159], s[46:47], 0, v[134:135]
	s_add_i32 m0, s23, 0xc000
	ds_read_b128 v[200:203], v149
	ds_read_b128 v[214:217], v149 offset:1024
	ds_read_b128 v[218:221], v149 offset:2048
	ds_read_b128 v[222:225], v149 offset:3072
	ds_read_b128 v[226:229], v149 offset:4096
	ds_read_b128 v[230:233], v149 offset:5120
	ds_read_b128 v[234:237], v149 offset:6144
	ds_read_b128 v[238:241], v149 offset:7168
	global_load_lds_dwordx4 v[158:159], off
	v_lshl_add_u64 v[158:159], s[46:47], 0, v[136:137]
	s_add_i32 m0, s23, 0xe000
	s_nop 0
	global_load_lds_dwordx4 v[158:159], off
	s_waitcnt vmcnt(8)
	s_waitcnt lgkmcnt(0)
	s_barrier
	s_setprio 1
	s_waitcnt lgkmcnt(0)
	v_mfma_f32_16x16x32_bf16 v[124:127], v[138:141], v[200:203], 0
	v_mfma_f32_16x16x32_bf16 v[120:123], v[150:153], v[200:203], 0
	v_mfma_f32_16x16x32_bf16 v[108:111], v[138:141], v[218:221], 0
	v_mfma_f32_16x16x32_bf16 v[104:107], v[150:153], v[218:221], 0
	v_mfma_f32_16x16x32_bf16 v[92:95], v[138:141], v[226:229], 0
	v_mfma_f32_16x16x32_bf16 v[88:91], v[150:153], v[226:229], 0
	v_mfma_f32_16x16x32_bf16 v[76:79], v[138:141], v[234:237], 0
	v_mfma_f32_16x16x32_bf16 v[72:75], v[150:153], v[234:237], 0
	v_mfma_f32_16x16x32_bf16 v[124:127], v[142:145], v[214:217], v[124:127]
	v_mfma_f32_16x16x32_bf16 v[120:123], v[154:157], v[214:217], v[120:123]
	v_mfma_f32_16x16x32_bf16 v[108:111], v[142:145], v[222:225], v[108:111]
	v_mfma_f32_16x16x32_bf16 v[104:107], v[154:157], v[222:225], v[104:107]
	v_mfma_f32_16x16x32_bf16 v[92:95], v[142:145], v[230:233], v[92:95]
	v_mfma_f32_16x16x32_bf16 v[88:91], v[154:157], v[230:233], v[88:91]
	v_mfma_f32_16x16x32_bf16 v[76:79], v[142:145], v[238:241], v[76:79]
	v_mfma_f32_16x16x32_bf16 v[72:75], v[154:157], v[238:241], v[72:75]
	s_setprio 0
	s_setprio 1
	v_mfma_f32_16x16x32_bf16 v[116:119], v[184:187], v[200:203], 0
	v_mfma_f32_16x16x32_bf16 v[112:115], v[192:195], v[200:203], 0
	v_mfma_f32_16x16x32_bf16 v[100:103], v[184:187], v[218:221], 0
	v_mfma_f32_16x16x32_bf16 v[96:99], v[192:195], v[218:221], 0
	v_mfma_f32_16x16x32_bf16 v[84:87], v[184:187], v[226:229], 0
	v_mfma_f32_16x16x32_bf16 v[80:83], v[192:195], v[226:229], 0
	v_mfma_f32_16x16x32_bf16 v[68:71], v[184:187], v[234:237], 0
	v_mfma_f32_16x16x32_bf16 v[64:67], v[192:195], v[234:237], 0
	v_mfma_f32_16x16x32_bf16 v[116:119], v[188:191], v[214:217], v[116:119]
	v_mfma_f32_16x16x32_bf16 v[112:115], v[196:199], v[214:217], v[112:115]
	v_mfma_f32_16x16x32_bf16 v[100:103], v[188:191], v[222:225], v[100:103]
	v_mfma_f32_16x16x32_bf16 v[96:99], v[196:199], v[222:225], v[96:99]
	v_mfma_f32_16x16x32_bf16 v[84:87], v[188:191], v[230:233], v[84:87]
	v_mfma_f32_16x16x32_bf16 v[80:83], v[196:199], v[230:233], v[80:83]
	v_mfma_f32_16x16x32_bf16 v[68:71], v[188:191], v[238:241], v[68:71]
	v_mfma_f32_16x16x32_bf16 v[64:67], v[196:199], v[238:241], v[64:67]
	s_setprio 0
	s_barrier
	s_add_i32 s58, s58, s22
	v_lshl_add_u64 v[158:159], s[48:49], 0, v[160:161]
	s_mov_b32 m0, s58
	ds_read_b128 v[200:203], v149 offset:16384
	ds_read_b128 v[214:217], v149 offset:17408
	ds_read_b128 v[218:221], v149 offset:18432
	ds_read_b128 v[222:225], v149 offset:19456
	ds_read_b128 v[226:229], v149 offset:20480
	ds_read_b128 v[230:233], v149 offset:21504
	ds_read_b128 v[234:237], v149 offset:22528
	ds_read_b128 v[238:241], v149 offset:23552
	global_load_lds_dwordx4 v[158:159], off
	s_add_i32 m0, s58, 0x2000
	s_add_u32 s58, s48, 0x200000
	v_lshl_add_u64 v[162:163], s[48:49], 0, v[132:133]
	s_addc_u32 s59, s49, 0
	s_add_i32 s60, s60, s22
	global_load_lds_dwordx4 v[162:163], off
	v_lshl_add_u64 v[242:243], s[58:59], 0, v[160:161]
	s_mov_b32 m0, s60
	v_lshl_add_u64 v[244:245], s[50:51], 0, v[130:131]
	global_load_lds_dwordx4 v[242:243], off
	v_lshl_add_u64 v[242:243], s[58:59], 0, v[132:133]
	s_add_i32 m0, s60, 0x2000
	s_nop 0
	global_load_lds_dwordx4 v[242:243], off
	v_lshl_add_u64 v[242:243], s[50:51], 0, v[128:129]
	s_mov_b32 m0, s23
	s_nop 0
	global_load_lds_dwordx4 v[242:243], off
	s_mov_b32 m0, s28
	s_nop 0
	global_load_lds_dwordx4 v[244:245], off
	s_waitcnt vmcnt(8)
	s_waitcnt lgkmcnt(0)
	s_barrier
; #define PG8_STAGE(bufoff, gbase, voff) do { _Pragma("unroll") for (int _i = 0; _i < 2; ++_i) \
;         __builtin_amdgcn_global_load_lds((const unsigned*)((const char*)(gbase) + (voff)[_i]), (PG8_LAS unsigned*)(lds + (bufoff) + ldsw + _i * 8192), 16, 0, 0); } while (0)
; #define PG8_WAIT_V(n) asm volatile("s_waitcnt vmcnt(" #n ")" ::: "memory")
; #define PG8_WAIT_L(n) asm volatile("s_waitcnt lgkmcnt(" #n ")" ::: "memory")
; #define PG8_BAR __builtin_amdgcn_s_barrier()
; #define PG8_SCHED __builtin_amdgcn_sched_barrier(0)
; template <class Epi, class Sched, bool ALIGN_EPI = false, bool SP2 = false, bool F8 = false>
; __device__ __forceinline__ void gemm_phase(PG8_LAS unsigned char* lds, const Gemm g, const Sched& S, const Epi& E) {
;     ...
;             PG8_WAIT_V(8); PG8_WAIT_L(0); PG8_BAR; PG8_MMA(1, 0, At, B0); PG8_MMA(1, 1, At, B1); PG8_BAR; PG8_SCHED;
;             PG8_LDB(B0, 1, 0); PG8_LDB(B1, 1, 1); PG8_SCHED; PG8_LDA(At, 1, 0); PG8_STAGE(PG8_SA(0, 1), a2 + hstep, voffA);
;             PG8_WAIT_V(8); PG8_WAIT_L(0); PG8_BAR; PG8_MMA(0, 0, At, B0); PG8_MMA(0, 1, At, B1); PG8_BAR; PG8_SCHED;
	s_setprio 1
	s_waitcnt lgkmcnt(0)
	v_mfma_f32_16x16x32_bf16 v[60:63], v[138:141], v[200:203], 0
	v_mfma_f32_16x16x32_bf16 v[56:59], v[150:153], v[200:203], 0
	v_mfma_f32_16x16x32_bf16 v[44:47], v[138:141], v[218:221], 0
	v_mfma_f32_16x16x32_bf16 v[40:43], v[150:153], v[218:221], 0
	v_mfma_f32_16x16x32_bf16 v[28:31], v[138:141], v[226:229], 0
	v_mfma_f32_16x16x32_bf16 v[24:27], v[150:153], v[226:229], 0
	v_mfma_f32_16x16x32_bf16 v[12:15], v[138:141], v[234:237], 0
	v_mfma_f32_16x16x32_bf16 v[8:11], v[150:153], v[234:237], 0
	v_mfma_f32_16x16x32_bf16 v[60:63], v[142:145], v[214:217], v[60:63]
	v_mfma_f32_16x16x32_bf16 v[56:59], v[154:157], v[214:217], v[56:59]
	v_mfma_f32_16x16x32_bf16 v[44:47], v[142:145], v[222:225], v[44:47]
	v_mfma_f32_16x16x32_bf16 v[40:43], v[154:157], v[222:225], v[40:43]
	v_mfma_f32_16x16x32_bf16 v[28:31], v[142:145], v[230:233], v[28:31]
	v_mfma_f32_16x16x32_bf16 v[24:27], v[154:157], v[230:233], v[24:27]
	v_mfma_f32_16x16x32_bf16 v[12:15], v[142:145], v[238:241], v[12:15]
	v_mfma_f32_16x16x32_bf16 v[8:11], v[154:157], v[238:241], v[8:11]
	s_setprio 0
	s_setprio 1
	v_mfma_f32_16x16x32_bf16 v[52:55], v[184:187], v[200:203], 0
	v_mfma_f32_16x16x32_bf16 v[48:51], v[192:195], v[200:203], 0
	v_mfma_f32_16x16x32_bf16 v[36:39], v[184:187], v[218:221], 0
	v_mfma_f32_16x16x32_bf16 v[32:35], v[192:195], v[218:221], 0
	v_mfma_f32_16x16x32_bf16 v[20:23], v[184:187], v[226:229], 0
	v_mfma_f32_16x16x32_bf16 v[16:19], v[192:195], v[226:229], 0
	v_mfma_f32_16x16x32_bf16 v[4:7], v[184:187], v[234:237], 0
	v_mfma_f32_16x16x32_bf16 v[0:3], v[192:195], v[234:237], 0
	v_mfma_f32_16x16x32_bf16 v[52:55], v[188:191], v[214:217], v[52:55]
	v_mfma_f32_16x16x32_bf16 v[48:51], v[196:199], v[214:217], v[48:51]
	v_mfma_f32_16x16x32_bf16 v[36:39], v[188:191], v[222:225], v[36:39]
	v_mfma_f32_16x16x32_bf16 v[32:35], v[196:199], v[222:225], v[32:35]
	v_mfma_f32_16x16x32_bf16 v[20:23], v[188:191], v[230:233], v[20:23]
	v_mfma_f32_16x16x32_bf16 v[16:19], v[196:199], v[230:233], v[16:19]
	v_mfma_f32_16x16x32_bf16 v[4:7], v[188:191], v[238:241], v[4:7]
	v_mfma_f32_16x16x32_bf16 v[0:3], v[196:199], v[238:241], v[0:3]
	s_setprio 0
	s_barrier
	s_add_i32 s58, 0, 0x18000
	s_add_i32 s59, 0, 0x1c000
	v_add_u32_e32 v154, s58, v147
	v_add_u32_e32 v196, s59, v147
	ds_read_b128 v[138:141], v154
	ds_read_b128 v[142:145], v154 offset:1024
	ds_read_b128 v[150:153], v154 offset:2048
	ds_read_b128 v[154:157], v154 offset:3072
	ds_read_b128 v[184:187], v196
	ds_read_b128 v[188:191], v196 offset:1024
	ds_read_b128 v[192:195], v196 offset:2048
	ds_read_b128 v[196:199], v196 offset:3072
	s_add_u32 s50, s50, 0x200000
	s_addc_u32 s51, s51, 0
	s_mov_b32 m0, s29
	v_lshl_add_u64 v[246:247], s[50:51], 0, v[128:129]
	ds_read_b128 v[200:203], v149 offset:32768
	ds_read_b128 v[214:217], v149 offset:33792
	ds_read_b128 v[218:221], v149 offset:34816
	ds_read_b128 v[222:225], v149 offset:35840
	ds_read_b128 v[226:229], v149 offset:36864
	ds_read_b128 v[230:233], v149 offset:37888
	ds_read_b128 v[234:237], v149 offset:38912
	ds_read_b128 v[238:241], v149 offset:39936
	global_load_lds_dwordx4 v[246:247], off
	v_lshl_add_u64 v[246:247], s[50:51], 0, v[130:131]
	s_mov_b32 m0, s34
	s_nop 0
	global_load_lds_dwordx4 v[246:247], off
	s_waitcnt vmcnt(8)
	s_waitcnt lgkmcnt(0)
	s_barrier
	s_setprio 1
	s_waitcnt lgkmcnt(0)
	v_mfma_f32_16x16x32_bf16 v[124:127], v[138:141], v[200:203], v[124:127]
	v_mfma_f32_16x16x32_bf16 v[120:123], v[150:153], v[200:203], v[120:123]
	v_mfma_f32_16x16x32_bf16 v[108:111], v[138:141], v[218:221], v[108:111]
	v_mfma_f32_16x16x32_bf16 v[104:107], v[150:153], v[218:221], v[104:107]
	v_mfma_f32_16x16x32_bf16 v[92:95], v[138:141], v[226:229], v[92:95]
	v_mfma_f32_16x16x32_bf16 v[88:91], v[150:153], v[226:229], v[88:91]
	v_mfma_f32_16x16x32_bf16 v[76:79], v[138:141], v[234:237], v[76:79]
	v_mfma_f32_16x16x32_bf16 v[72:75], v[150:153], v[234:237], v[72:75]
	v_mfma_f32_16x16x32_bf16 v[124:127], v[142:145], v[214:217], v[124:127]
	v_mfma_f32_16x16x32_bf16 v[120:123], v[154:157], v[214:217], v[120:123]
	v_mfma_f32_16x16x32_bf16 v[108:111], v[142:145], v[222:225], v[108:111]
	v_mfma_f32_16x16x32_bf16 v[104:107], v[154:157], v[222:225], v[104:107]
	v_mfma_f32_16x16x32_bf16 v[92:95], v[142:145], v[230:233], v[92:95]
	v_mfma_f32_16x16x32_bf16 v[88:91], v[154:157], v[230:233], v[88:91]
	v_mfma_f32_16x16x32_bf16 v[76:79], v[142:145], v[238:241], v[76:79]
	v_mfma_f32_16x16x32_bf16 v[72:75], v[154:157], v[238:241], v[72:75]
	s_setprio 0
	s_setprio 1
	v_mfma_f32_16x16x32_bf16 v[116:119], v[184:187], v[200:203], v[116:119]
	v_mfma_f32_16x16x32_bf16 v[112:115], v[192:195], v[200:203], v[112:115]
	v_mfma_f32_16x16x32_bf16 v[100:103], v[184:187], v[218:221], v[100:103]
	v_mfma_f32_16x16x32_bf16 v[96:99], v[192:195], v[218:221], v[96:99]
	v_mfma_f32_16x16x32_bf16 v[84:87], v[184:187], v[226:229], v[84:87]
	v_mfma_f32_16x16x32_bf16 v[80:83], v[192:195], v[226:229], v[80:83]
	v_mfma_f32_16x16x32_bf16 v[68:71], v[184:187], v[234:237], v[68:71]
	v_mfma_f32_16x16x32_bf16 v[64:67], v[192:195], v[234:237], v[64:67]
	v_mfma_f32_16x16x32_bf16 v[116:119], v[188:191], v[214:217], v[116:119]
	v_mfma_f32_16x16x32_bf16 v[112:115], v[196:199], v[214:217], v[112:115]
	v_mfma_f32_16x16x32_bf16 v[100:103], v[188:191], v[222:225], v[100:103]
	v_mfma_f32_16x16x32_bf16 v[96:99], v[196:199], v[222:225], v[96:99]
	v_mfma_f32_16x16x32_bf16 v[84:87], v[188:191], v[230:233], v[84:87]
	v_mfma_f32_16x16x32_bf16 v[80:83], v[196:199], v[230:233], v[80:83]
	v_mfma_f32_16x16x32_bf16 v[68:71], v[188:191], v[238:241], v[68:71]
	v_mfma_f32_16x16x32_bf16 v[64:67], v[196:199], v[238:241], v[64:67]
	s_setprio 0
	s_barrier
; #define PG8_STAGE(bufoff, gbase, voff) do { _Pragma("unroll") for (int _i = 0; _i < 2; ++_i) \
;         __builtin_amdgcn_global_load_lds((const unsigned*)((const char*)(gbase) + (voff)[_i]), (PG8_LAS unsigned*)(lds + (bufoff) + ldsw + _i * 8192), 16, 0, 0); } while (0)
; #define PG8_WAIT_V(n) asm volatile("s_waitcnt vmcnt(" #n ")" ::: "memory")
; #define PG8_WAIT_L(n) asm volatile("s_waitcnt lgkmcnt(" #n ")" ::: "memory")
; #define PG8_BAR __builtin_amdgcn_s_barrier()
; #define PG8_SCHED __builtin_amdgcn_sched_barrier(0)
; template <class Epi, class Sched, bool ALIGN_EPI = false, bool SP2 = false, bool F8 = false>
; __device__ __forceinline__ void gemm_phase(PG8_LAS unsigned char* lds, const Gemm g, const Sched& S, const Epi& E) {
;     ...
;             PG8_LDA(At, 1, 1); PG8_STAGE(PG8_SB(1, 0), b3, voffB); PG8_STAGE(PG8_SB(1, 1), b3 + hstep, voffB); PG8_STAGE(PG8_SA(1, 0), a3, voffA);
;             PG8_WAIT_V(8); PG8_WAIT_L(0); PG8_BAR; PG8_MMA(1, 0, At, B0); PG8_MMA(1, 1, At, B1); PG8_BAR; PG8_SCHED;
	s_add_i32 s50, s58, s22
	v_lshl_add_u64 v[158:159], v[158:159], 0, s[14:15]
	s_mov_b32 m0, s50
	ds_read_b128 v[200:203], v149 offset:49152
	ds_read_b128 v[214:217], v149 offset:50176
	ds_read_b128 v[218:221], v149 offset:51200
	ds_read_b128 v[222:225], v149 offset:52224
	ds_read_b128 v[226:229], v149 offset:53248
	ds_read_b128 v[230:233], v149 offset:54272
	ds_read_b128 v[234:237], v149 offset:55296
	ds_read_b128 v[238:241], v149 offset:56320
	global_load_lds_dwordx4 v[158:159], off
	s_add_i32 m0, s50, 0x2000
	s_add_u32 s48, s48, 0x200080
	v_lshl_add_u64 v[158:159], v[162:163], 0, s[14:15]
	s_addc_u32 s49, s49, 0
	s_add_i32 s50, s59, s22
	global_load_lds_dwordx4 v[158:159], off
	v_lshl_add_u64 v[158:159], s[48:49], 0, v[160:161]
	s_mov_b32 m0, s50
	s_nop 0
	global_load_lds_dwordx4 v[158:159], off
	v_lshl_add_u64 v[158:159], s[48:49], 0, v[132:133]
	s_add_i32 m0, s50, 0x2000
	s_nop 0
	global_load_lds_dwordx4 v[158:159], off
	v_lshl_add_u64 v[158:159], v[242:243], 0, s[14:15]
	s_mov_b32 m0, s8
	s_nop 0
	global_load_lds_dwordx4 v[158:159], off
	v_lshl_add_u64 v[158:159], v[244:245], 0, s[14:15]
	s_mov_b32 m0, s9
	s_nop 0
	global_load_lds_dwordx4 v[158:159], off
	s_waitcnt vmcnt(8)
	s_waitcnt lgkmcnt(0)
	s_barrier
	s_setprio 1
	s_waitcnt lgkmcnt(0)
	v_mfma_f32_16x16x32_bf16 v[60:63], v[138:141], v[200:203], v[60:63]
	v_mfma_f32_16x16x32_bf16 v[56:59], v[150:153], v[200:203], v[56:59]
	v_mfma_f32_16x16x32_bf16 v[44:47], v[138:141], v[218:221], v[44:47]
	v_mfma_f32_16x16x32_bf16 v[40:43], v[150:153], v[218:221], v[40:43]
	v_mfma_f32_16x16x32_bf16 v[28:31], v[138:141], v[226:229], v[28:31]
	v_mfma_f32_16x16x32_bf16 v[24:27], v[150:153], v[226:229], v[24:27]
	v_mfma_f32_16x16x32_bf16 v[12:15], v[138:141], v[234:237], v[12:15]
	v_mfma_f32_16x16x32_bf16 v[8:11], v[150:153], v[234:237], v[8:11]
	v_mfma_f32_16x16x32_bf16 v[60:63], v[142:145], v[214:217], v[60:63]
	v_mfma_f32_16x16x32_bf16 v[56:59], v[154:157], v[214:217], v[56:59]
	v_mfma_f32_16x16x32_bf16 v[44:47], v[142:145], v[222:225], v[44:47]
	v_mfma_f32_16x16x32_bf16 v[40:43], v[154:157], v[222:225], v[40:43]
	v_mfma_f32_16x16x32_bf16 v[28:31], v[142:145], v[230:233], v[28:31]
	v_mfma_f32_16x16x32_bf16 v[24:27], v[154:157], v[230:233], v[24:27]
	v_mfma_f32_16x16x32_bf16 v[12:15], v[142:145], v[238:241], v[12:15]
	v_mfma_f32_16x16x32_bf16 v[8:11], v[154:157], v[238:241], v[8:11]
	s_setprio 0
	s_setprio 1
	v_mfma_f32_16x16x32_bf16 v[52:55], v[184:187], v[200:203], v[52:55]
	v_mfma_f32_16x16x32_bf16 v[48:51], v[192:195], v[200:203], v[48:51]
	v_mfma_f32_16x16x32_bf16 v[36:39], v[184:187], v[218:221], v[36:39]
	v_mfma_f32_16x16x32_bf16 v[32:35], v[192:195], v[218:221], v[32:35]
	v_mfma_f32_16x16x32_bf16 v[20:23], v[184:187], v[226:229], v[20:23]
	v_mfma_f32_16x16x32_bf16 v[16:19], v[192:195], v[226:229], v[16:19]
	v_mfma_f32_16x16x32_bf16 v[4:7], v[184:187], v[234:237], v[4:7]
	v_mfma_f32_16x16x32_bf16 v[0:3], v[192:195], v[234:237], v[0:3]
	v_mfma_f32_16x16x32_bf16 v[52:55], v[188:191], v[214:217], v[52:55]
	v_mfma_f32_16x16x32_bf16 v[48:51], v[196:199], v[214:217], v[48:51]
	v_mfma_f32_16x16x32_bf16 v[36:39], v[188:191], v[222:225], v[36:39]
	v_mfma_f32_16x16x32_bf16 v[32:35], v[196:199], v[222:225], v[32:35]
	v_mfma_f32_16x16x32_bf16 v[20:23], v[188:191], v[230:233], v[20:23]
	v_mfma_f32_16x16x32_bf16 v[16:19], v[196:199], v[230:233], v[16:19]
	v_mfma_f32_16x16x32_bf16 v[4:7], v[188:191], v[238:241], v[4:7]
	v_mfma_f32_16x16x32_bf16 v[0:3], v[196:199], v[238:241], v[0:3]
	s_setprio 0
	s_barrier
	s_add_i32 s56, s56, 2
	s_add_u32 s46, s46, 0x100
	s_addc_u32 s47, s47, 0
	s_add_u32 s54, s54, 0x100
	s_addc_u32 s55, s55, 0
	s_cmpk_gt_u32 s56, 0x7d
	s_cbranch_scc0 .LBB0_1148
	s_branch .Lgk_after_1148

; #define PG8_BAR __builtin_amdgcn_s_barrier()
; template <class Epi, class Sched, bool ALIGN_EPI = false, bool SP2 = false, bool F8 = false>
; __device__ __forceinline__ void gemm_phase(PG8_LAS unsigned char* lds, const Gemm g, const Sched& S, const Epi& E) {
;     ...
;         if constexpr (ALIGN_EPI) { if (wr == 0) PG8_BAR; }
.Lgk_after_1148:
	s_and_b64 vcc, exec, s[10:11]
	s_cbranch_vccz .LBB0_1151
	s_barrier
